# GLA stream loop rewritten by hand: packed f32 recurrence, double-buffered LDS staging, one barrier per 16 tokens, type-specific loops; GEMM K-loop spurious vmcnt(0) removed
# speedup vs baseline: 1.0512x; 1.0512x over previous
.LBB0_129:
	s_add_u32 s16, s14, 0x100
	s_addc_u32 s17, s15, 0
	s_add_i32 s42, 0, 0x10000
	v_add_u32_e32 v140, s42, v143
	ds_read_b128 v[136:139], v140
	ds_read_b128 v[146:149], v140 offset:1024
	ds_read_b128 v[150:153], v140 offset:2048
	ds_read_b128 v[154:157], v140 offset:3072
	s_cmpk_eq_i32 s41, 0x54
	s_cselect_b32 s21, s11, s17
	s_cselect_b32 s20, s10, s16
	s_cselect_b32 s19, s13, s40
	s_cselect_b32 s18, s12, s39
	v_lshl_add_u64 v[140:141], s[14:15], 0, v[132:133]
	s_add_i32 m0, s26, 0xc000
	ds_read_b128 v[158:161], v145
	ds_read_b128 v[176:179], v145 offset:1024
	ds_read_b128 v[180:183], v145 offset:2048
	ds_read_b128 v[184:187], v145 offset:3072
	ds_read_b128 v[188:191], v145 offset:4096
	ds_read_b128 v[192:195], v145 offset:5120
	ds_read_b128 v[208:211], v145 offset:6144
	ds_read_b128 v[212:215], v145 offset:7168
	global_load_lds_dwordx4 v[140:141], off
	v_lshl_add_u64 v[140:141], s[14:15], 0, v[134:135]
	s_add_i32 m0, s26, 0xe000
	s_nop 0
	global_load_lds_dwordx4 v[140:141], off
	s_waitcnt lgkmcnt(8)
	s_barrier
	s_waitcnt lgkmcnt(0)
	s_setprio 1
	s_waitcnt lgkmcnt(0)
	v_mfma_f32_16x16x32_bf16 v[124:127], v[136:139], v[158:161], v[124:127]
	v_mfma_f32_16x16x32_bf16 v[120:123], v[150:153], v[158:161], v[120:123]
	v_mfma_f32_16x16x32_bf16 v[108:111], v[136:139], v[180:183], v[108:111]
	v_mfma_f32_16x16x32_bf16 v[104:107], v[150:153], v[180:183], v[104:107]
	v_mfma_f32_16x16x32_bf16 v[92:95], v[136:139], v[188:191], v[92:95]
	v_mfma_f32_16x16x32_bf16 v[88:91], v[150:153], v[188:191], v[88:91]
	v_mfma_f32_16x16x32_bf16 v[76:79], v[136:139], v[208:211], v[76:79]
	v_mfma_f32_16x16x32_bf16 v[72:75], v[150:153], v[208:211], v[72:75]
	v_mfma_f32_16x16x32_bf16 v[124:127], v[146:149], v[176:179], v[124:127]
	v_mfma_f32_16x16x32_bf16 v[120:123], v[154:157], v[176:179], v[120:123]
	v_mfma_f32_16x16x32_bf16 v[108:111], v[146:149], v[184:187], v[108:111]
	v_mfma_f32_16x16x32_bf16 v[104:107], v[154:157], v[184:187], v[104:107]
	v_mfma_f32_16x16x32_bf16 v[92:95], v[146:149], v[192:195], v[92:95]
	v_mfma_f32_16x16x32_bf16 v[88:91], v[154:157], v[192:195], v[88:91]
	v_mfma_f32_16x16x32_bf16 v[76:79], v[146:149], v[212:215], v[76:79]
	v_mfma_f32_16x16x32_bf16 v[72:75], v[154:157], v[212:215], v[72:75]
	s_setprio 0
	s_barrier
	s_add_i32 s43, 0, 0x14000
	v_add_u32_e32 v140, s43, v143
	s_add_i32 s14, s42, s25
	ds_read_b128 v[216:219], v140
	ds_read_b128 v[220:223], v140 offset:1024
	ds_read_b128 v[224:227], v140 offset:2048
	ds_read_b128 v[228:231], v140 offset:3072
	v_lshl_add_u64 v[140:141], s[18:19], 0, v[128:129]
	s_mov_b32 m0, s14
	v_lshl_add_u64 v[232:233], s[18:19], 0, v[130:131]
	global_load_lds_dwordx4 v[140:141], off
	s_add_i32 m0, s14, 0x2000
	s_nop 0
	global_load_lds_dwordx4 v[232:233], off
	s_barrier
	s_waitcnt lgkmcnt(0)
	s_setprio 1
	s_waitcnt lgkmcnt(0)
	v_mfma_f32_16x16x32_bf16 v[116:119], v[216:219], v[158:161], v[116:119]
	v_mfma_f32_16x16x32_bf16 v[112:115], v[224:227], v[158:161], v[112:115]
	v_mfma_f32_16x16x32_bf16 v[100:103], v[216:219], v[180:183], v[100:103]
	v_mfma_f32_16x16x32_bf16 v[96:99], v[224:227], v[180:183], v[96:99]
	v_mfma_f32_16x16x32_bf16 v[84:87], v[216:219], v[188:191], v[84:87]
	v_mfma_f32_16x16x32_bf16 v[80:83], v[224:227], v[188:191], v[80:83]
	v_mfma_f32_16x16x32_bf16 v[68:71], v[216:219], v[208:211], v[68:71]
	v_mfma_f32_16x16x32_bf16 v[64:67], v[224:227], v[208:211], v[64:67]
	v_mfma_f32_16x16x32_bf16 v[116:119], v[220:223], v[176:179], v[116:119]
	v_mfma_f32_16x16x32_bf16 v[112:115], v[228:231], v[176:179], v[112:115]
	v_mfma_f32_16x16x32_bf16 v[100:103], v[220:223], v[184:187], v[100:103]
	v_mfma_f32_16x16x32_bf16 v[96:99], v[228:231], v[184:187], v[96:99]
	v_mfma_f32_16x16x32_bf16 v[84:87], v[220:223], v[192:195], v[84:87]
	v_mfma_f32_16x16x32_bf16 v[80:83], v[228:231], v[192:195], v[80:83]
	v_mfma_f32_16x16x32_bf16 v[68:71], v[220:223], v[212:215], v[68:71]
	v_mfma_f32_16x16x32_bf16 v[64:67], v[228:231], v[212:215], v[64:67]
	s_setprio 0
	s_mov_b32 m0, s26
	v_lshl_add_u64 v[234:235], s[20:21], 0, v[128:129]
	s_barrier
	ds_read_b128 v[158:161], v145 offset:16384
	ds_read_b128 v[176:179], v145 offset:17408
	ds_read_b128 v[180:183], v145 offset:18432
	ds_read_b128 v[184:187], v145 offset:19456
	ds_read_b128 v[188:191], v145 offset:20480
	ds_read_b128 v[192:195], v145 offset:21504
	ds_read_b128 v[208:211], v145 offset:22528
	ds_read_b128 v[212:215], v145 offset:23552
	global_load_lds_dwordx4 v[234:235], off
	v_lshl_add_u64 v[236:237], s[20:21], 0, v[130:131]
	s_mov_b32 m0, s27
	s_nop 0
	global_load_lds_dwordx4 v[236:237], off
	s_barrier
	s_waitcnt lgkmcnt(0)
	s_setprio 1
	s_waitcnt lgkmcnt(0)
	v_mfma_f32_16x16x32_bf16 v[60:63], v[136:139], v[158:161], v[60:63]
	v_mfma_f32_16x16x32_bf16 v[56:59], v[150:153], v[158:161], v[56:59]
	v_mfma_f32_16x16x32_bf16 v[44:47], v[136:139], v[180:183], v[44:47]
	v_mfma_f32_16x16x32_bf16 v[40:43], v[150:153], v[180:183], v[40:43]
	v_mfma_f32_16x16x32_bf16 v[28:31], v[136:139], v[188:191], v[28:31]
	v_mfma_f32_16x16x32_bf16 v[24:27], v[150:153], v[188:191], v[24:27]
	v_mfma_f32_16x16x32_bf16 v[12:15], v[136:139], v[208:211], v[12:15]
	v_mfma_f32_16x16x32_bf16 v[8:11], v[150:153], v[208:211], v[8:11]
	v_mfma_f32_16x16x32_bf16 v[60:63], v[146:149], v[176:179], v[60:63]
	v_mfma_f32_16x16x32_bf16 v[56:59], v[154:157], v[176:179], v[56:59]
	v_mfma_f32_16x16x32_bf16 v[44:47], v[146:149], v[184:187], v[44:47]
	v_mfma_f32_16x16x32_bf16 v[40:43], v[154:157], v[184:187], v[40:43]
	v_mfma_f32_16x16x32_bf16 v[28:31], v[146:149], v[192:195], v[28:31]
	v_mfma_f32_16x16x32_bf16 v[24:27], v[154:157], v[192:195], v[24:27]
	v_mfma_f32_16x16x32_bf16 v[12:15], v[146:149], v[212:215], v[12:15]
	v_mfma_f32_16x16x32_bf16 v[8:11], v[154:157], v[212:215], v[8:11]
	s_setprio 0
	s_barrier
	s_add_u32 s14, s18, 0x160000
	s_addc_u32 s15, s19, 0
	s_add_i32 s42, s43, s25
	v_lshl_add_u64 v[136:137], s[14:15], 0, v[128:129]
	s_mov_b32 m0, s42
	s_nop 0
	global_load_lds_dwordx4 v[136:137], off
	v_lshl_add_u64 v[136:137], s[14:15], 0, v[130:131]
	s_add_i32 m0, s42, 0x2000
	s_nop 0
	global_load_lds_dwordx4 v[136:137], off
	s_waitcnt vmcnt(6)
	s_barrier
	s_setprio 1
	v_mfma_f32_16x16x32_bf16 v[52:55], v[216:219], v[158:161], v[52:55]
	v_mfma_f32_16x16x32_bf16 v[48:51], v[224:227], v[158:161], v[48:51]
	v_mfma_f32_16x16x32_bf16 v[36:39], v[216:219], v[180:183], v[36:39]
	v_mfma_f32_16x16x32_bf16 v[32:35], v[224:227], v[180:183], v[32:35]
	v_mfma_f32_16x16x32_bf16 v[20:23], v[216:219], v[188:191], v[20:23]
	v_mfma_f32_16x16x32_bf16 v[16:19], v[224:227], v[188:191], v[16:19]
	v_mfma_f32_16x16x32_bf16 v[4:7], v[216:219], v[208:211], v[4:7]
	v_mfma_f32_16x16x32_bf16 v[0:3], v[224:227], v[208:211], v[0:3]
	v_mfma_f32_16x16x32_bf16 v[52:55], v[220:223], v[176:179], v[52:55]
	v_mfma_f32_16x16x32_bf16 v[48:51], v[228:231], v[176:179], v[48:51]
	v_mfma_f32_16x16x32_bf16 v[36:39], v[220:223], v[184:187], v[36:39]
	v_mfma_f32_16x16x32_bf16 v[32:35], v[228:231], v[184:187], v[32:35]
	v_mfma_f32_16x16x32_bf16 v[20:23], v[220:223], v[192:195], v[20:23]
	v_mfma_f32_16x16x32_bf16 v[16:19], v[228:231], v[192:195], v[16:19]
	v_mfma_f32_16x16x32_bf16 v[4:7], v[220:223], v[212:215], v[4:7]
	v_mfma_f32_16x16x32_bf16 v[0:3], v[228:231], v[212:215], v[0:3]
	s_setprio 0
	s_add_i32 s42, 0, 0x18000
	v_add_u32_e32 v154, s42, v143
	s_barrier
	ds_read_b128 v[136:139], v154
	ds_read_b128 v[146:149], v154 offset:1024
	ds_read_b128 v[150:153], v154 offset:2048
	ds_read_b128 v[154:157], v154 offset:3072
	s_add_u32 s14, s20, 0x160000
	s_addc_u32 s15, s21, 0
	s_mov_b32 m0, s28
	v_lshl_add_u64 v[216:217], s[14:15], 0, v[128:129]
	ds_read_b128 v[158:161], v145 offset:32768
	ds_read_b128 v[176:179], v145 offset:33792
	ds_read_b128 v[180:183], v145 offset:34816
	ds_read_b128 v[184:187], v145 offset:35840
	ds_read_b128 v[188:191], v145 offset:36864
	ds_read_b128 v[192:195], v145 offset:37888
	ds_read_b128 v[208:211], v145 offset:38912
	ds_read_b128 v[212:215], v145 offset:39936
	global_load_lds_dwordx4 v[216:217], off
	v_lshl_add_u64 v[216:217], s[14:15], 0, v[130:131]
	s_mov_b32 m0, s29
	s_nop 0
	global_load_lds_dwordx4 v[216:217], off
	s_waitcnt lgkmcnt(8)
	s_barrier
	s_waitcnt lgkmcnt(0)
	s_setprio 1
	s_waitcnt lgkmcnt(0)
	v_mfma_f32_16x16x32_bf16 v[124:127], v[136:139], v[158:161], v[124:127]
	v_mfma_f32_16x16x32_bf16 v[120:123], v[150:153], v[158:161], v[120:123]
	v_mfma_f32_16x16x32_bf16 v[108:111], v[136:139], v[180:183], v[108:111]
	v_mfma_f32_16x16x32_bf16 v[104:107], v[150:153], v[180:183], v[104:107]
	v_mfma_f32_16x16x32_bf16 v[92:95], v[136:139], v[188:191], v[92:95]
	v_mfma_f32_16x16x32_bf16 v[88:91], v[150:153], v[188:191], v[88:91]
	v_mfma_f32_16x16x32_bf16 v[76:79], v[136:139], v[208:211], v[76:79]
	v_mfma_f32_16x16x32_bf16 v[72:75], v[150:153], v[208:211], v[72:75]
	v_mfma_f32_16x16x32_bf16 v[124:127], v[146:149], v[176:179], v[124:127]
	v_mfma_f32_16x16x32_bf16 v[120:123], v[154:157], v[176:179], v[120:123]
	v_mfma_f32_16x16x32_bf16 v[108:111], v[146:149], v[184:187], v[108:111]
	v_mfma_f32_16x16x32_bf16 v[104:107], v[154:157], v[184:187], v[104:107]
	v_mfma_f32_16x16x32_bf16 v[92:95], v[146:149], v[192:195], v[92:95]
	v_mfma_f32_16x16x32_bf16 v[88:91], v[154:157], v[192:195], v[88:91]
	v_mfma_f32_16x16x32_bf16 v[76:79], v[146:149], v[212:215], v[76:79]
	v_mfma_f32_16x16x32_bf16 v[72:75], v[154:157], v[212:215], v[72:75]
	s_setprio 0
	s_barrier
	s_add_i32 s20, 0, 0x1c000
	s_add_i32 s14, s42, s25
	v_add_u32_e32 v196, s20, v143
	v_lshl_add_u64 v[140:141], v[140:141], 0, s[6:7]
	s_mov_b32 m0, s14
	ds_read_b128 v[216:219], v196
	ds_read_b128 v[220:223], v196 offset:1024
	ds_read_b128 v[224:227], v196 offset:2048
	ds_read_b128 v[228:231], v196 offset:3072
	global_load_lds_dwordx4 v[140:141], off
	v_lshl_add_u64 v[140:141], v[232:233], 0, s[6:7]
	s_add_i32 m0, s14, 0x2000
	s_nop 0
	global_load_lds_dwordx4 v[140:141], off
	s_barrier
	s_waitcnt lgkmcnt(0)
	s_setprio 1
	s_waitcnt lgkmcnt(0)
	v_mfma_f32_16x16x32_bf16 v[116:119], v[216:219], v[158:161], v[116:119]
	v_mfma_f32_16x16x32_bf16 v[112:115], v[224:227], v[158:161], v[112:115]
	v_mfma_f32_16x16x32_bf16 v[100:103], v[216:219], v[180:183], v[100:103]
	v_mfma_f32_16x16x32_bf16 v[96:99], v[224:227], v[180:183], v[96:99]
	v_mfma_f32_16x16x32_bf16 v[84:87], v[216:219], v[188:191], v[84:87]
	v_mfma_f32_16x16x32_bf16 v[80:83], v[224:227], v[188:191], v[80:83]
	v_mfma_f32_16x16x32_bf16 v[68:71], v[216:219], v[208:211], v[68:71]
	v_mfma_f32_16x16x32_bf16 v[64:67], v[224:227], v[208:211], v[64:67]
	v_mfma_f32_16x16x32_bf16 v[116:119], v[220:223], v[176:179], v[116:119]
	v_mfma_f32_16x16x32_bf16 v[112:115], v[228:231], v[176:179], v[112:115]
	v_mfma_f32_16x16x32_bf16 v[100:103], v[220:223], v[184:187], v[100:103]
	v_mfma_f32_16x16x32_bf16 v[96:99], v[228:231], v[184:187], v[96:99]
	v_mfma_f32_16x16x32_bf16 v[84:87], v[220:223], v[192:195], v[84:87]
	v_mfma_f32_16x16x32_bf16 v[80:83], v[228:231], v[192:195], v[80:83]
	v_mfma_f32_16x16x32_bf16 v[68:71], v[220:223], v[212:215], v[68:71]
	v_mfma_f32_16x16x32_bf16 v[64:67], v[228:231], v[212:215], v[64:67]
	s_setprio 0
	s_mov_b32 m0, s30
	v_lshl_add_u64 v[140:141], v[234:235], 0, s[6:7]
	s_barrier
	ds_read_b128 v[158:161], v145 offset:49152
	ds_read_b128 v[176:179], v145 offset:50176
	ds_read_b128 v[180:183], v145 offset:51200
	ds_read_b128 v[184:187], v145 offset:52224
	ds_read_b128 v[188:191], v145 offset:53248
	ds_read_b128 v[192:195], v145 offset:54272
	ds_read_b128 v[208:211], v145 offset:55296
	ds_read_b128 v[212:215], v145 offset:56320
	global_load_lds_dwordx4 v[140:141], off
	v_lshl_add_u64 v[140:141], v[236:237], 0, s[6:7]
	s_mov_b32 m0, s31
	s_nop 0
	global_load_lds_dwordx4 v[140:141], off
	s_barrier
	s_waitcnt lgkmcnt(0)
	s_setprio 1
	s_waitcnt lgkmcnt(0)
	v_mfma_f32_16x16x32_bf16 v[60:63], v[136:139], v[158:161], v[60:63]
	v_mfma_f32_16x16x32_bf16 v[56:59], v[150:153], v[158:161], v[56:59]
	v_mfma_f32_16x16x32_bf16 v[44:47], v[136:139], v[180:183], v[44:47]
	v_mfma_f32_16x16x32_bf16 v[40:43], v[150:153], v[180:183], v[40:43]
	v_mfma_f32_16x16x32_bf16 v[28:31], v[136:139], v[188:191], v[28:31]
	v_mfma_f32_16x16x32_bf16 v[24:27], v[150:153], v[188:191], v[24:27]
	v_mfma_f32_16x16x32_bf16 v[12:15], v[136:139], v[208:211], v[12:15]
	v_mfma_f32_16x16x32_bf16 v[8:11], v[150:153], v[208:211], v[8:11]
	v_mfma_f32_16x16x32_bf16 v[60:63], v[146:149], v[176:179], v[60:63]
	v_mfma_f32_16x16x32_bf16 v[56:59], v[154:157], v[176:179], v[56:59]
	v_mfma_f32_16x16x32_bf16 v[44:47], v[146:149], v[184:187], v[44:47]
	v_mfma_f32_16x16x32_bf16 v[40:43], v[154:157], v[184:187], v[40:43]
	v_mfma_f32_16x16x32_bf16 v[28:31], v[146:149], v[192:195], v[28:31]
	v_mfma_f32_16x16x32_bf16 v[24:27], v[154:157], v[192:195], v[24:27]
	v_mfma_f32_16x16x32_bf16 v[12:15], v[146:149], v[212:215], v[12:15]
	v_mfma_f32_16x16x32_bf16 v[8:11], v[154:157], v[212:215], v[8:11]
	s_setprio 0
	s_barrier
	s_add_u32 s14, s18, 0x160080
	s_addc_u32 s15, s19, 0
	s_add_i32 s18, s20, s25
	v_lshl_add_u64 v[136:137], s[14:15], 0, v[128:129]
	s_mov_b32 m0, s18
	s_nop 0
	global_load_lds_dwordx4 v[136:137], off
	v_lshl_add_u64 v[136:137], s[14:15], 0, v[130:131]
	s_add_i32 m0, s18, 0x2000
	s_nop 0
	global_load_lds_dwordx4 v[136:137], off
	s_waitcnt vmcnt(6)
	s_barrier
	s_setprio 1
	v_mfma_f32_16x16x32_bf16 v[52:55], v[216:219], v[158:161], v[52:55]
	v_mfma_f32_16x16x32_bf16 v[48:51], v[224:227], v[158:161], v[48:51]
	v_mfma_f32_16x16x32_bf16 v[36:39], v[216:219], v[180:183], v[36:39]
	v_mfma_f32_16x16x32_bf16 v[32:35], v[224:227], v[180:183], v[32:35]
	v_mfma_f32_16x16x32_bf16 v[20:23], v[216:219], v[188:191], v[20:23]
	v_mfma_f32_16x16x32_bf16 v[16:19], v[224:227], v[188:191], v[16:19]
	v_mfma_f32_16x16x32_bf16 v[4:7], v[216:219], v[208:211], v[4:7]
	v_mfma_f32_16x16x32_bf16 v[0:3], v[224:227], v[208:211], v[0:3]
	v_mfma_f32_16x16x32_bf16 v[52:55], v[220:223], v[176:179], v[52:55]
	v_mfma_f32_16x16x32_bf16 v[48:51], v[228:231], v[176:179], v[48:51]
	v_mfma_f32_16x16x32_bf16 v[36:39], v[220:223], v[184:187], v[36:39]
	v_mfma_f32_16x16x32_bf16 v[32:35], v[228:231], v[184:187], v[32:35]
	v_mfma_f32_16x16x32_bf16 v[20:23], v[220:223], v[192:195], v[20:23]
	v_mfma_f32_16x16x32_bf16 v[16:19], v[228:231], v[192:195], v[16:19]
	v_mfma_f32_16x16x32_bf16 v[4:7], v[220:223], v[212:215], v[4:7]
	v_mfma_f32_16x16x32_bf16 v[0:3], v[228:231], v[212:215], v[0:3]
	s_setprio 0
	s_add_i32 s41, s41, 2
	s_add_u32 s39, s39, 0x100
	s_addc_u32 s40, s40, 0
	s_cmpk_gt_u32 s41, 0x55
	s_mov_b64 s[14:15], s[16:17]
	s_barrier
	s_cbranch_scc0 .LBB0_129
	v_lshl_add_u32 v140, s37, 8, v142
	v_lshl_or_b32 v138, s38, 8, v144
	v_ashrrev_i32_e32 v141, 31, v140
	v_ashrrev_i32_e32 v139, 31, v138
	v_lshlrev_b64 v[136:137], 11, v[140:141]
	v_readlane_b32 s16, v255, 34
	v_lshl_add_u64 v[136:137], v[136:137], 0, v[138:139]
	v_readlane_b32 s17, v255, 35
	s_mov_b64 s[14:15], 0x40000
	s_and_b64 vcc, exec, s[8:9]
	v_lshl_add_u64 v[146:147], v[136:137], 1, s[16:17]
	global_load_dwordx2 v[148:149], v[146:147], off
	s_mov_b32 s38, s35
	s_mov_b32 s37, s36
	s_waitcnt vmcnt(0)
	v_lshlrev_b32_e32 v150, 16, v148
	v_and_b32_e32 v151, 0xffff0000, v148
	v_lshlrev_b32_e32 v148, 16, v149
	v_and_b32_e32 v149, 0xffff0000, v149
	v_pk_mul_f32 v[150:151], v[150:151], s[74:75] op_sel_hi:[1,0]
	v_pk_mul_f32 v[148:149], v[148:149], s[74:75] op_sel_hi:[1,0]
	v_pk_fma_f32 v[124:125], v[124:125], 0.5, v[150:151] op_sel_hi:[1,0,1]
	v_pk_fma_f32 v[126:127], v[126:127], 0.5, v[148:149] op_sel_hi:[1,0,1]
	v_lshl_add_u64 v[148:149], v[136:137], 2, s[76:77]
	global_store_dwordx4 v[148:149], v[124:127], off
	global_load_dwordx2 v[124:125], v[146:147], off offset:32
	s_waitcnt vmcnt(0)
	v_lshlrev_b32_e32 v126, 16, v124
	v_and_b32_e32 v127, 0xffff0000, v124
	v_lshlrev_b32_e32 v124, 16, v125
	v_and_b32_e32 v125, 0xffff0000, v125
	v_pk_mul_f32 v[126:127], v[126:127], s[74:75] op_sel_hi:[1,0]
	v_pk_mul_f32 v[124:125], v[124:125], s[74:75] op_sel_hi:[1,0]
	v_pk_fma_f32 v[120:121], v[120:121], 0.5, v[126:127] op_sel_hi:[1,0,1]
	v_pk_fma_f32 v[122:123], v[122:123], 0.5, v[124:125] op_sel_hi:[1,0,1]
	global_store_dwordx4 v[148:149], v[120:123], off offset:64
	global_load_dwordx2 v[120:121], v[146:147], off offset:256
	s_waitcnt vmcnt(0)
	v_lshlrev_b32_e32 v122, 16, v120
	v_and_b32_e32 v123, 0xffff0000, v120
	v_lshlrev_b32_e32 v120, 16, v121
	v_and_b32_e32 v121, 0xffff0000, v121
	v_pk_mul_f32 v[122:123], v[122:123], s[74:75] op_sel_hi:[1,0]
	v_pk_mul_f32 v[120:121], v[120:121], s[74:75] op_sel_hi:[1,0]
	v_pk_fma_f32 v[116:117], v[116:117], 0.5, v[122:123] op_sel_hi:[1,0,1]
	v_pk_fma_f32 v[118:119], v[118:119], 0.5, v[120:121] op_sel_hi:[1,0,1]
	global_store_dwordx4 v[148:149], v[116:119], off offset:512
	global_load_dwordx2 v[116:117], v[146:147], off offset:288
	s_waitcnt vmcnt(0)
	v_lshlrev_b32_e32 v118, 16, v116
	v_and_b32_e32 v119, 0xffff0000, v116
	v_lshlrev_b32_e32 v116, 16, v117
	v_and_b32_e32 v117, 0xffff0000, v117
	v_pk_mul_f32 v[118:119], v[118:119], s[74:75] op_sel_hi:[1,0]
	v_pk_mul_f32 v[116:117], v[116:117], s[74:75] op_sel_hi:[1,0]
	v_pk_fma_f32 v[112:113], v[112:113], 0.5, v[118:119] op_sel_hi:[1,0,1]
	v_pk_fma_f32 v[114:115], v[114:115], 0.5, v[116:117] op_sel_hi:[1,0,1]
	global_store_dwordx4 v[148:149], v[112:115], off offset:576
	s_nop 1
	v_or_b32_e32 v112, 16, v140
	v_ashrrev_i32_e32 v113, 31, v112
	v_lshlrev_b64 v[112:113], 11, v[112:113]
	v_lshl_add_u64 v[112:113], v[112:113], 0, v[138:139]
	v_lshl_add_u64 v[114:115], v[112:113], 1, s[16:17]
	global_load_dwordx2 v[116:117], v[114:115], off
	v_lshl_add_u64 v[112:113], v[112:113], 2, s[76:77]
	s_waitcnt vmcnt(0)
	v_lshlrev_b32_e32 v118, 16, v116
	v_and_b32_e32 v119, 0xffff0000, v116
	v_lshlrev_b32_e32 v116, 16, v117
	v_and_b32_e32 v117, 0xffff0000, v117
	v_pk_mul_f32 v[118:119], v[118:119], s[74:75] op_sel_hi:[1,0]
	v_pk_mul_f32 v[116:117], v[116:117], s[74:75] op_sel_hi:[1,0]
	v_pk_fma_f32 v[108:109], v[108:109], 0.5, v[118:119] op_sel_hi:[1,0,1]
	v_pk_fma_f32 v[110:111], v[110:111], 0.5, v[116:117] op_sel_hi:[1,0,1]
	global_store_dwordx4 v[112:113], v[108:111], off
	global_load_dwordx2 v[108:109], v[114:115], off offset:32
	s_waitcnt vmcnt(0)
	v_lshlrev_b32_e32 v110, 16, v108
	v_and_b32_e32 v111, 0xffff0000, v108
	v_lshlrev_b32_e32 v108, 16, v109
	v_and_b32_e32 v109, 0xffff0000, v109
	v_pk_mul_f32 v[110:111], v[110:111], s[74:75] op_sel_hi:[1,0]
	v_pk_mul_f32 v[108:109], v[108:109], s[74:75] op_sel_hi:[1,0]
	v_pk_fma_f32 v[104:105], v[104:105], 0.5, v[110:111] op_sel_hi:[1,0,1]
	v_pk_fma_f32 v[106:107], v[106:107], 0.5, v[108:109] op_sel_hi:[1,0,1]
	global_store_dwordx4 v[112:113], v[104:107], off offset:64
	global_load_dwordx2 v[104:105], v[114:115], off offset:256
	s_waitcnt vmcnt(0)
	v_lshlrev_b32_e32 v106, 16, v104
	v_and_b32_e32 v107, 0xffff0000, v104
	v_lshlrev_b32_e32 v104, 16, v105
	v_and_b32_e32 v105, 0xffff0000, v105
	v_pk_mul_f32 v[106:107], v[106:107], s[74:75] op_sel_hi:[1,0]
	v_pk_mul_f32 v[104:105], v[104:105], s[74:75] op_sel_hi:[1,0]
	v_pk_fma_f32 v[100:101], v[100:101], 0.5, v[106:107] op_sel_hi:[1,0,1]
	v_pk_fma_f32 v[102:103], v[102:103], 0.5, v[104:105] op_sel_hi:[1,0,1]
	global_store_dwordx4 v[112:113], v[100:103], off offset:512
	global_load_dwordx2 v[100:101], v[114:115], off offset:288
	s_waitcnt vmcnt(0)
	v_lshlrev_b32_e32 v102, 16, v100
	v_and_b32_e32 v103, 0xffff0000, v100
	v_lshlrev_b32_e32 v100, 16, v101
	v_and_b32_e32 v101, 0xffff0000, v101
	v_pk_mul_f32 v[102:103], v[102:103], s[74:75] op_sel_hi:[1,0]
	v_pk_mul_f32 v[100:101], v[100:101], s[74:75] op_sel_hi:[1,0]
	v_pk_fma_f32 v[96:97], v[96:97], 0.5, v[102:103] op_sel_hi:[1,0,1]
	v_pk_fma_f32 v[98:99], v[98:99], 0.5, v[100:101] op_sel_hi:[1,0,1]
	global_store_dwordx4 v[112:113], v[96:99], off offset:576
	s_nop 1
	v_or_b32_e32 v96, 32, v140
	v_ashrrev_i32_e32 v97, 31, v96
	v_lshlrev_b64 v[96:97], 11, v[96:97]
	v_lshl_add_u64 v[96:97], v[96:97], 0, v[138:139]
	v_lshl_add_u64 v[98:99], v[96:97], 1, s[16:17]
	global_load_dwordx2 v[100:101], v[98:99], off
	v_lshl_add_u64 v[96:97], v[96:97], 2, s[76:77]
	s_waitcnt vmcnt(0)
	v_lshlrev_b32_e32 v102, 16, v100
	v_and_b32_e32 v103, 0xffff0000, v100
	v_lshlrev_b32_e32 v100, 16, v101
	v_and_b32_e32 v101, 0xffff0000, v101
	v_pk_mul_f32 v[102:103], v[102:103], s[74:75] op_sel_hi:[1,0]
	v_pk_mul_f32 v[100:101], v[100:101], s[74:75] op_sel_hi:[1,0]
	v_pk_fma_f32 v[92:93], v[92:93], 0.5, v[102:103] op_sel_hi:[1,0,1]
	v_pk_fma_f32 v[94:95], v[94:95], 0.5, v[100:101] op_sel_hi:[1,0,1]
	global_store_dwordx4 v[96:97], v[92:95], off
	global_load_dwordx2 v[92:93], v[98:99], off offset:32
	s_waitcnt vmcnt(0)
	v_lshlrev_b32_e32 v94, 16, v92
	v_and_b32_e32 v95, 0xffff0000, v92
	v_lshlrev_b32_e32 v92, 16, v93
	v_and_b32_e32 v93, 0xffff0000, v93
	v_pk_mul_f32 v[94:95], v[94:95], s[74:75] op_sel_hi:[1,0]
	v_pk_mul_f32 v[92:93], v[92:93], s[74:75] op_sel_hi:[1,0]
	v_pk_fma_f32 v[88:89], v[88:89], 0.5, v[94:95] op_sel_hi:[1,0,1]
	v_pk_fma_f32 v[90:91], v[90:91], 0.5, v[92:93] op_sel_hi:[1,0,1]
	global_store_dwordx4 v[96:97], v[88:91], off offset:64
	global_load_dwordx2 v[88:89], v[98:99], off offset:256
	s_waitcnt vmcnt(0)
	v_lshlrev_b32_e32 v90, 16, v88
	v_and_b32_e32 v91, 0xffff0000, v88
	v_lshlrev_b32_e32 v88, 16, v89
	v_and_b32_e32 v89, 0xffff0000, v89
	v_pk_mul_f32 v[90:91], v[90:91], s[74:75] op_sel_hi:[1,0]
	v_pk_mul_f32 v[88:89], v[88:89], s[74:75] op_sel_hi:[1,0]
	v_pk_fma_f32 v[84:85], v[84:85], 0.5, v[90:91] op_sel_hi:[1,0,1]
	v_pk_fma_f32 v[86:87], v[86:87], 0.5, v[88:89] op_sel_hi:[1,0,1]
	global_store_dwordx4 v[96:97], v[84:87], off offset:512
	global_load_dwordx2 v[84:85], v[98:99], off offset:288
	s_waitcnt vmcnt(0)
	v_lshlrev_b32_e32 v86, 16, v84
	v_and_b32_e32 v87, 0xffff0000, v84
	v_lshlrev_b32_e32 v84, 16, v85
	v_and_b32_e32 v85, 0xffff0000, v85
	v_pk_mul_f32 v[86:87], v[86:87], s[74:75] op_sel_hi:[1,0]
	v_pk_mul_f32 v[84:85], v[84:85], s[74:75] op_sel_hi:[1,0]
	v_pk_fma_f32 v[80:81], v[80:81], 0.5, v[86:87] op_sel_hi:[1,0,1]
	v_pk_fma_f32 v[82:83], v[82:83], 0.5, v[84:85] op_sel_hi:[1,0,1]
	global_store_dwordx4 v[96:97], v[80:83], off offset:576
	s_nop 1
	v_or_b32_e32 v80, 48, v140
	v_ashrrev_i32_e32 v81, 31, v80
	v_lshlrev_b64 v[80:81], 11, v[80:81]
	v_lshl_add_u64 v[80:81], v[80:81], 0, v[138:139]
	v_lshl_add_u64 v[82:83], v[80:81], 1, s[16:17]
	global_load_dwordx2 v[84:85], v[82:83], off
	v_lshl_add_u64 v[80:81], v[80:81], 2, s[76:77]
	s_waitcnt vmcnt(0)
	v_lshlrev_b32_e32 v86, 16, v84
	v_and_b32_e32 v87, 0xffff0000, v84
	v_lshlrev_b32_e32 v84, 16, v85
	v_and_b32_e32 v85, 0xffff0000, v85
	v_pk_mul_f32 v[86:87], v[86:87], s[74:75] op_sel_hi:[1,0]
	v_pk_mul_f32 v[84:85], v[84:85], s[74:75] op_sel_hi:[1,0]
	v_pk_fma_f32 v[76:77], v[76:77], 0.5, v[86:87] op_sel_hi:[1,0,1]
	v_pk_fma_f32 v[78:79], v[78:79], 0.5, v[84:85] op_sel_hi:[1,0,1]
	global_store_dwordx4 v[80:81], v[76:79], off
	global_load_dwordx2 v[76:77], v[82:83], off offset:32
	s_waitcnt vmcnt(0)
	v_lshlrev_b32_e32 v78, 16, v76
	v_and_b32_e32 v79, 0xffff0000, v76
	v_lshlrev_b32_e32 v76, 16, v77
	v_and_b32_e32 v77, 0xffff0000, v77
	v_pk_mul_f32 v[78:79], v[78:79], s[74:75] op_sel_hi:[1,0]
	v_pk_mul_f32 v[76:77], v[76:77], s[74:75] op_sel_hi:[1,0]
	v_pk_fma_f32 v[72:73], v[72:73], 0.5, v[78:79] op_sel_hi:[1,0,1]
	v_pk_fma_f32 v[74:75], v[74:75], 0.5, v[76:77] op_sel_hi:[1,0,1]
	global_store_dwordx4 v[80:81], v[72:75], off offset:64
	global_load_dwordx2 v[72:73], v[82:83], off offset:256
	s_waitcnt vmcnt(0)
	v_lshlrev_b32_e32 v74, 16, v72
	v_and_b32_e32 v75, 0xffff0000, v72
	v_lshlrev_b32_e32 v72, 16, v73
	v_and_b32_e32 v73, 0xffff0000, v73
	v_pk_mul_f32 v[74:75], v[74:75], s[74:75] op_sel_hi:[1,0]
	v_pk_mul_f32 v[72:73], v[72:73], s[74:75] op_sel_hi:[1,0]
	v_pk_fma_f32 v[68:69], v[68:69], 0.5, v[74:75] op_sel_hi:[1,0,1]
	v_pk_fma_f32 v[70:71], v[70:71], 0.5, v[72:73] op_sel_hi:[1,0,1]
	global_store_dwordx4 v[80:81], v[68:71], off offset:512
	global_load_dwordx2 v[68:69], v[82:83], off offset:288
	s_waitcnt vmcnt(0)
	v_lshlrev_b32_e32 v70, 16, v68
	v_and_b32_e32 v71, 0xffff0000, v68
	v_lshlrev_b32_e32 v68, 16, v69
	v_and_b32_e32 v69, 0xffff0000, v69
	v_pk_mul_f32 v[70:71], v[70:71], s[74:75] op_sel_hi:[1,0]
	v_pk_mul_f32 v[68:69], v[68:69], s[74:75] op_sel_hi:[1,0]
	v_pk_fma_f32 v[64:65], v[64:65], 0.5, v[70:71] op_sel_hi:[1,0,1]
	v_pk_fma_f32 v[66:67], v[66:67], 0.5, v[68:69] op_sel_hi:[1,0,1]
	global_store_dwordx4 v[80:81], v[64:67], off offset:576
	s_nop 1
	v_lshl_add_u64 v[64:65], v[136:137], 0, s[14:15]
	v_lshl_add_u64 v[66:67], v[64:65], 1, s[16:17]
	global_load_dwordx2 v[68:69], v[66:67], off
	v_lshl_add_u64 v[64:65], v[64:65], 2, s[76:77]
	s_mov_b64 s[14:15], 0x48000
	s_waitcnt vmcnt(0)
	v_lshlrev_b32_e32 v70, 16, v68
	v_and_b32_e32 v71, 0xffff0000, v68
	v_lshlrev_b32_e32 v68, 16, v69
	v_and_b32_e32 v69, 0xffff0000, v69
	v_pk_mul_f32 v[70:71], v[70:71], s[74:75] op_sel_hi:[1,0]
	v_pk_mul_f32 v[68:69], v[68:69], s[74:75] op_sel_hi:[1,0]
	v_pk_fma_f32 v[60:61], v[60:61], 0.5, v[70:71] op_sel_hi:[1,0,1]
	v_pk_fma_f32 v[62:63], v[62:63], 0.5, v[68:69] op_sel_hi:[1,0,1]
	global_store_dwordx4 v[64:65], v[60:63], off
	global_load_dwordx2 v[60:61], v[66:67], off offset:32
	s_waitcnt vmcnt(0)
	v_lshlrev_b32_e32 v62, 16, v60
	v_and_b32_e32 v63, 0xffff0000, v60
	v_lshlrev_b32_e32 v60, 16, v61
	v_and_b32_e32 v61, 0xffff0000, v61
	v_pk_mul_f32 v[62:63], v[62:63], s[74:75] op_sel_hi:[1,0]
	v_pk_mul_f32 v[60:61], v[60:61], s[74:75] op_sel_hi:[1,0]
	v_pk_fma_f32 v[56:57], v[56:57], 0.5, v[62:63] op_sel_hi:[1,0,1]
	v_pk_fma_f32 v[58:59], v[58:59], 0.5, v[60:61] op_sel_hi:[1,0,1]
	global_store_dwordx4 v[64:65], v[56:59], off offset:64
	global_load_dwordx2 v[56:57], v[66:67], off offset:256
	s_waitcnt vmcnt(0)
	v_lshlrev_b32_e32 v58, 16, v56
	v_and_b32_e32 v59, 0xffff0000, v56
	v_lshlrev_b32_e32 v56, 16, v57
	v_and_b32_e32 v57, 0xffff0000, v57
	v_pk_mul_f32 v[58:59], v[58:59], s[74:75] op_sel_hi:[1,0]
	v_pk_mul_f32 v[56:57], v[56:57], s[74:75] op_sel_hi:[1,0]
	v_pk_fma_f32 v[52:53], v[52:53], 0.5, v[58:59] op_sel_hi:[1,0,1]
	v_pk_fma_f32 v[54:55], v[54:55], 0.5, v[56:57] op_sel_hi:[1,0,1]
	global_store_dwordx4 v[64:65], v[52:55], off offset:512
	global_load_dwordx2 v[52:53], v[66:67], off offset:288
	s_waitcnt vmcnt(0)
	v_lshlrev_b32_e32 v54, 16, v52
	v_and_b32_e32 v55, 0xffff0000, v52
	v_lshlrev_b32_e32 v52, 16, v53
	v_and_b32_e32 v53, 0xffff0000, v53
	v_pk_mul_f32 v[54:55], v[54:55], s[74:75] op_sel_hi:[1,0]
	v_pk_mul_f32 v[52:53], v[52:53], s[74:75] op_sel_hi:[1,0]
	v_pk_fma_f32 v[48:49], v[48:49], 0.5, v[54:55] op_sel_hi:[1,0,1]
	v_pk_fma_f32 v[50:51], v[50:51], 0.5, v[52:53] op_sel_hi:[1,0,1]
	global_store_dwordx4 v[64:65], v[48:51], off offset:576
	s_nop 1
	v_lshl_add_u64 v[48:49], v[136:137], 0, s[14:15]
	v_lshl_add_u64 v[50:51], v[48:49], 1, s[16:17]
	global_load_dwordx2 v[52:53], v[50:51], off
	v_lshl_add_u64 v[48:49], v[48:49], 2, s[76:77]
	s_mov_b64 s[14:15], 0x50000
	s_waitcnt vmcnt(0)
	v_lshlrev_b32_e32 v54, 16, v52
	v_and_b32_e32 v55, 0xffff0000, v52
	v_lshlrev_b32_e32 v52, 16, v53
	v_and_b32_e32 v53, 0xffff0000, v53
	v_pk_mul_f32 v[54:55], v[54:55], s[74:75] op_sel_hi:[1,0]
	v_pk_mul_f32 v[52:53], v[52:53], s[74:75] op_sel_hi:[1,0]
	v_pk_fma_f32 v[44:45], v[44:45], 0.5, v[54:55] op_sel_hi:[1,0,1]
	v_pk_fma_f32 v[46:47], v[46:47], 0.5, v[52:53] op_sel_hi:[1,0,1]
	global_store_dwordx4 v[48:49], v[44:47], off
	global_load_dwordx2 v[44:45], v[50:51], off offset:32
	s_waitcnt vmcnt(0)
	v_lshlrev_b32_e32 v46, 16, v44
	v_and_b32_e32 v47, 0xffff0000, v44
	v_lshlrev_b32_e32 v44, 16, v45
	v_and_b32_e32 v45, 0xffff0000, v45
	v_pk_mul_f32 v[46:47], v[46:47], s[74:75] op_sel_hi:[1,0]
	v_pk_mul_f32 v[44:45], v[44:45], s[74:75] op_sel_hi:[1,0]
	v_pk_fma_f32 v[40:41], v[40:41], 0.5, v[46:47] op_sel_hi:[1,0,1]
	v_pk_fma_f32 v[42:43], v[42:43], 0.5, v[44:45] op_sel_hi:[1,0,1]
	global_store_dwordx4 v[48:49], v[40:43], off offset:64
	global_load_dwordx2 v[40:41], v[50:51], off offset:256
	s_waitcnt vmcnt(0)
	v_lshlrev_b32_e32 v42, 16, v40
	v_and_b32_e32 v43, 0xffff0000, v40
	v_lshlrev_b32_e32 v40, 16, v41
	v_and_b32_e32 v41, 0xffff0000, v41
	v_pk_mul_f32 v[42:43], v[42:43], s[74:75] op_sel_hi:[1,0]
	v_pk_mul_f32 v[40:41], v[40:41], s[74:75] op_sel_hi:[1,0]
	v_pk_fma_f32 v[36:37], v[36:37], 0.5, v[42:43] op_sel_hi:[1,0,1]
	v_pk_fma_f32 v[38:39], v[38:39], 0.5, v[40:41] op_sel_hi:[1,0,1]
	global_store_dwordx4 v[48:49], v[36:39], off offset:512
	global_load_dwordx2 v[36:37], v[50:51], off offset:288
	s_waitcnt vmcnt(0)
	v_lshlrev_b32_e32 v38, 16, v36
	v_and_b32_e32 v39, 0xffff0000, v36
	v_lshlrev_b32_e32 v36, 16, v37
	v_and_b32_e32 v37, 0xffff0000, v37
	v_pk_mul_f32 v[38:39], v[38:39], s[74:75] op_sel_hi:[1,0]
	v_pk_mul_f32 v[36:37], v[36:37], s[74:75] op_sel_hi:[1,0]
	v_pk_fma_f32 v[32:33], v[32:33], 0.5, v[38:39] op_sel_hi:[1,0,1]
	v_pk_fma_f32 v[34:35], v[34:35], 0.5, v[36:37] op_sel_hi:[1,0,1]
	global_store_dwordx4 v[48:49], v[32:35], off offset:576
	s_nop 1
	v_lshl_add_u64 v[32:33], v[136:137], 0, s[14:15]
	v_lshl_add_u64 v[34:35], v[32:33], 1, s[16:17]
	global_load_dwordx2 v[36:37], v[34:35], off
	v_lshl_add_u64 v[32:33], v[32:33], 2, s[76:77]
	s_mov_b64 s[14:15], 0x58000
	s_waitcnt vmcnt(0)
	v_lshlrev_b32_e32 v38, 16, v36
	v_and_b32_e32 v39, 0xffff0000, v36
	v_lshlrev_b32_e32 v36, 16, v37
	v_and_b32_e32 v37, 0xffff0000, v37
	v_pk_mul_f32 v[38:39], v[38:39], s[74:75] op_sel_hi:[1,0]
	v_pk_mul_f32 v[36:37], v[36:37], s[74:75] op_sel_hi:[1,0]
	v_pk_fma_f32 v[28:29], v[28:29], 0.5, v[38:39] op_sel_hi:[1,0,1]
	v_pk_fma_f32 v[30:31], v[30:31], 0.5, v[36:37] op_sel_hi:[1,0,1]
	global_store_dwordx4 v[32:33], v[28:31], off
	global_load_dwordx2 v[28:29], v[34:35], off offset:32
	s_waitcnt vmcnt(0)
	v_lshlrev_b32_e32 v30, 16, v28
	v_and_b32_e32 v31, 0xffff0000, v28
	v_lshlrev_b32_e32 v28, 16, v29
	v_and_b32_e32 v29, 0xffff0000, v29
	v_pk_mul_f32 v[30:31], v[30:31], s[74:75] op_sel_hi:[1,0]
	v_pk_mul_f32 v[28:29], v[28:29], s[74:75] op_sel_hi:[1,0]
	v_pk_fma_f32 v[24:25], v[24:25], 0.5, v[30:31] op_sel_hi:[1,0,1]
	v_pk_fma_f32 v[26:27], v[26:27], 0.5, v[28:29] op_sel_hi:[1,0,1]
	global_store_dwordx4 v[32:33], v[24:27], off offset:64
	global_load_dwordx2 v[24:25], v[34:35], off offset:256
	s_waitcnt vmcnt(0)
	v_lshlrev_b32_e32 v26, 16, v24
	v_and_b32_e32 v27, 0xffff0000, v24
	v_lshlrev_b32_e32 v24, 16, v25
	v_and_b32_e32 v25, 0xffff0000, v25
	v_pk_mul_f32 v[26:27], v[26:27], s[74:75] op_sel_hi:[1,0]
	v_pk_mul_f32 v[24:25], v[24:25], s[74:75] op_sel_hi:[1,0]
	v_pk_fma_f32 v[20:21], v[20:21], 0.5, v[26:27] op_sel_hi:[1,0,1]
	v_pk_fma_f32 v[22:23], v[22:23], 0.5, v[24:25] op_sel_hi:[1,0,1]
	global_store_dwordx4 v[32:33], v[20:23], off offset:512
	global_load_dwordx2 v[20:21], v[34:35], off offset:288
	s_waitcnt vmcnt(0)
	v_lshlrev_b32_e32 v22, 16, v20
	v_and_b32_e32 v23, 0xffff0000, v20
	v_lshlrev_b32_e32 v20, 16, v21
	v_and_b32_e32 v21, 0xffff0000, v21
	v_pk_mul_f32 v[22:23], v[22:23], s[74:75] op_sel_hi:[1,0]
	v_pk_mul_f32 v[20:21], v[20:21], s[74:75] op_sel_hi:[1,0]
	v_pk_fma_f32 v[16:17], v[16:17], 0.5, v[22:23] op_sel_hi:[1,0,1]
	v_pk_fma_f32 v[18:19], v[18:19], 0.5, v[20:21] op_sel_hi:[1,0,1]
	global_store_dwordx4 v[32:33], v[16:19], off offset:576
	s_nop 1
	v_lshl_add_u64 v[16:17], v[136:137], 0, s[14:15]
	v_lshl_add_u64 v[18:19], v[16:17], 1, s[16:17]
	global_load_dwordx2 v[20:21], v[18:19], off
	v_lshl_add_u64 v[16:17], v[16:17], 2, s[76:77]
	s_mov_b64 s[16:17], s[12:13]
	s_mov_b64 s[14:15], s[10:11]
	s_waitcnt vmcnt(0)
	v_lshlrev_b32_e32 v22, 16, v20
	v_and_b32_e32 v23, 0xffff0000, v20
	v_lshlrev_b32_e32 v20, 16, v21
	v_and_b32_e32 v21, 0xffff0000, v21
	v_pk_mul_f32 v[22:23], v[22:23], s[74:75] op_sel_hi:[1,0]
	v_pk_mul_f32 v[20:21], v[20:21], s[74:75] op_sel_hi:[1,0]
	v_pk_fma_f32 v[12:13], v[12:13], 0.5, v[22:23] op_sel_hi:[1,0,1]
	v_pk_fma_f32 v[14:15], v[14:15], 0.5, v[20:21] op_sel_hi:[1,0,1]
	global_store_dwordx4 v[16:17], v[12:15], off
	global_load_dwordx2 v[12:13], v[18:19], off offset:32
	s_waitcnt vmcnt(0)
	v_lshlrev_b32_e32 v14, 16, v12
	v_and_b32_e32 v15, 0xffff0000, v12
	v_lshlrev_b32_e32 v12, 16, v13
	v_and_b32_e32 v13, 0xffff0000, v13
	v_pk_mul_f32 v[14:15], v[14:15], s[74:75] op_sel_hi:[1,0]
	v_pk_mul_f32 v[12:13], v[12:13], s[74:75] op_sel_hi:[1,0]
	v_pk_fma_f32 v[8:9], v[8:9], 0.5, v[14:15] op_sel_hi:[1,0,1]
	v_pk_fma_f32 v[10:11], v[10:11], 0.5, v[12:13] op_sel_hi:[1,0,1]
	global_store_dwordx4 v[16:17], v[8:11], off offset:64
	global_load_dwordx2 v[8:9], v[18:19], off offset:256
	s_waitcnt vmcnt(0)
	v_lshlrev_b32_e32 v10, 16, v8
	v_and_b32_e32 v11, 0xffff0000, v8
	v_lshlrev_b32_e32 v8, 16, v9
	v_and_b32_e32 v9, 0xffff0000, v9
	v_pk_mul_f32 v[10:11], v[10:11], s[74:75] op_sel_hi:[1,0]
	v_pk_mul_f32 v[8:9], v[8:9], s[74:75] op_sel_hi:[1,0]
	v_pk_fma_f32 v[4:5], v[4:5], 0.5, v[10:11] op_sel_hi:[1,0,1]
	v_pk_fma_f32 v[6:7], v[6:7], 0.5, v[8:9] op_sel_hi:[1,0,1]
	global_store_dwordx4 v[16:17], v[4:7], off offset:512
	global_load_dwordx2 v[4:5], v[18:19], off offset:288
	s_waitcnt vmcnt(0)
	v_lshlrev_b32_e32 v6, 16, v4
	v_and_b32_e32 v7, 0xffff0000, v4
	v_lshlrev_b32_e32 v4, 16, v5
	v_and_b32_e32 v5, 0xffff0000, v5
	v_pk_mul_f32 v[6:7], v[6:7], s[74:75] op_sel_hi:[1,0]
	v_pk_mul_f32 v[4:5], v[4:5], s[74:75] op_sel_hi:[1,0]
	v_pk_fma_f32 v[0:1], v[0:1], 0.5, v[6:7] op_sel_hi:[1,0,1]
	v_pk_fma_f32 v[2:3], v[2:3], 0.5, v[4:5] op_sel_hi:[1,0,1]
	global_store_dwordx4 v[16:17], v[0:3], off offset:576
	s_cbranch_vccz .LBB0_118
	s_waitcnt vmcnt(0)
	s_cmpk_gt_u32 s1, 0xff
	s_cbranch_scc1 .LBB0_133
	s_barrier

.LBB0_143:
	s_add_u32 s22, s20, 0xfff80080
	s_addc_u32 s23, s21, -1
	s_add_i32 s44, 0, 0x10000
	v_add_u32_e32 v156, s44, v141
	ds_read_b128 v[144:147], v156
	ds_read_b128 v[148:151], v156 offset:1024
	ds_read_b128 v[152:155], v156 offset:2048
	ds_read_b128 v[156:159], v156 offset:3072
	s_cmp_eq_u32 s43, 28
	s_cselect_b32 s25, s13, s23
	s_cselect_b32 s24, s39, s22
	s_cselect_b32 s23, s11, s42
	s_cselect_b32 s22, s40, s41
	v_lshl_add_u64 v[160:161], s[20:21], 0, v[136:137]
	s_add_i32 m0, s19, 0xc000
	ds_read_b128 v[176:179], v143
	ds_read_b128 v[180:183], v143 offset:1024
	ds_read_b128 v[184:187], v143 offset:2048
	ds_read_b128 v[188:191], v143 offset:3072
	ds_read_b128 v[192:195], v143 offset:4096
	ds_read_b128 v[208:211], v143 offset:5120
	ds_read_b128 v[212:215], v143 offset:6144
	ds_read_b128 v[216:219], v143 offset:7168
	global_load_lds_dwordx4 v[160:161], off
	v_lshl_add_u64 v[160:161], s[20:21], 0, v[138:139]
	s_add_i32 m0, s19, 0xe000
	s_nop 0
	global_load_lds_dwordx4 v[160:161], off
	s_waitcnt lgkmcnt(8)
	s_barrier
	s_waitcnt lgkmcnt(0)
	s_setprio 1
	s_waitcnt lgkmcnt(0)
	v_mfma_f32_16x16x32_bf16 v[124:127], v[144:147], v[176:179], v[124:127]
	v_mfma_f32_16x16x32_bf16 v[116:119], v[152:155], v[176:179], v[116:119]
	v_mfma_f32_16x16x32_bf16 v[108:111], v[144:147], v[184:187], v[108:111]
	v_mfma_f32_16x16x32_bf16 v[100:103], v[152:155], v[184:187], v[100:103]
	v_mfma_f32_16x16x32_bf16 v[92:95], v[144:147], v[192:195], v[92:95]
	v_mfma_f32_16x16x32_bf16 v[84:87], v[152:155], v[192:195], v[84:87]
	v_mfma_f32_16x16x32_bf16 v[76:79], v[144:147], v[212:215], v[76:79]
	v_mfma_f32_16x16x32_bf16 v[68:71], v[152:155], v[212:215], v[68:71]
	v_mfma_f32_16x16x32_bf16 v[124:127], v[148:151], v[180:183], v[124:127]
	v_mfma_f32_16x16x32_bf16 v[116:119], v[156:159], v[180:183], v[116:119]
	v_mfma_f32_16x16x32_bf16 v[108:111], v[148:151], v[188:191], v[108:111]
	v_mfma_f32_16x16x32_bf16 v[100:103], v[156:159], v[188:191], v[100:103]
	v_mfma_f32_16x16x32_bf16 v[92:95], v[148:151], v[208:211], v[92:95]
	v_mfma_f32_16x16x32_bf16 v[84:87], v[156:159], v[208:211], v[84:87]
	v_mfma_f32_16x16x32_bf16 v[76:79], v[148:151], v[216:219], v[76:79]
	v_mfma_f32_16x16x32_bf16 v[68:71], v[156:159], v[216:219], v[68:71]
	s_setprio 0
	s_barrier
	s_add_i32 s46, 0, 0x14000
	v_add_u32_e32 v160, s46, v141
	s_add_i32 s44, s44, s28
	ds_read_b128 v[220:223], v160
	ds_read_b128 v[224:227], v160 offset:1024
	ds_read_b128 v[228:231], v160 offset:2048
	ds_read_b128 v[232:235], v160 offset:3072
	v_lshl_add_u64 v[160:161], s[22:23], 0, v[128:129]
	s_mov_b32 m0, s44
	v_lshl_add_u64 v[236:237], s[22:23], 0, v[130:131]
	global_load_lds_dwordx4 v[160:161], off
	s_add_i32 m0, s44, 0x2000
	s_nop 0
	global_load_lds_dwordx4 v[236:237], off
	s_barrier
	s_waitcnt lgkmcnt(0)
	s_setprio 1
	s_waitcnt lgkmcnt(0)
	v_mfma_f32_16x16x32_bf16 v[120:123], v[220:223], v[176:179], v[120:123]
	v_mfma_f32_16x16x32_bf16 v[112:115], v[228:231], v[176:179], v[112:115]
	v_mfma_f32_16x16x32_bf16 v[104:107], v[220:223], v[184:187], v[104:107]
	v_mfma_f32_16x16x32_bf16 v[96:99], v[228:231], v[184:187], v[96:99]
	v_mfma_f32_16x16x32_bf16 v[88:91], v[220:223], v[192:195], v[88:91]
	v_mfma_f32_16x16x32_bf16 v[80:83], v[228:231], v[192:195], v[80:83]
	v_mfma_f32_16x16x32_bf16 v[72:75], v[220:223], v[212:215], v[72:75]
	v_mfma_f32_16x16x32_bf16 v[64:67], v[228:231], v[212:215], v[64:67]
	v_mfma_f32_16x16x32_bf16 v[120:123], v[224:227], v[180:183], v[120:123]
	v_mfma_f32_16x16x32_bf16 v[112:115], v[232:235], v[180:183], v[112:115]
	v_mfma_f32_16x16x32_bf16 v[104:107], v[224:227], v[188:191], v[104:107]
	v_mfma_f32_16x16x32_bf16 v[96:99], v[232:235], v[188:191], v[96:99]
	v_mfma_f32_16x16x32_bf16 v[88:91], v[224:227], v[208:211], v[88:91]
	v_mfma_f32_16x16x32_bf16 v[80:83], v[232:235], v[208:211], v[80:83]
	v_mfma_f32_16x16x32_bf16 v[72:75], v[224:227], v[216:219], v[72:75]
	v_mfma_f32_16x16x32_bf16 v[64:67], v[232:235], v[216:219], v[64:67]
	s_setprio 0
	s_mov_b32 m0, s19
	v_lshl_add_u64 v[238:239], s[24:25], 0, v[134:135]
	s_barrier
	ds_read_b128 v[176:179], v143 offset:16384
	ds_read_b128 v[180:183], v143 offset:17408
	ds_read_b128 v[184:187], v143 offset:18432
	ds_read_b128 v[188:191], v143 offset:19456
	ds_read_b128 v[192:195], v143 offset:20480
	ds_read_b128 v[208:211], v143 offset:21504
	ds_read_b128 v[212:215], v143 offset:22528
	ds_read_b128 v[216:219], v143 offset:23552
	global_load_lds_dwordx4 v[238:239], off
	v_lshl_add_u64 v[240:241], s[24:25], 0, v[132:133]
	s_mov_b32 m0, s30
	s_nop 0
	global_load_lds_dwordx4 v[240:241], off
	s_barrier
	s_waitcnt lgkmcnt(0)
	s_setprio 1
	s_waitcnt lgkmcnt(0)
	v_mfma_f32_16x16x32_bf16 v[60:63], v[144:147], v[176:179], v[60:63]
	v_mfma_f32_16x16x32_bf16 v[52:55], v[152:155], v[176:179], v[52:55]
	v_mfma_f32_16x16x32_bf16 v[44:47], v[144:147], v[184:187], v[44:47]
	v_mfma_f32_16x16x32_bf16 v[36:39], v[152:155], v[184:187], v[36:39]
	v_mfma_f32_16x16x32_bf16 v[28:31], v[144:147], v[192:195], v[28:31]
	v_mfma_f32_16x16x32_bf16 v[20:23], v[152:155], v[192:195], v[20:23]
	v_mfma_f32_16x16x32_bf16 v[12:15], v[144:147], v[212:215], v[12:15]
	v_mfma_f32_16x16x32_bf16 v[4:7], v[152:155], v[212:215], v[4:7]
	v_mfma_f32_16x16x32_bf16 v[60:63], v[148:151], v[180:183], v[60:63]
	v_mfma_f32_16x16x32_bf16 v[52:55], v[156:159], v[180:183], v[52:55]
	v_mfma_f32_16x16x32_bf16 v[44:47], v[148:151], v[188:191], v[44:47]
	v_mfma_f32_16x16x32_bf16 v[36:39], v[156:159], v[188:191], v[36:39]
	v_mfma_f32_16x16x32_bf16 v[28:31], v[148:151], v[208:211], v[28:31]
	v_mfma_f32_16x16x32_bf16 v[20:23], v[156:159], v[208:211], v[20:23]
	v_mfma_f32_16x16x32_bf16 v[12:15], v[148:151], v[216:219], v[12:15]
	v_mfma_f32_16x16x32_bf16 v[4:7], v[156:159], v[216:219], v[4:7]
	s_setprio 0
	s_barrier
	s_add_u32 s44, s22, 0x80000
	s_addc_u32 s45, s23, 0
	s_add_i32 s46, s46, s28
	v_lshl_add_u64 v[144:145], s[44:45], 0, v[128:129]
	s_mov_b32 m0, s46
	s_nop 0
	global_load_lds_dwordx4 v[144:145], off
	v_lshl_add_u64 v[144:145], s[44:45], 0, v[130:131]
	s_add_i32 m0, s46, 0x2000
	s_nop 0
	global_load_lds_dwordx4 v[144:145], off
	s_waitcnt vmcnt(6)
	s_barrier
	s_setprio 1
	v_mfma_f32_16x16x32_bf16 v[56:59], v[220:223], v[176:179], v[56:59]
	v_mfma_f32_16x16x32_bf16 v[48:51], v[228:231], v[176:179], v[48:51]
	v_mfma_f32_16x16x32_bf16 v[40:43], v[220:223], v[184:187], v[40:43]
	v_mfma_f32_16x16x32_bf16 v[32:35], v[228:231], v[184:187], v[32:35]
	v_mfma_f32_16x16x32_bf16 v[24:27], v[220:223], v[192:195], v[24:27]
	v_mfma_f32_16x16x32_bf16 v[16:19], v[228:231], v[192:195], v[16:19]
	v_mfma_f32_16x16x32_bf16 v[8:11], v[220:223], v[212:215], v[8:11]
	v_mfma_f32_16x16x32_bf16 v[0:3], v[228:231], v[212:215], v[0:3]
	v_mfma_f32_16x16x32_bf16 v[56:59], v[224:227], v[180:183], v[56:59]
	v_mfma_f32_16x16x32_bf16 v[48:51], v[232:235], v[180:183], v[48:51]
	v_mfma_f32_16x16x32_bf16 v[40:43], v[224:227], v[188:191], v[40:43]
	v_mfma_f32_16x16x32_bf16 v[32:35], v[232:235], v[188:191], v[32:35]
	v_mfma_f32_16x16x32_bf16 v[24:27], v[224:227], v[208:211], v[24:27]
	v_mfma_f32_16x16x32_bf16 v[16:19], v[232:235], v[208:211], v[16:19]
	v_mfma_f32_16x16x32_bf16 v[8:11], v[224:227], v[216:219], v[8:11]
	v_mfma_f32_16x16x32_bf16 v[0:3], v[232:235], v[216:219], v[0:3]
	s_setprio 0
	s_add_i32 s44, 0, 0x18000
	v_add_u32_e32 v156, s44, v141
	s_barrier
	ds_read_b128 v[144:147], v156
	ds_read_b128 v[148:151], v156 offset:1024
	ds_read_b128 v[152:155], v156 offset:2048
	ds_read_b128 v[156:159], v156 offset:3072
	s_add_u32 s24, s24, 0x80000
	s_addc_u32 s25, s25, 0
	s_mov_b32 m0, s31
	v_lshl_add_u64 v[220:221], s[24:25], 0, v[134:135]
	ds_read_b128 v[176:179], v143 offset:32768
	ds_read_b128 v[180:183], v143 offset:33792
	ds_read_b128 v[184:187], v143 offset:34816
	ds_read_b128 v[188:191], v143 offset:35840
	ds_read_b128 v[192:195], v143 offset:36864
	ds_read_b128 v[208:211], v143 offset:37888
	ds_read_b128 v[212:215], v143 offset:38912
	ds_read_b128 v[216:219], v143 offset:39936
	global_load_lds_dwordx4 v[220:221], off
	v_lshl_add_u64 v[220:221], s[24:25], 0, v[132:133]
	s_mov_b32 m0, s34
	s_nop 0
	global_load_lds_dwordx4 v[220:221], off
	s_waitcnt lgkmcnt(8)
	s_barrier
	s_waitcnt lgkmcnt(0)
	s_setprio 1
	s_waitcnt lgkmcnt(0)
	v_mfma_f32_16x16x32_bf16 v[124:127], v[144:147], v[176:179], v[124:127]
	v_mfma_f32_16x16x32_bf16 v[116:119], v[152:155], v[176:179], v[116:119]
	v_mfma_f32_16x16x32_bf16 v[108:111], v[144:147], v[184:187], v[108:111]
	v_mfma_f32_16x16x32_bf16 v[100:103], v[152:155], v[184:187], v[100:103]
	v_mfma_f32_16x16x32_bf16 v[92:95], v[144:147], v[192:195], v[92:95]
	v_mfma_f32_16x16x32_bf16 v[84:87], v[152:155], v[192:195], v[84:87]
	v_mfma_f32_16x16x32_bf16 v[76:79], v[144:147], v[212:215], v[76:79]
	v_mfma_f32_16x16x32_bf16 v[68:71], v[152:155], v[212:215], v[68:71]
	v_mfma_f32_16x16x32_bf16 v[124:127], v[148:151], v[180:183], v[124:127]
	v_mfma_f32_16x16x32_bf16 v[116:119], v[156:159], v[180:183], v[116:119]
	v_mfma_f32_16x16x32_bf16 v[108:111], v[148:151], v[188:191], v[108:111]
	v_mfma_f32_16x16x32_bf16 v[100:103], v[156:159], v[188:191], v[100:103]
	v_mfma_f32_16x16x32_bf16 v[92:95], v[148:151], v[208:211], v[92:95]
	v_mfma_f32_16x16x32_bf16 v[84:87], v[156:159], v[208:211], v[84:87]
	v_mfma_f32_16x16x32_bf16 v[76:79], v[148:151], v[216:219], v[76:79]
	v_mfma_f32_16x16x32_bf16 v[68:71], v[156:159], v[216:219], v[68:71]
	s_setprio 0
	s_barrier
	s_add_i32 s24, 0, 0x1c000
	s_add_i32 s25, s44, s28
	v_add_u32_e32 v196, s24, v141
	v_lshl_add_u64 v[160:161], v[160:161], 0, s[6:7]
	s_mov_b32 m0, s25
	ds_read_b128 v[220:223], v196
	ds_read_b128 v[224:227], v196 offset:1024
	ds_read_b128 v[228:231], v196 offset:2048
	ds_read_b128 v[232:235], v196 offset:3072
	global_load_lds_dwordx4 v[160:161], off
	v_lshl_add_u64 v[160:161], v[236:237], 0, s[6:7]
	s_add_i32 m0, s25, 0x2000
	s_nop 0
	global_load_lds_dwordx4 v[160:161], off
	s_barrier
	s_waitcnt lgkmcnt(0)
	s_setprio 1
	s_waitcnt lgkmcnt(0)
	v_mfma_f32_16x16x32_bf16 v[120:123], v[220:223], v[176:179], v[120:123]
	v_mfma_f32_16x16x32_bf16 v[112:115], v[228:231], v[176:179], v[112:115]
	v_mfma_f32_16x16x32_bf16 v[104:107], v[220:223], v[184:187], v[104:107]
	v_mfma_f32_16x16x32_bf16 v[96:99], v[228:231], v[184:187], v[96:99]
	v_mfma_f32_16x16x32_bf16 v[88:91], v[220:223], v[192:195], v[88:91]
	v_mfma_f32_16x16x32_bf16 v[80:83], v[228:231], v[192:195], v[80:83]
	v_mfma_f32_16x16x32_bf16 v[72:75], v[220:223], v[212:215], v[72:75]
	v_mfma_f32_16x16x32_bf16 v[64:67], v[228:231], v[212:215], v[64:67]
	v_mfma_f32_16x16x32_bf16 v[120:123], v[224:227], v[180:183], v[120:123]
	v_mfma_f32_16x16x32_bf16 v[112:115], v[232:235], v[180:183], v[112:115]
	v_mfma_f32_16x16x32_bf16 v[104:107], v[224:227], v[188:191], v[104:107]
	v_mfma_f32_16x16x32_bf16 v[96:99], v[232:235], v[188:191], v[96:99]
	v_mfma_f32_16x16x32_bf16 v[88:91], v[224:227], v[208:211], v[88:91]
	v_mfma_f32_16x16x32_bf16 v[80:83], v[232:235], v[208:211], v[80:83]
	v_mfma_f32_16x16x32_bf16 v[72:75], v[224:227], v[216:219], v[72:75]
	v_mfma_f32_16x16x32_bf16 v[64:67], v[232:235], v[216:219], v[64:67]
	s_setprio 0
	s_mov_b32 m0, s35
	v_lshl_add_u64 v[160:161], v[238:239], 0, s[6:7]
	s_barrier
	ds_read_b128 v[176:179], v143 offset:49152
	ds_read_b128 v[180:183], v143 offset:50176
	ds_read_b128 v[184:187], v143 offset:51200
	ds_read_b128 v[188:191], v143 offset:52224
	ds_read_b128 v[192:195], v143 offset:53248
	ds_read_b128 v[208:211], v143 offset:54272
	ds_read_b128 v[212:215], v143 offset:55296
	ds_read_b128 v[216:219], v143 offset:56320
	global_load_lds_dwordx4 v[160:161], off
	v_lshl_add_u64 v[160:161], v[240:241], 0, s[6:7]
	s_mov_b32 m0, s36
	s_nop 0
	global_load_lds_dwordx4 v[160:161], off
	s_barrier
	s_waitcnt lgkmcnt(0)
	s_setprio 1
	s_waitcnt lgkmcnt(0)
	v_mfma_f32_16x16x32_bf16 v[60:63], v[144:147], v[176:179], v[60:63]
	v_mfma_f32_16x16x32_bf16 v[52:55], v[152:155], v[176:179], v[52:55]
	v_mfma_f32_16x16x32_bf16 v[44:47], v[144:147], v[184:187], v[44:47]
	v_mfma_f32_16x16x32_bf16 v[36:39], v[152:155], v[184:187], v[36:39]
	v_mfma_f32_16x16x32_bf16 v[28:31], v[144:147], v[192:195], v[28:31]
	v_mfma_f32_16x16x32_bf16 v[20:23], v[152:155], v[192:195], v[20:23]
	v_mfma_f32_16x16x32_bf16 v[12:15], v[144:147], v[212:215], v[12:15]
	v_mfma_f32_16x16x32_bf16 v[4:7], v[152:155], v[212:215], v[4:7]
	v_mfma_f32_16x16x32_bf16 v[60:63], v[148:151], v[180:183], v[60:63]
	v_mfma_f32_16x16x32_bf16 v[52:55], v[156:159], v[180:183], v[52:55]
	v_mfma_f32_16x16x32_bf16 v[44:47], v[148:151], v[188:191], v[44:47]
	v_mfma_f32_16x16x32_bf16 v[36:39], v[156:159], v[188:191], v[36:39]
	v_mfma_f32_16x16x32_bf16 v[28:31], v[148:151], v[208:211], v[28:31]
	v_mfma_f32_16x16x32_bf16 v[20:23], v[156:159], v[208:211], v[20:23]
	v_mfma_f32_16x16x32_bf16 v[12:15], v[148:151], v[216:219], v[12:15]
	v_mfma_f32_16x16x32_bf16 v[4:7], v[156:159], v[216:219], v[4:7]
	s_setprio 0
	s_barrier
	s_add_u32 s22, s22, 0x80080
	s_addc_u32 s23, s23, 0
	s_add_i32 s24, s24, s28
	v_lshl_add_u64 v[144:145], s[22:23], 0, v[128:129]
	s_mov_b32 m0, s24
	s_nop 0
	global_load_lds_dwordx4 v[144:145], off
	v_lshl_add_u64 v[144:145], s[22:23], 0, v[130:131]
	s_add_i32 m0, s24, 0x2000
	s_nop 0
	global_load_lds_dwordx4 v[144:145], off
	s_waitcnt vmcnt(6)
	s_barrier
	s_setprio 1
	v_mfma_f32_16x16x32_bf16 v[56:59], v[220:223], v[176:179], v[56:59]
	v_mfma_f32_16x16x32_bf16 v[48:51], v[228:231], v[176:179], v[48:51]
	v_mfma_f32_16x16x32_bf16 v[40:43], v[220:223], v[184:187], v[40:43]
	v_mfma_f32_16x16x32_bf16 v[32:35], v[228:231], v[184:187], v[32:35]
	v_mfma_f32_16x16x32_bf16 v[24:27], v[220:223], v[192:195], v[24:27]
	v_mfma_f32_16x16x32_bf16 v[16:19], v[228:231], v[192:195], v[16:19]
	v_mfma_f32_16x16x32_bf16 v[8:11], v[220:223], v[212:215], v[8:11]
	v_mfma_f32_16x16x32_bf16 v[0:3], v[228:231], v[212:215], v[0:3]
	v_mfma_f32_16x16x32_bf16 v[56:59], v[224:227], v[180:183], v[56:59]
	v_mfma_f32_16x16x32_bf16 v[48:51], v[232:235], v[180:183], v[48:51]
	v_mfma_f32_16x16x32_bf16 v[40:43], v[224:227], v[188:191], v[40:43]
	v_mfma_f32_16x16x32_bf16 v[32:35], v[232:235], v[188:191], v[32:35]
	v_mfma_f32_16x16x32_bf16 v[24:27], v[224:227], v[208:211], v[24:27]
	v_mfma_f32_16x16x32_bf16 v[16:19], v[232:235], v[208:211], v[16:19]
	v_mfma_f32_16x16x32_bf16 v[8:11], v[224:227], v[216:219], v[8:11]
	v_mfma_f32_16x16x32_bf16 v[0:3], v[232:235], v[216:219], v[0:3]
	s_setprio 0
	s_add_i32 s43, s43, 2
	s_add_u32 s20, s20, 0x100
	s_addc_u32 s21, s21, 0
	s_add_u32 s41, s41, 0x100
	s_addc_u32 s42, s42, 0
	s_cmp_gt_u32 s43, 29
	s_barrier
	s_cbranch_scc0 .LBB0_143
	v_mul_f32_e32 v145, 0xbfb8aa3b, v124
	v_exp_f32_e32 v145, v145
	v_lshl_or_b32 v146, s38, 7, v142
	v_lshl_add_u32 v144, s18, 8, v140
	v_ashrrev_i32_e32 v147, 31, v146
	v_add_f32_e32 v145, 1.0, v145
	v_rcp_f32_e32 v145, v145
	s_and_b64 vcc, exec, s[8:9]
	s_mov_b32 s38, s10
	s_mov_b32 s18, s12
	v_mul_f32_e32 v124, v124, v145
	v_mul_f32_e32 v120, v124, v120
	v_mul_f32_e32 v124, 0xbfb8aa3b, v125
	v_exp_f32_e32 v124, v124
	s_mov_b64 s[22:23], s[16:17]
	v_add_f32_e32 v124, 1.0, v124
	v_rcp_f32_e32 v124, v124
	s_nop 0
	v_mul_f32_e32 v124, v125, v124
	v_mul_f32_e32 v121, v124, v121
	v_mul_f32_e32 v124, 0xbfb8aa3b, v126
	v_exp_f32_e32 v124, v124
	s_nop 0
	v_add_f32_e32 v124, 1.0, v124
	v_rcp_f32_e32 v124, v124
	s_nop 0
	v_mul_f32_e32 v124, v126, v124
	v_mul_f32_e32 v122, v124, v122
	v_mul_f32_e32 v124, 0xbfb8aa3b, v127
	v_exp_f32_e32 v124, v124
	s_nop 0
	v_add_f32_e32 v124, 1.0, v124
	v_rcp_f32_e32 v124, v124
	s_nop 0
	v_mul_f32_e32 v124, v127, v124
	v_mul_f32_e32 v123, v124, v123
	v_mul_f32_e32 v124, 0xbfb8aa3b, v116
	v_exp_f32_e32 v124, v124
	s_nop 0
	v_add_f32_e32 v124, 1.0, v124
	v_rcp_f32_e32 v124, v124
	s_nop 0
	v_mul_f32_e32 v116, v116, v124
	v_mul_f32_e32 v112, v116, v112
	v_mul_f32_e32 v116, 0xbfb8aa3b, v117
	v_exp_f32_e32 v116, v116
	s_nop 0
	v_add_f32_e32 v116, 1.0, v116
	v_rcp_f32_e32 v116, v116
	s_nop 0
	v_mul_f32_e32 v116, v117, v116
	v_mul_f32_e32 v113, v116, v113
	v_mul_f32_e32 v116, 0xbfb8aa3b, v118
	v_exp_f32_e32 v116, v116
	v_cvt_pk_bf16_f32 v117, v122, v123
	s_nop 0
	v_add_f32_e32 v116, 1.0, v116
	v_rcp_f32_e32 v116, v116
	s_nop 0
	v_mul_f32_e32 v116, v118, v116
	v_mul_f32_e32 v114, v116, v114
	v_mul_f32_e32 v116, 0xbfb8aa3b, v119
	v_exp_f32_e32 v116, v116
	v_cvt_pk_bf16_f32 v118, v112, v113
	v_mov_b64_e32 v[112:113], s[48:49]
	v_add_f32_e32 v116, 1.0, v116
	v_rcp_f32_e32 v116, v116
	s_nop 0
	v_mul_f32_e32 v116, v119, v116
	v_mul_f32_e32 v115, v116, v115
	v_cvt_pk_bf16_f32 v116, v120, v121
	v_cvt_pk_bf16_f32 v119, v114, v115
	v_mad_i64_i32 v[120:121], s[20:21], v144, s3, v[112:113]
	v_lshlrev_b64 v[114:115], 1, v[146:147]
	v_lshl_add_u64 v[120:121], v[120:121], 0, v[114:115]
	global_store_dwordx4 v[120:121], v[116:119], off nt
	s_nop 1
	v_mul_f32_e32 v116, 0xbfb8aa3b, v108
	v_exp_f32_e32 v116, v116
	s_nop 0
	v_add_f32_e32 v116, 1.0, v116
	v_rcp_f32_e32 v116, v116
	s_nop 0
	v_mul_f32_e32 v108, v108, v116
	v_mul_f32_e32 v104, v108, v104
	v_mul_f32_e32 v108, 0xbfb8aa3b, v109
	v_exp_f32_e32 v108, v108
	s_nop 0
	v_add_f32_e32 v108, 1.0, v108
	v_rcp_f32_e32 v108, v108
	s_nop 0
	v_mul_f32_e32 v108, v109, v108
	v_mul_f32_e32 v105, v108, v105
	v_mul_f32_e32 v108, 0xbfb8aa3b, v110
	v_exp_f32_e32 v108, v108
	s_nop 0
	v_add_f32_e32 v108, 1.0, v108
	v_rcp_f32_e32 v108, v108
	s_nop 0
	v_mul_f32_e32 v108, v110, v108
	v_mul_f32_e32 v106, v108, v106
	v_mul_f32_e32 v108, 0xbfb8aa3b, v111
	v_exp_f32_e32 v108, v108
	s_nop 0
	v_add_f32_e32 v108, 1.0, v108
	v_rcp_f32_e32 v108, v108
	s_nop 0
	v_mul_f32_e32 v108, v111, v108
	v_mul_f32_e32 v107, v108, v107
	v_mul_f32_e32 v108, 0xbfb8aa3b, v100
	v_exp_f32_e32 v108, v108
	s_nop 0
	v_add_f32_e32 v108, 1.0, v108
	v_rcp_f32_e32 v108, v108
	s_nop 0
	v_mul_f32_e32 v100, v100, v108
	v_mul_f32_e32 v100, v100, v96
	v_mul_f32_e32 v96, 0xbfb8aa3b, v101
	v_exp_f32_e32 v96, v96
	s_nop 0
	v_add_f32_e32 v96, 1.0, v96
	v_rcp_f32_e32 v96, v96
	s_nop 0
	v_mul_f32_e32 v96, v101, v96
	v_mul_f32_e32 v101, v96, v97
	v_mul_f32_e32 v96, 0xbfb8aa3b, v102
	v_exp_f32_e32 v96, v96
	v_cvt_pk_bf16_f32 v97, v106, v107
	s_nop 0
	v_add_f32_e32 v96, 1.0, v96
	v_rcp_f32_e32 v96, v96
	s_nop 0
	v_mul_f32_e32 v96, v102, v96
	v_mul_f32_e32 v102, v96, v98
	v_mul_f32_e32 v96, 0xbfb8aa3b, v103
	v_exp_f32_e32 v96, v96
	v_cvt_pk_bf16_f32 v98, v100, v101
	v_or_b32_e32 v100, 16, v144
	v_mad_i64_i32 v[100:101], s[20:21], v100, s3, v[112:113]
	v_add_f32_e32 v96, 1.0, v96
	v_rcp_f32_e32 v96, v96
	v_lshl_add_u64 v[100:101], v[100:101], 0, v[114:115]
	v_mul_f32_e32 v96, v103, v96
	v_mul_f32_e32 v99, v96, v99
	v_cvt_pk_bf16_f32 v96, v104, v105
	v_cvt_pk_bf16_f32 v99, v102, v99
	global_store_dwordx4 v[100:101], v[96:99], off nt
	s_nop 1
	v_mul_f32_e32 v96, 0xbfb8aa3b, v92
	v_exp_f32_e32 v96, v96
	s_nop 0
	v_add_f32_e32 v96, 1.0, v96
	v_rcp_f32_e32 v96, v96
	s_nop 0
	v_mul_f32_e32 v92, v92, v96
	v_mul_f32_e32 v88, v92, v88
	v_mul_f32_e32 v92, 0xbfb8aa3b, v93
	v_exp_f32_e32 v92, v92
	s_nop 0
	v_add_f32_e32 v92, 1.0, v92
	v_rcp_f32_e32 v92, v92
	s_nop 0
	v_mul_f32_e32 v92, v93, v92
	v_mul_f32_e32 v89, v92, v89
	v_mul_f32_e32 v92, 0xbfb8aa3b, v94
	v_exp_f32_e32 v92, v92
	s_nop 0
	v_add_f32_e32 v92, 1.0, v92
	v_rcp_f32_e32 v92, v92
	s_nop 0
	v_mul_f32_e32 v92, v94, v92
	v_mul_f32_e32 v90, v92, v90
	v_mul_f32_e32 v92, 0xbfb8aa3b, v95
	v_exp_f32_e32 v92, v92
	s_nop 0
	v_add_f32_e32 v92, 1.0, v92
	v_rcp_f32_e32 v92, v92
	s_nop 0
	v_mul_f32_e32 v92, v95, v92
	v_mul_f32_e32 v91, v92, v91
	v_mul_f32_e32 v92, 0xbfb8aa3b, v84
	v_exp_f32_e32 v92, v92
	s_nop 0
	v_add_f32_e32 v92, 1.0, v92
	v_rcp_f32_e32 v92, v92
	s_nop 0
	v_mul_f32_e32 v84, v84, v92
	v_mul_f32_e32 v84, v84, v80
	v_mul_f32_e32 v80, 0xbfb8aa3b, v85
	v_exp_f32_e32 v80, v80
	s_nop 0
	v_add_f32_e32 v80, 1.0, v80
	v_rcp_f32_e32 v80, v80
	s_nop 0
	v_mul_f32_e32 v80, v85, v80
	v_mul_f32_e32 v85, v80, v81
	v_mul_f32_e32 v80, 0xbfb8aa3b, v86
	v_exp_f32_e32 v80, v80
	v_cvt_pk_bf16_f32 v81, v90, v91
	s_nop 0
	v_add_f32_e32 v80, 1.0, v80
	v_rcp_f32_e32 v80, v80
	s_nop 0
	v_mul_f32_e32 v80, v86, v80
	v_mul_f32_e32 v86, v80, v82
	v_mul_f32_e32 v80, 0xbfb8aa3b, v87
	v_exp_f32_e32 v80, v80
	v_cvt_pk_bf16_f32 v82, v84, v85
	v_or_b32_e32 v84, 32, v144
	v_mad_i64_i32 v[84:85], s[20:21], v84, s3, v[112:113]
	v_add_f32_e32 v80, 1.0, v80
	v_rcp_f32_e32 v80, v80
	v_lshl_add_u64 v[84:85], v[84:85], 0, v[114:115]
	v_mul_f32_e32 v80, v87, v80
	v_mul_f32_e32 v83, v80, v83
	v_cvt_pk_bf16_f32 v80, v88, v89
	v_cvt_pk_bf16_f32 v83, v86, v83
	global_store_dwordx4 v[84:85], v[80:83], off nt
	s_nop 1
	v_mul_f32_e32 v80, 0xbfb8aa3b, v76
	v_exp_f32_e32 v80, v80
	s_nop 0
	v_add_f32_e32 v80, 1.0, v80
	v_rcp_f32_e32 v80, v80
	s_nop 0
	v_mul_f32_e32 v76, v76, v80
	v_mul_f32_e32 v72, v76, v72
	v_mul_f32_e32 v76, 0xbfb8aa3b, v77
	v_exp_f32_e32 v76, v76
	s_nop 0
	v_add_f32_e32 v76, 1.0, v76
	v_rcp_f32_e32 v76, v76
	s_nop 0
	v_mul_f32_e32 v76, v77, v76
	v_mul_f32_e32 v73, v76, v73
	v_mul_f32_e32 v76, 0xbfb8aa3b, v78
	v_exp_f32_e32 v76, v76
	s_nop 0
	v_add_f32_e32 v76, 1.0, v76
	v_rcp_f32_e32 v76, v76
	s_nop 0
	v_mul_f32_e32 v76, v78, v76
	v_mul_f32_e32 v74, v76, v74
	v_mul_f32_e32 v76, 0xbfb8aa3b, v79
	v_exp_f32_e32 v76, v76
	s_nop 0
	v_add_f32_e32 v76, 1.0, v76
	v_rcp_f32_e32 v76, v76
	s_nop 0
	v_mul_f32_e32 v76, v79, v76
	v_mul_f32_e32 v75, v76, v75
	v_mul_f32_e32 v76, 0xbfb8aa3b, v68
	v_exp_f32_e32 v76, v76
	s_nop 0
	v_add_f32_e32 v76, 1.0, v76
	v_rcp_f32_e32 v76, v76
	s_nop 0
	v_mul_f32_e32 v68, v68, v76
	v_mul_f32_e32 v68, v68, v64
	v_mul_f32_e32 v64, 0xbfb8aa3b, v69
	v_exp_f32_e32 v64, v64
	s_nop 0
	v_add_f32_e32 v64, 1.0, v64
	v_rcp_f32_e32 v64, v64
	s_nop 0
	v_mul_f32_e32 v64, v69, v64
	v_mul_f32_e32 v69, v64, v65
	v_mul_f32_e32 v64, 0xbfb8aa3b, v70
	v_exp_f32_e32 v64, v64
	v_cvt_pk_bf16_f32 v65, v74, v75
	s_nop 0
	v_add_f32_e32 v64, 1.0, v64
	v_rcp_f32_e32 v64, v64
	s_nop 0
	v_mul_f32_e32 v64, v70, v64
	v_mul_f32_e32 v70, v64, v66
	v_mul_f32_e32 v64, 0xbfb8aa3b, v71
	v_exp_f32_e32 v64, v64
	v_cvt_pk_bf16_f32 v66, v68, v69
	v_or_b32_e32 v68, 48, v144
	v_mad_i64_i32 v[68:69], s[20:21], v68, s3, v[112:113]
	v_add_f32_e32 v64, 1.0, v64
	v_rcp_f32_e32 v64, v64
	v_lshl_add_u64 v[68:69], v[68:69], 0, v[114:115]
	v_mul_f32_e32 v64, v71, v64
	v_mul_f32_e32 v67, v64, v67
	v_cvt_pk_bf16_f32 v64, v72, v73
	v_cvt_pk_bf16_f32 v67, v70, v67
	global_store_dwordx4 v[68:69], v[64:67], off nt
	s_nop 1
	v_mul_f32_e32 v65, 0xbfb8aa3b, v60
	v_exp_f32_e32 v65, v65
	v_add_u32_e32 v64, 0x80, v144
	v_add_f32_e32 v65, 1.0, v65
	v_rcp_f32_e32 v65, v65
	s_nop 0
	v_mul_f32_e32 v60, v60, v65
	v_mul_f32_e32 v56, v60, v56
	v_mul_f32_e32 v60, 0xbfb8aa3b, v61
	v_exp_f32_e32 v60, v60
	s_nop 0
	v_add_f32_e32 v60, 1.0, v60
	v_rcp_f32_e32 v60, v60
	s_nop 0
	v_mul_f32_e32 v60, v61, v60
	v_mul_f32_e32 v57, v60, v57
	v_mul_f32_e32 v60, 0xbfb8aa3b, v62
	v_exp_f32_e32 v60, v60
	s_nop 0
	v_add_f32_e32 v60, 1.0, v60
	v_rcp_f32_e32 v60, v60
	s_nop 0
	v_mul_f32_e32 v60, v62, v60
	v_mul_f32_e32 v58, v60, v58
	v_mul_f32_e32 v60, 0xbfb8aa3b, v63
	v_exp_f32_e32 v60, v60
	s_nop 0
	v_add_f32_e32 v60, 1.0, v60
	v_rcp_f32_e32 v60, v60
	s_nop 0
	v_mul_f32_e32 v60, v63, v60
	v_mul_f32_e32 v59, v60, v59
	v_mul_f32_e32 v60, 0xbfb8aa3b, v52
	v_exp_f32_e32 v60, v60
	s_nop 0
	v_add_f32_e32 v60, 1.0, v60
	v_rcp_f32_e32 v60, v60
	s_nop 0
	v_mul_f32_e32 v52, v52, v60
	v_mul_f32_e32 v52, v52, v48
	v_mul_f32_e32 v48, 0xbfb8aa3b, v53
	v_exp_f32_e32 v48, v48
	s_nop 0
	v_add_f32_e32 v48, 1.0, v48
	v_rcp_f32_e32 v48, v48
	s_nop 0
	v_mul_f32_e32 v48, v53, v48
	v_mul_f32_e32 v53, v48, v49
	v_mul_f32_e32 v48, 0xbfb8aa3b, v54
	v_exp_f32_e32 v48, v48
	v_cvt_pk_bf16_f32 v49, v58, v59
	s_nop 0
	v_add_f32_e32 v48, 1.0, v48
	v_rcp_f32_e32 v48, v48
	s_nop 0
	v_mul_f32_e32 v48, v54, v48
	v_mul_f32_e32 v54, v48, v50
	v_mul_f32_e32 v48, 0xbfb8aa3b, v55
	v_exp_f32_e32 v48, v48
	v_cvt_pk_bf16_f32 v50, v52, v53
	v_mad_i64_i32 v[52:53], s[20:21], v64, s3, v[112:113]
	v_add_f32_e32 v48, 1.0, v48
	v_rcp_f32_e32 v48, v48
	v_lshl_add_u64 v[52:53], v[52:53], 0, v[114:115]
	v_mul_f32_e32 v48, v55, v48
	v_mul_f32_e32 v51, v48, v51
	v_cvt_pk_bf16_f32 v48, v56, v57
	v_cvt_pk_bf16_f32 v51, v54, v51
	global_store_dwordx4 v[52:53], v[48:51], off nt
	s_nop 1
	v_mul_f32_e32 v48, 0xbfb8aa3b, v44
	v_exp_f32_e32 v48, v48
	s_nop 0
	v_add_f32_e32 v48, 1.0, v48
	v_rcp_f32_e32 v48, v48
	s_nop 0
	v_mul_f32_e32 v44, v44, v48
	v_mul_f32_e32 v40, v44, v40
	v_mul_f32_e32 v44, 0xbfb8aa3b, v45
	v_exp_f32_e32 v44, v44
	s_nop 0
	v_add_f32_e32 v44, 1.0, v44
	v_rcp_f32_e32 v44, v44
	s_nop 0
	v_mul_f32_e32 v44, v45, v44
	v_mul_f32_e32 v41, v44, v41
	v_mul_f32_e32 v44, 0xbfb8aa3b, v46
	v_exp_f32_e32 v44, v44
	s_nop 0
	v_add_f32_e32 v44, 1.0, v44
	v_rcp_f32_e32 v44, v44
	s_nop 0
	v_mul_f32_e32 v44, v46, v44
	v_mul_f32_e32 v42, v44, v42
	v_mul_f32_e32 v44, 0xbfb8aa3b, v47
	v_exp_f32_e32 v44, v44
	s_nop 0
	v_add_f32_e32 v44, 1.0, v44
	v_rcp_f32_e32 v44, v44
	s_nop 0
	v_mul_f32_e32 v44, v47, v44
	v_mul_f32_e32 v43, v44, v43
	v_mul_f32_e32 v44, 0xbfb8aa3b, v36
	v_exp_f32_e32 v44, v44
	s_nop 0
	v_add_f32_e32 v44, 1.0, v44
	v_rcp_f32_e32 v44, v44
	s_nop 0
	v_mul_f32_e32 v36, v36, v44
	v_mul_f32_e32 v36, v36, v32
	v_mul_f32_e32 v32, 0xbfb8aa3b, v37
	v_exp_f32_e32 v32, v32
	s_nop 0
	v_add_f32_e32 v32, 1.0, v32
	v_rcp_f32_e32 v32, v32
	s_nop 0
	v_mul_f32_e32 v32, v37, v32
	v_mul_f32_e32 v37, v32, v33
	v_mul_f32_e32 v32, 0xbfb8aa3b, v38
	v_exp_f32_e32 v32, v32
	v_cvt_pk_bf16_f32 v33, v42, v43
	s_nop 0
	v_add_f32_e32 v32, 1.0, v32
	v_rcp_f32_e32 v32, v32
	s_nop 0
	v_mul_f32_e32 v32, v38, v32
	v_mul_f32_e32 v38, v32, v34
	v_mul_f32_e32 v32, 0xbfb8aa3b, v39
	v_exp_f32_e32 v32, v32
	v_cvt_pk_bf16_f32 v34, v36, v37
	v_add_u32_e32 v36, 0x90, v144
	v_mad_i64_i32 v[36:37], s[20:21], v36, s3, v[112:113]
	v_add_f32_e32 v32, 1.0, v32
	v_rcp_f32_e32 v32, v32
	v_lshl_add_u64 v[36:37], v[36:37], 0, v[114:115]
	v_mul_f32_e32 v32, v39, v32
	v_mul_f32_e32 v35, v32, v35
	v_cvt_pk_bf16_f32 v32, v40, v41
	v_cvt_pk_bf16_f32 v35, v38, v35
	global_store_dwordx4 v[36:37], v[32:35], off nt
	s_nop 1
	v_mul_f32_e32 v32, 0xbfb8aa3b, v28
	v_exp_f32_e32 v32, v32
	s_nop 0
	v_add_f32_e32 v32, 1.0, v32
	v_rcp_f32_e32 v32, v32
	s_nop 0
	v_mul_f32_e32 v28, v28, v32
	v_mul_f32_e32 v24, v28, v24
	v_mul_f32_e32 v28, 0xbfb8aa3b, v29
	v_exp_f32_e32 v28, v28
	s_nop 0
	v_add_f32_e32 v28, 1.0, v28
	v_rcp_f32_e32 v28, v28
	s_nop 0
	v_mul_f32_e32 v28, v29, v28
	v_mul_f32_e32 v25, v28, v25
	v_mul_f32_e32 v28, 0xbfb8aa3b, v30
	v_exp_f32_e32 v28, v28
	s_nop 0
	v_add_f32_e32 v28, 1.0, v28
	v_rcp_f32_e32 v28, v28
	s_nop 0
	v_mul_f32_e32 v28, v30, v28
	v_mul_f32_e32 v26, v28, v26
	v_mul_f32_e32 v28, 0xbfb8aa3b, v31
	v_exp_f32_e32 v28, v28
	s_nop 0
	v_add_f32_e32 v28, 1.0, v28
	v_rcp_f32_e32 v28, v28
	s_nop 0
	v_mul_f32_e32 v28, v31, v28
	v_mul_f32_e32 v27, v28, v27
	v_mul_f32_e32 v28, 0xbfb8aa3b, v20
	v_exp_f32_e32 v28, v28
	s_nop 0
	v_add_f32_e32 v28, 1.0, v28
	v_rcp_f32_e32 v28, v28
	s_nop 0
	v_mul_f32_e32 v20, v20, v28
	v_mul_f32_e32 v20, v20, v16
	v_mul_f32_e32 v16, 0xbfb8aa3b, v21
	v_exp_f32_e32 v16, v16
	s_nop 0
	v_add_f32_e32 v16, 1.0, v16
	v_rcp_f32_e32 v16, v16
	s_nop 0
	v_mul_f32_e32 v16, v21, v16
	v_mul_f32_e32 v21, v16, v17
	v_mul_f32_e32 v16, 0xbfb8aa3b, v22
	v_exp_f32_e32 v16, v16
	v_cvt_pk_bf16_f32 v17, v26, v27
	s_nop 0
	v_add_f32_e32 v16, 1.0, v16
	v_rcp_f32_e32 v16, v16
	s_nop 0
	v_mul_f32_e32 v16, v22, v16
	v_mul_f32_e32 v22, v16, v18
	v_mul_f32_e32 v16, 0xbfb8aa3b, v23
	v_exp_f32_e32 v16, v16
	v_cvt_pk_bf16_f32 v18, v20, v21
	v_add_u32_e32 v20, 0xa0, v144
	v_mad_i64_i32 v[20:21], s[20:21], v20, s3, v[112:113]
	v_add_f32_e32 v16, 1.0, v16
	v_rcp_f32_e32 v16, v16
	v_lshl_add_u64 v[20:21], v[20:21], 0, v[114:115]
	v_mul_f32_e32 v16, v23, v16
	v_mul_f32_e32 v19, v16, v19
	v_cvt_pk_bf16_f32 v16, v24, v25
	v_cvt_pk_bf16_f32 v19, v22, v19
	global_store_dwordx4 v[20:21], v[16:19], off nt
	s_nop 1
	v_mul_f32_e32 v16, 0xbfb8aa3b, v12
	v_exp_f32_e32 v16, v16
	s_nop 0
	v_add_f32_e32 v16, 1.0, v16
	v_rcp_f32_e32 v16, v16
	s_nop 0
	v_mul_f32_e32 v12, v12, v16
	v_mul_f32_e32 v8, v12, v8
	v_mul_f32_e32 v12, 0xbfb8aa3b, v13
	v_exp_f32_e32 v12, v12
	s_nop 0
	v_add_f32_e32 v12, 1.0, v12
	v_rcp_f32_e32 v12, v12
	s_nop 0
	v_mul_f32_e32 v12, v13, v12
	v_mul_f32_e32 v9, v12, v9
	v_mul_f32_e32 v12, 0xbfb8aa3b, v14
	v_exp_f32_e32 v12, v12
	s_nop 0
	v_add_f32_e32 v12, 1.0, v12
	v_rcp_f32_e32 v12, v12
	s_nop 0
	v_mul_f32_e32 v12, v14, v12
	v_mul_f32_e32 v10, v12, v10
	v_mul_f32_e32 v12, 0xbfb8aa3b, v15
	v_exp_f32_e32 v12, v12
	s_nop 0
	v_add_f32_e32 v12, 1.0, v12
	v_rcp_f32_e32 v12, v12
	s_nop 0
	v_mul_f32_e32 v12, v15, v12
	v_mul_f32_e32 v11, v12, v11
	v_mul_f32_e32 v12, 0xbfb8aa3b, v4
	v_exp_f32_e32 v12, v12
	s_nop 0
	v_add_f32_e32 v12, 1.0, v12
	v_rcp_f32_e32 v12, v12
	s_nop 0
	v_mul_f32_e32 v4, v4, v12
	v_mul_f32_e32 v4, v4, v0
	v_mul_f32_e32 v0, 0xbfb8aa3b, v5
	v_exp_f32_e32 v0, v0
	s_nop 0
	v_add_f32_e32 v0, 1.0, v0
	v_rcp_f32_e32 v0, v0
	s_nop 0
	v_mul_f32_e32 v0, v5, v0
	v_mul_f32_e32 v5, v0, v1
	v_mul_f32_e32 v0, 0xbfb8aa3b, v6
	v_exp_f32_e32 v0, v0
	v_cvt_pk_bf16_f32 v1, v10, v11
	s_nop 0
	v_add_f32_e32 v0, 1.0, v0
	v_rcp_f32_e32 v0, v0
	s_nop 0
	v_mul_f32_e32 v0, v6, v0
	v_mul_f32_e32 v6, v0, v2
	v_mul_f32_e32 v0, 0xbfb8aa3b, v7
	v_exp_f32_e32 v0, v0
	v_cvt_pk_bf16_f32 v2, v4, v5
	v_add_u32_e32 v4, 0xb0, v144
	v_mad_i64_i32 v[4:5], s[20:21], v4, s3, v[112:113]
	v_add_f32_e32 v0, 1.0, v0
	v_rcp_f32_e32 v0, v0
	v_lshl_add_u64 v[4:5], v[4:5], 0, v[114:115]
	s_mov_b64 s[20:21], s[14:15]
	v_mul_f32_e32 v0, v7, v0
	v_mul_f32_e32 v3, v0, v3
	v_cvt_pk_bf16_f32 v0, v8, v9
	v_cvt_pk_bf16_f32 v3, v6, v3
	global_store_dwordx4 v[4:5], v[0:3], off nt
	s_cbranch_vccz .LBB0_140
	s_waitcnt vmcnt(0)
	s_cmpk_gt_u32 s1, 0xff
	s_cbranch_scc1 .LBB0_147
	s_barrier

.LBB0_167:
	s_add_u32 s22, s20, 0x100
	s_addc_u32 s23, s21, 0
	s_add_i32 s46, 0, 0x10000
	v_add_u32_e32 v140, s46, v143
	ds_read_b128 v[136:139], v140
	ds_read_b128 v[146:149], v140 offset:1024
	ds_read_b128 v[150:153], v140 offset:2048
	ds_read_b128 v[154:157], v140 offset:3072
	s_cmp_eq_u32 s45, 28
	s_cselect_b32 s27, s13, s23
	s_cselect_b32 s26, s41, s22
	s_cselect_b32 s25, s11, s44
	s_cselect_b32 s24, s42, s43
	v_lshl_add_u64 v[140:141], s[20:21], 0, v[132:133]
	s_add_i32 m0, s19, 0xc000
	ds_read_b128 v[158:161], v145
	ds_read_b128 v[176:179], v145 offset:1024
	ds_read_b128 v[180:183], v145 offset:2048
	ds_read_b128 v[184:187], v145 offset:3072
	ds_read_b128 v[188:191], v145 offset:4096
	ds_read_b128 v[192:195], v145 offset:5120
	ds_read_b128 v[208:211], v145 offset:6144
	ds_read_b128 v[212:215], v145 offset:7168
	global_load_lds_dwordx4 v[140:141], off
	v_lshl_add_u64 v[140:141], s[20:21], 0, v[134:135]
	s_add_i32 m0, s19, 0xe000
	s_nop 0
	global_load_lds_dwordx4 v[140:141], off
	s_waitcnt lgkmcnt(8)
	s_barrier
	s_waitcnt lgkmcnt(0)
	s_setprio 1
	s_waitcnt lgkmcnt(0)
	v_mfma_f32_16x16x32_bf16 v[124:127], v[136:139], v[158:161], v[124:127]
	v_mfma_f32_16x16x32_bf16 v[120:123], v[150:153], v[158:161], v[120:123]
	v_mfma_f32_16x16x32_bf16 v[108:111], v[136:139], v[180:183], v[108:111]
	v_mfma_f32_16x16x32_bf16 v[104:107], v[150:153], v[180:183], v[104:107]
	v_mfma_f32_16x16x32_bf16 v[92:95], v[136:139], v[188:191], v[92:95]
	v_mfma_f32_16x16x32_bf16 v[88:91], v[150:153], v[188:191], v[88:91]
	v_mfma_f32_16x16x32_bf16 v[76:79], v[136:139], v[208:211], v[76:79]
	v_mfma_f32_16x16x32_bf16 v[72:75], v[150:153], v[208:211], v[72:75]
	v_mfma_f32_16x16x32_bf16 v[124:127], v[146:149], v[176:179], v[124:127]
	v_mfma_f32_16x16x32_bf16 v[120:123], v[154:157], v[176:179], v[120:123]
	v_mfma_f32_16x16x32_bf16 v[108:111], v[146:149], v[184:187], v[108:111]
	v_mfma_f32_16x16x32_bf16 v[104:107], v[154:157], v[184:187], v[104:107]
	v_mfma_f32_16x16x32_bf16 v[92:95], v[146:149], v[192:195], v[92:95]
	v_mfma_f32_16x16x32_bf16 v[88:91], v[154:157], v[192:195], v[88:91]
	v_mfma_f32_16x16x32_bf16 v[76:79], v[146:149], v[212:215], v[76:79]
	v_mfma_f32_16x16x32_bf16 v[72:75], v[154:157], v[212:215], v[72:75]
	s_setprio 0
	s_barrier
	s_add_i32 s47, 0, 0x14000
	v_add_u32_e32 v140, s47, v143
	s_add_i32 s20, s46, s31
	ds_read_b128 v[216:219], v140
	ds_read_b128 v[220:223], v140 offset:1024
	ds_read_b128 v[224:227], v140 offset:2048
	ds_read_b128 v[228:231], v140 offset:3072
	v_lshl_add_u64 v[140:141], s[24:25], 0, v[128:129]
	s_mov_b32 m0, s20
	v_lshl_add_u64 v[232:233], s[24:25], 0, v[130:131]
	global_load_lds_dwordx4 v[140:141], off
	s_add_i32 m0, s20, 0x2000
	s_nop 0
	global_load_lds_dwordx4 v[232:233], off
	s_barrier
	s_waitcnt lgkmcnt(0)
	s_setprio 1
	s_waitcnt lgkmcnt(0)
	v_mfma_f32_16x16x32_bf16 v[116:119], v[216:219], v[158:161], v[116:119]
	v_mfma_f32_16x16x32_bf16 v[112:115], v[224:227], v[158:161], v[112:115]
	v_mfma_f32_16x16x32_bf16 v[100:103], v[216:219], v[180:183], v[100:103]
	v_mfma_f32_16x16x32_bf16 v[96:99], v[224:227], v[180:183], v[96:99]
	v_mfma_f32_16x16x32_bf16 v[84:87], v[216:219], v[188:191], v[84:87]
	v_mfma_f32_16x16x32_bf16 v[80:83], v[224:227], v[188:191], v[80:83]
	v_mfma_f32_16x16x32_bf16 v[68:71], v[216:219], v[208:211], v[68:71]
	v_mfma_f32_16x16x32_bf16 v[64:67], v[224:227], v[208:211], v[64:67]
	v_mfma_f32_16x16x32_bf16 v[116:119], v[220:223], v[176:179], v[116:119]
	v_mfma_f32_16x16x32_bf16 v[112:115], v[228:231], v[176:179], v[112:115]
	v_mfma_f32_16x16x32_bf16 v[100:103], v[220:223], v[184:187], v[100:103]
	v_mfma_f32_16x16x32_bf16 v[96:99], v[228:231], v[184:187], v[96:99]
	v_mfma_f32_16x16x32_bf16 v[84:87], v[220:223], v[192:195], v[84:87]
	v_mfma_f32_16x16x32_bf16 v[80:83], v[228:231], v[192:195], v[80:83]
	v_mfma_f32_16x16x32_bf16 v[68:71], v[220:223], v[212:215], v[68:71]
	v_mfma_f32_16x16x32_bf16 v[64:67], v[228:231], v[212:215], v[64:67]
	s_setprio 0
	s_mov_b32 m0, s19
	v_lshl_add_u64 v[234:235], s[26:27], 0, v[128:129]
	s_barrier
	ds_read_b128 v[158:161], v145 offset:16384
	ds_read_b128 v[176:179], v145 offset:17408
	ds_read_b128 v[180:183], v145 offset:18432
	ds_read_b128 v[184:187], v145 offset:19456
	ds_read_b128 v[188:191], v145 offset:20480
	ds_read_b128 v[192:195], v145 offset:21504
	ds_read_b128 v[208:211], v145 offset:22528
	ds_read_b128 v[212:215], v145 offset:23552
	global_load_lds_dwordx4 v[234:235], off
	v_lshl_add_u64 v[236:237], s[26:27], 0, v[130:131]
	s_mov_b32 m0, s34
	s_nop 0
	global_load_lds_dwordx4 v[236:237], off
	s_barrier
	s_waitcnt lgkmcnt(0)
	s_setprio 1
	s_waitcnt lgkmcnt(0)
	v_mfma_f32_16x16x32_bf16 v[60:63], v[136:139], v[158:161], v[60:63]
	v_mfma_f32_16x16x32_bf16 v[56:59], v[150:153], v[158:161], v[56:59]
	v_mfma_f32_16x16x32_bf16 v[52:55], v[136:139], v[180:183], v[52:55]
	v_mfma_f32_16x16x32_bf16 v[48:51], v[150:153], v[180:183], v[48:51]
	v_mfma_f32_16x16x32_bf16 v[36:39], v[136:139], v[188:191], v[36:39]
	v_mfma_f32_16x16x32_bf16 v[32:35], v[150:153], v[188:191], v[32:35]
	v_mfma_f32_16x16x32_bf16 v[12:15], v[136:139], v[208:211], v[12:15]
	v_mfma_f32_16x16x32_bf16 v[8:11], v[150:153], v[208:211], v[8:11]
	v_mfma_f32_16x16x32_bf16 v[60:63], v[146:149], v[176:179], v[60:63]
	v_mfma_f32_16x16x32_bf16 v[56:59], v[154:157], v[176:179], v[56:59]
	v_mfma_f32_16x16x32_bf16 v[52:55], v[146:149], v[184:187], v[52:55]
	v_mfma_f32_16x16x32_bf16 v[48:51], v[154:157], v[184:187], v[48:51]
	v_mfma_f32_16x16x32_bf16 v[36:39], v[146:149], v[192:195], v[36:39]
	v_mfma_f32_16x16x32_bf16 v[32:35], v[154:157], v[192:195], v[32:35]
	v_mfma_f32_16x16x32_bf16 v[12:15], v[146:149], v[212:215], v[12:15]
	v_mfma_f32_16x16x32_bf16 v[8:11], v[154:157], v[212:215], v[8:11]
	s_setprio 0
	s_barrier
	s_add_u32 s20, s24, 0x80000
	s_addc_u32 s21, s25, 0
	s_add_i32 s46, s47, s31
	v_lshl_add_u64 v[136:137], s[20:21], 0, v[128:129]
	s_mov_b32 m0, s46
	s_nop 0
	global_load_lds_dwordx4 v[136:137], off
	v_lshl_add_u64 v[136:137], s[20:21], 0, v[130:131]
	s_add_i32 m0, s46, 0x2000
	s_nop 0
	global_load_lds_dwordx4 v[136:137], off
	s_waitcnt vmcnt(6)
	s_barrier
	s_setprio 1
	v_mfma_f32_16x16x32_bf16 v[44:47], v[216:219], v[158:161], v[44:47]
	v_mfma_f32_16x16x32_bf16 v[40:43], v[224:227], v[158:161], v[40:43]
	v_mfma_f32_16x16x32_bf16 v[28:31], v[216:219], v[180:183], v[28:31]
	v_mfma_f32_16x16x32_bf16 v[24:27], v[224:227], v[180:183], v[24:27]
	v_mfma_f32_16x16x32_bf16 v[20:23], v[216:219], v[188:191], v[20:23]
	v_mfma_f32_16x16x32_bf16 v[16:19], v[224:227], v[188:191], v[16:19]
	v_mfma_f32_16x16x32_bf16 v[4:7], v[216:219], v[208:211], v[4:7]
	v_mfma_f32_16x16x32_bf16 v[0:3], v[224:227], v[208:211], v[0:3]
	v_mfma_f32_16x16x32_bf16 v[44:47], v[220:223], v[176:179], v[44:47]
	v_mfma_f32_16x16x32_bf16 v[40:43], v[228:231], v[176:179], v[40:43]
	v_mfma_f32_16x16x32_bf16 v[28:31], v[220:223], v[184:187], v[28:31]
	v_mfma_f32_16x16x32_bf16 v[24:27], v[228:231], v[184:187], v[24:27]
	v_mfma_f32_16x16x32_bf16 v[20:23], v[220:223], v[192:195], v[20:23]
	v_mfma_f32_16x16x32_bf16 v[16:19], v[228:231], v[192:195], v[16:19]
	v_mfma_f32_16x16x32_bf16 v[4:7], v[220:223], v[212:215], v[4:7]
	v_mfma_f32_16x16x32_bf16 v[0:3], v[228:231], v[212:215], v[0:3]
	s_setprio 0
	s_add_i32 s46, 0, 0x18000
	v_add_u32_e32 v154, s46, v143
	s_barrier
	ds_read_b128 v[136:139], v154
	ds_read_b128 v[146:149], v154 offset:1024
	ds_read_b128 v[150:153], v154 offset:2048
	ds_read_b128 v[154:157], v154 offset:3072
	s_add_u32 s20, s26, 0x80000
	s_addc_u32 s21, s27, 0
	s_mov_b32 m0, s35
	v_lshl_add_u64 v[216:217], s[20:21], 0, v[128:129]
	ds_read_b128 v[158:161], v145 offset:32768
	ds_read_b128 v[176:179], v145 offset:33792
	ds_read_b128 v[180:183], v145 offset:34816
	ds_read_b128 v[184:187], v145 offset:35840
	ds_read_b128 v[188:191], v145 offset:36864
	ds_read_b128 v[192:195], v145 offset:37888
	ds_read_b128 v[208:211], v145 offset:38912
	ds_read_b128 v[212:215], v145 offset:39936
	global_load_lds_dwordx4 v[216:217], off
	v_lshl_add_u64 v[216:217], s[20:21], 0, v[130:131]
	s_mov_b32 m0, s36
	s_nop 0
	global_load_lds_dwordx4 v[216:217], off
	s_waitcnt lgkmcnt(8)
	s_barrier
	s_waitcnt lgkmcnt(0)
	s_setprio 1
	s_waitcnt lgkmcnt(0)
	v_mfma_f32_16x16x32_bf16 v[124:127], v[136:139], v[158:161], v[124:127]
	v_mfma_f32_16x16x32_bf16 v[120:123], v[150:153], v[158:161], v[120:123]
	v_mfma_f32_16x16x32_bf16 v[108:111], v[136:139], v[180:183], v[108:111]
	v_mfma_f32_16x16x32_bf16 v[104:107], v[150:153], v[180:183], v[104:107]
	v_mfma_f32_16x16x32_bf16 v[92:95], v[136:139], v[188:191], v[92:95]
	v_mfma_f32_16x16x32_bf16 v[88:91], v[150:153], v[188:191], v[88:91]
	v_mfma_f32_16x16x32_bf16 v[76:79], v[136:139], v[208:211], v[76:79]
	v_mfma_f32_16x16x32_bf16 v[72:75], v[150:153], v[208:211], v[72:75]
	v_mfma_f32_16x16x32_bf16 v[124:127], v[146:149], v[176:179], v[124:127]
	v_mfma_f32_16x16x32_bf16 v[120:123], v[154:157], v[176:179], v[120:123]
	v_mfma_f32_16x16x32_bf16 v[108:111], v[146:149], v[184:187], v[108:111]
	v_mfma_f32_16x16x32_bf16 v[104:107], v[154:157], v[184:187], v[104:107]
	v_mfma_f32_16x16x32_bf16 v[92:95], v[146:149], v[192:195], v[92:95]
	v_mfma_f32_16x16x32_bf16 v[88:91], v[154:157], v[192:195], v[88:91]
	v_mfma_f32_16x16x32_bf16 v[76:79], v[146:149], v[212:215], v[76:79]
	v_mfma_f32_16x16x32_bf16 v[72:75], v[154:157], v[212:215], v[72:75]
	s_setprio 0
	s_barrier
	s_add_i32 s26, 0, 0x1c000
	s_add_i32 s20, s46, s31
	v_add_u32_e32 v196, s26, v143
	v_lshl_add_u64 v[140:141], v[140:141], 0, s[6:7]
	s_mov_b32 m0, s20
	ds_read_b128 v[216:219], v196
	ds_read_b128 v[220:223], v196 offset:1024
	ds_read_b128 v[224:227], v196 offset:2048
	ds_read_b128 v[228:231], v196 offset:3072
	global_load_lds_dwordx4 v[140:141], off
	v_lshl_add_u64 v[140:141], v[232:233], 0, s[6:7]
	s_add_i32 m0, s20, 0x2000
	s_nop 0
	global_load_lds_dwordx4 v[140:141], off
	s_barrier
	s_waitcnt lgkmcnt(0)
	s_setprio 1
	s_waitcnt lgkmcnt(0)
	v_mfma_f32_16x16x32_bf16 v[116:119], v[216:219], v[158:161], v[116:119]
	v_mfma_f32_16x16x32_bf16 v[112:115], v[224:227], v[158:161], v[112:115]
	v_mfma_f32_16x16x32_bf16 v[100:103], v[216:219], v[180:183], v[100:103]
	v_mfma_f32_16x16x32_bf16 v[96:99], v[224:227], v[180:183], v[96:99]
	v_mfma_f32_16x16x32_bf16 v[84:87], v[216:219], v[188:191], v[84:87]
	v_mfma_f32_16x16x32_bf16 v[80:83], v[224:227], v[188:191], v[80:83]
	v_mfma_f32_16x16x32_bf16 v[68:71], v[216:219], v[208:211], v[68:71]
	v_mfma_f32_16x16x32_bf16 v[64:67], v[224:227], v[208:211], v[64:67]
	v_mfma_f32_16x16x32_bf16 v[116:119], v[220:223], v[176:179], v[116:119]
	v_mfma_f32_16x16x32_bf16 v[112:115], v[228:231], v[176:179], v[112:115]
	v_mfma_f32_16x16x32_bf16 v[100:103], v[220:223], v[184:187], v[100:103]
	v_mfma_f32_16x16x32_bf16 v[96:99], v[228:231], v[184:187], v[96:99]
	v_mfma_f32_16x16x32_bf16 v[84:87], v[220:223], v[192:195], v[84:87]
	v_mfma_f32_16x16x32_bf16 v[80:83], v[228:231], v[192:195], v[80:83]
	v_mfma_f32_16x16x32_bf16 v[68:71], v[220:223], v[212:215], v[68:71]
	v_mfma_f32_16x16x32_bf16 v[64:67], v[228:231], v[212:215], v[64:67]
	s_setprio 0
	s_mov_b32 m0, s37
	v_lshl_add_u64 v[140:141], v[234:235], 0, s[6:7]
	s_barrier
	ds_read_b128 v[158:161], v145 offset:49152
	ds_read_b128 v[176:179], v145 offset:50176
	ds_read_b128 v[180:183], v145 offset:51200
	ds_read_b128 v[184:187], v145 offset:52224
	ds_read_b128 v[188:191], v145 offset:53248
	ds_read_b128 v[192:195], v145 offset:54272
	ds_read_b128 v[208:211], v145 offset:55296
	ds_read_b128 v[212:215], v145 offset:56320
	global_load_lds_dwordx4 v[140:141], off
	v_lshl_add_u64 v[140:141], v[236:237], 0, s[6:7]
	s_mov_b32 m0, s38
	s_nop 0
	global_load_lds_dwordx4 v[140:141], off
	s_barrier
	s_waitcnt lgkmcnt(0)
	s_setprio 1
	s_waitcnt lgkmcnt(0)
	v_mfma_f32_16x16x32_bf16 v[60:63], v[136:139], v[158:161], v[60:63]
	v_mfma_f32_16x16x32_bf16 v[56:59], v[150:153], v[158:161], v[56:59]
	v_mfma_f32_16x16x32_bf16 v[52:55], v[136:139], v[180:183], v[52:55]
	v_mfma_f32_16x16x32_bf16 v[48:51], v[150:153], v[180:183], v[48:51]
	v_mfma_f32_16x16x32_bf16 v[36:39], v[136:139], v[188:191], v[36:39]
	v_mfma_f32_16x16x32_bf16 v[32:35], v[150:153], v[188:191], v[32:35]
	v_mfma_f32_16x16x32_bf16 v[12:15], v[136:139], v[208:211], v[12:15]
	v_mfma_f32_16x16x32_bf16 v[8:11], v[150:153], v[208:211], v[8:11]
	v_mfma_f32_16x16x32_bf16 v[60:63], v[146:149], v[176:179], v[60:63]
	v_mfma_f32_16x16x32_bf16 v[56:59], v[154:157], v[176:179], v[56:59]
	v_mfma_f32_16x16x32_bf16 v[52:55], v[146:149], v[184:187], v[52:55]
	v_mfma_f32_16x16x32_bf16 v[48:51], v[154:157], v[184:187], v[48:51]
	v_mfma_f32_16x16x32_bf16 v[36:39], v[146:149], v[192:195], v[36:39]
	v_mfma_f32_16x16x32_bf16 v[32:35], v[154:157], v[192:195], v[32:35]
	v_mfma_f32_16x16x32_bf16 v[12:15], v[146:149], v[212:215], v[12:15]
	v_mfma_f32_16x16x32_bf16 v[8:11], v[154:157], v[212:215], v[8:11]
	s_setprio 0
	s_barrier
	s_add_u32 s20, s24, 0x80080
	s_addc_u32 s21, s25, 0
	s_add_i32 s24, s26, s31
	v_lshl_add_u64 v[136:137], s[20:21], 0, v[128:129]
	s_mov_b32 m0, s24
	s_nop 0
	global_load_lds_dwordx4 v[136:137], off
	v_lshl_add_u64 v[136:137], s[20:21], 0, v[130:131]
	s_add_i32 m0, s24, 0x2000
	s_nop 0
	global_load_lds_dwordx4 v[136:137], off
	s_waitcnt vmcnt(6)
	s_barrier
	s_setprio 1
	v_mfma_f32_16x16x32_bf16 v[44:47], v[216:219], v[158:161], v[44:47]
	v_mfma_f32_16x16x32_bf16 v[40:43], v[224:227], v[158:161], v[40:43]
	v_mfma_f32_16x16x32_bf16 v[28:31], v[216:219], v[180:183], v[28:31]
	v_mfma_f32_16x16x32_bf16 v[24:27], v[224:227], v[180:183], v[24:27]
	v_mfma_f32_16x16x32_bf16 v[20:23], v[216:219], v[188:191], v[20:23]
	v_mfma_f32_16x16x32_bf16 v[16:19], v[224:227], v[188:191], v[16:19]
	v_mfma_f32_16x16x32_bf16 v[4:7], v[216:219], v[208:211], v[4:7]
	v_mfma_f32_16x16x32_bf16 v[0:3], v[224:227], v[208:211], v[0:3]
	v_mfma_f32_16x16x32_bf16 v[44:47], v[220:223], v[176:179], v[44:47]
	v_mfma_f32_16x16x32_bf16 v[40:43], v[228:231], v[176:179], v[40:43]
	v_mfma_f32_16x16x32_bf16 v[28:31], v[220:223], v[184:187], v[28:31]
	v_mfma_f32_16x16x32_bf16 v[24:27], v[228:231], v[184:187], v[24:27]
	v_mfma_f32_16x16x32_bf16 v[20:23], v[220:223], v[192:195], v[20:23]
	v_mfma_f32_16x16x32_bf16 v[16:19], v[228:231], v[192:195], v[16:19]
	v_mfma_f32_16x16x32_bf16 v[4:7], v[220:223], v[212:215], v[4:7]
	v_mfma_f32_16x16x32_bf16 v[0:3], v[228:231], v[212:215], v[0:3]
	s_setprio 0
	s_add_i32 s45, s45, 2
	s_add_u32 s43, s43, 0x100
	s_addc_u32 s44, s44, 0
	s_cmp_gt_u32 s45, 29
	s_mov_b64 s[20:21], s[22:23]
	s_barrier
	s_cbranch_scc0 .LBB0_167
	v_lshl_add_u32 v140, s18, 8, v142
	v_lshl_or_b32 v136, s40, 8, v144
	v_ashrrev_i32_e32 v141, 31, v140
	v_ashrrev_i32_e32 v137, 31, v136
	v_lshlrev_b64 v[138:139], 13, v[140:141]
	v_lshl_add_u64 v[146:147], s[76:77], 0, v[138:139]
	v_lshlrev_b64 v[138:139], 2, v[136:137]
	v_lshl_add_u64 v[136:137], v[146:147], 0, v[138:139]
	global_load_dwordx4 v[146:149], v[136:137], off
	s_mov_b64 s[20:21], 0x100000
	s_mov_b32 s11, 0x160000
	s_mov_b32 s40, s10
	s_mov_b32 s18, s12
	s_mov_b64 s[22:23], s[16:17]
	s_waitcnt vmcnt(0)
	v_pk_fma_f32 v[126:127], v[148:149], s[74:75], v[126:127] op_sel_hi:[1,0,1]
	v_pk_fma_f32 v[124:125], v[146:147], s[74:75], v[124:125] op_sel_hi:[1,0,1]
	global_store_dwordx4 v[136:137], v[124:127], off
	global_load_dwordx4 v[124:127], v[136:137], off offset:64
	s_waitcnt vmcnt(0)
	v_pk_fma_f32 v[122:123], v[126:127], s[74:75], v[122:123] op_sel_hi:[1,0,1]
	v_pk_fma_f32 v[120:121], v[124:125], s[74:75], v[120:121] op_sel_hi:[1,0,1]
	global_store_dwordx4 v[136:137], v[120:123], off offset:64
	global_load_dwordx4 v[120:123], v[136:137], off offset:512
	s_waitcnt vmcnt(0)
	v_pk_fma_f32 v[118:119], v[122:123], s[74:75], v[118:119] op_sel_hi:[1,0,1]
	v_pk_fma_f32 v[116:117], v[120:121], s[74:75], v[116:117] op_sel_hi:[1,0,1]
	global_store_dwordx4 v[136:137], v[116:119], off offset:512
	global_load_dwordx4 v[116:119], v[136:137], off offset:576
	s_waitcnt vmcnt(0)
	v_pk_fma_f32 v[114:115], v[118:119], s[74:75], v[114:115] op_sel_hi:[1,0,1]
	v_pk_fma_f32 v[112:113], v[116:117], s[74:75], v[112:113] op_sel_hi:[1,0,1]
	global_store_dwordx4 v[136:137], v[112:115], off offset:576
	s_nop 1
	v_or_b32_e32 v112, 16, v140
	v_ashrrev_i32_e32 v113, 31, v112
	v_lshlrev_b64 v[112:113], 13, v[112:113]
	v_lshl_add_u64 v[112:113], s[76:77], 0, v[112:113]
	v_lshl_add_u64 v[116:117], v[112:113], 0, v[138:139]
	global_load_dwordx4 v[112:115], v[116:117], off
	s_waitcnt vmcnt(0)
	v_pk_fma_f32 v[110:111], v[114:115], s[74:75], v[110:111] op_sel_hi:[1,0,1]
	v_pk_fma_f32 v[108:109], v[112:113], s[74:75], v[108:109] op_sel_hi:[1,0,1]
	global_store_dwordx4 v[116:117], v[108:111], off
	global_load_dwordx4 v[108:111], v[116:117], off offset:64
	s_waitcnt vmcnt(0)
	v_pk_fma_f32 v[106:107], v[110:111], s[74:75], v[106:107] op_sel_hi:[1,0,1]
	v_pk_fma_f32 v[104:105], v[108:109], s[74:75], v[104:105] op_sel_hi:[1,0,1]
	global_store_dwordx4 v[116:117], v[104:107], off offset:64
	global_load_dwordx4 v[104:107], v[116:117], off offset:512
	s_waitcnt vmcnt(0)
	v_pk_fma_f32 v[102:103], v[106:107], s[74:75], v[102:103] op_sel_hi:[1,0,1]
	v_pk_fma_f32 v[100:101], v[104:105], s[74:75], v[100:101] op_sel_hi:[1,0,1]
	global_store_dwordx4 v[116:117], v[100:103], off offset:512
	global_load_dwordx4 v[100:103], v[116:117], off offset:576
	s_waitcnt vmcnt(0)
	v_pk_fma_f32 v[98:99], v[102:103], s[74:75], v[98:99] op_sel_hi:[1,0,1]
	v_pk_fma_f32 v[96:97], v[100:101], s[74:75], v[96:97] op_sel_hi:[1,0,1]
	global_store_dwordx4 v[116:117], v[96:99], off offset:576
	s_nop 1
	v_or_b32_e32 v96, 32, v140
	v_ashrrev_i32_e32 v97, 31, v96
	v_lshlrev_b64 v[96:97], 13, v[96:97]
	v_lshl_add_u64 v[96:97], s[76:77], 0, v[96:97]
	v_lshl_add_u64 v[100:101], v[96:97], 0, v[138:139]
	global_load_dwordx4 v[96:99], v[100:101], off
	s_waitcnt vmcnt(0)
	v_pk_fma_f32 v[94:95], v[98:99], s[74:75], v[94:95] op_sel_hi:[1,0,1]
	v_pk_fma_f32 v[92:93], v[96:97], s[74:75], v[92:93] op_sel_hi:[1,0,1]
	global_store_dwordx4 v[100:101], v[92:95], off
	global_load_dwordx4 v[92:95], v[100:101], off offset:64
	s_waitcnt vmcnt(0)
	v_pk_fma_f32 v[90:91], v[94:95], s[74:75], v[90:91] op_sel_hi:[1,0,1]
	v_pk_fma_f32 v[88:89], v[92:93], s[74:75], v[88:89] op_sel_hi:[1,0,1]
	global_store_dwordx4 v[100:101], v[88:91], off offset:64
	global_load_dwordx4 v[88:91], v[100:101], off offset:512
	s_waitcnt vmcnt(0)
	v_pk_fma_f32 v[86:87], v[90:91], s[74:75], v[86:87] op_sel_hi:[1,0,1]
	v_pk_fma_f32 v[84:85], v[88:89], s[74:75], v[84:85] op_sel_hi:[1,0,1]
	global_store_dwordx4 v[100:101], v[84:87], off offset:512
	global_load_dwordx4 v[84:87], v[100:101], off offset:576
	s_waitcnt vmcnt(0)
	v_pk_fma_f32 v[82:83], v[86:87], s[74:75], v[82:83] op_sel_hi:[1,0,1]
	v_pk_fma_f32 v[80:81], v[84:85], s[74:75], v[80:81] op_sel_hi:[1,0,1]
	global_store_dwordx4 v[100:101], v[80:83], off offset:576
	s_nop 1
	v_or_b32_e32 v80, 48, v140
	v_ashrrev_i32_e32 v81, 31, v80
	v_lshlrev_b64 v[80:81], 13, v[80:81]
	v_lshl_add_u64 v[80:81], s[76:77], 0, v[80:81]
	v_lshl_add_u64 v[84:85], v[80:81], 0, v[138:139]
	global_load_dwordx4 v[80:83], v[84:85], off
	s_waitcnt vmcnt(0)
	v_pk_fma_f32 v[78:79], v[82:83], s[74:75], v[78:79] op_sel_hi:[1,0,1]
	v_pk_fma_f32 v[76:77], v[80:81], s[74:75], v[76:77] op_sel_hi:[1,0,1]
	global_store_dwordx4 v[84:85], v[76:79], off
	global_load_dwordx4 v[76:79], v[84:85], off offset:64
	s_waitcnt vmcnt(0)
	v_pk_fma_f32 v[74:75], v[78:79], s[74:75], v[74:75] op_sel_hi:[1,0,1]
	v_pk_fma_f32 v[72:73], v[76:77], s[74:75], v[72:73] op_sel_hi:[1,0,1]
	global_store_dwordx4 v[84:85], v[72:75], off offset:64
	global_load_dwordx4 v[72:75], v[84:85], off offset:512
	s_waitcnt vmcnt(0)
	v_pk_fma_f32 v[70:71], v[74:75], s[74:75], v[70:71] op_sel_hi:[1,0,1]
	v_pk_fma_f32 v[68:69], v[72:73], s[74:75], v[68:69] op_sel_hi:[1,0,1]
	global_store_dwordx4 v[84:85], v[68:71], off offset:512
	global_load_dwordx4 v[68:71], v[84:85], off offset:576
	s_waitcnt vmcnt(0)
	v_pk_fma_f32 v[66:67], v[70:71], s[74:75], v[66:67] op_sel_hi:[1,0,1]
	v_add_co_u32_e32 v70, vcc, s90, v136
	v_pk_fma_f32 v[64:65], v[68:69], s[74:75], v[64:65] op_sel_hi:[1,0,1]
	s_nop 0
	v_addc_co_u32_e32 v71, vcc, 0, v137, vcc
	global_store_dwordx4 v[84:85], v[64:67], off offset:576
	global_load_dwordx4 v[64:67], v[70:71], off
	v_lshl_add_u64 v[68:69], v[136:137], 0, s[20:21]
	s_mov_b64 s[20:21], 0x120000
	s_waitcnt vmcnt(0)
	v_pk_fma_f32 v[62:63], v[66:67], s[74:75], v[62:63] op_sel_hi:[1,0,1]
	v_pk_fma_f32 v[60:61], v[64:65], s[74:75], v[60:61] op_sel_hi:[1,0,1]
	global_store_dwordx4 v[70:71], v[60:63], off
	global_load_dwordx4 v[60:63], v[68:69], off offset:64
	s_waitcnt vmcnt(0)
	v_pk_fma_f32 v[58:59], v[62:63], s[74:75], v[58:59] op_sel_hi:[1,0,1]
	v_pk_fma_f32 v[56:57], v[60:61], s[74:75], v[56:57] op_sel_hi:[1,0,1]
	global_store_dwordx4 v[68:69], v[56:59], off offset:64
	global_load_dwordx4 v[56:59], v[68:69], off offset:512
	s_waitcnt vmcnt(0)
	v_pk_fma_f32 v[46:47], v[58:59], s[74:75], v[46:47] op_sel_hi:[1,0,1]
	v_pk_fma_f32 v[44:45], v[56:57], s[74:75], v[44:45] op_sel_hi:[1,0,1]
	global_store_dwordx4 v[68:69], v[44:47], off offset:512
	global_load_dwordx4 v[44:47], v[68:69], off offset:576
	s_waitcnt vmcnt(0)
	v_pk_fma_f32 v[42:43], v[46:47], s[74:75], v[42:43] op_sel_hi:[1,0,1]
	v_add_co_u32_e32 v46, vcc, s91, v136
	v_pk_fma_f32 v[40:41], v[44:45], s[74:75], v[40:41] op_sel_hi:[1,0,1]
	s_nop 0
	v_addc_co_u32_e32 v47, vcc, 0, v137, vcc
	global_store_dwordx4 v[68:69], v[40:43], off offset:576
	global_load_dwordx4 v[40:43], v[46:47], off
	v_lshl_add_u64 v[44:45], v[136:137], 0, s[20:21]
	s_mov_b64 s[20:21], 0x140000
	s_waitcnt vmcnt(0)
	v_pk_fma_f32 v[42:43], v[42:43], s[74:75], v[54:55] op_sel_hi:[1,0,1]
	v_pk_fma_f32 v[40:41], v[40:41], s[74:75], v[52:53] op_sel_hi:[1,0,1]
	global_store_dwordx4 v[46:47], v[40:43], off
	global_load_dwordx4 v[40:43], v[44:45], off offset:64
	s_waitcnt vmcnt(0)
	v_pk_fma_f32 v[42:43], v[42:43], s[74:75], v[50:51] op_sel_hi:[1,0,1]
	v_pk_fma_f32 v[40:41], v[40:41], s[74:75], v[48:49] op_sel_hi:[1,0,1]
	global_store_dwordx4 v[44:45], v[40:43], off offset:64
	global_load_dwordx4 v[40:43], v[44:45], off offset:512
	s_waitcnt vmcnt(0)
	v_pk_fma_f32 v[30:31], v[42:43], s[74:75], v[30:31] op_sel_hi:[1,0,1]
	v_pk_fma_f32 v[28:29], v[40:41], s[74:75], v[28:29] op_sel_hi:[1,0,1]
	global_store_dwordx4 v[44:45], v[28:31], off offset:512
	global_load_dwordx4 v[28:31], v[44:45], off offset:576
	s_waitcnt vmcnt(0)
	v_pk_fma_f32 v[26:27], v[30:31], s[74:75], v[26:27] op_sel_hi:[1,0,1]
	v_add_co_u32_e32 v30, vcc, s96, v136
	v_pk_fma_f32 v[24:25], v[28:29], s[74:75], v[24:25] op_sel_hi:[1,0,1]
	s_nop 0
	v_addc_co_u32_e32 v31, vcc, 0, v137, vcc
	global_store_dwordx4 v[44:45], v[24:27], off offset:576
	global_load_dwordx4 v[24:27], v[30:31], off
	v_lshl_add_u64 v[28:29], v[136:137], 0, s[20:21]
	s_mov_b64 s[20:21], 0x160000
	s_waitcnt vmcnt(0)
	v_pk_fma_f32 v[26:27], v[26:27], s[74:75], v[38:39] op_sel_hi:[1,0,1]
	v_pk_fma_f32 v[24:25], v[24:25], s[74:75], v[36:37] op_sel_hi:[1,0,1]
	global_store_dwordx4 v[30:31], v[24:27], off
	global_load_dwordx4 v[24:27], v[28:29], off offset:64
	s_waitcnt vmcnt(0)
	v_pk_fma_f32 v[26:27], v[26:27], s[74:75], v[34:35] op_sel_hi:[1,0,1]
	v_pk_fma_f32 v[24:25], v[24:25], s[74:75], v[32:33] op_sel_hi:[1,0,1]
	global_store_dwordx4 v[28:29], v[24:27], off offset:64
	global_load_dwordx4 v[24:27], v[28:29], off offset:512
	s_waitcnt vmcnt(0)
	v_pk_fma_f32 v[22:23], v[26:27], s[74:75], v[22:23] op_sel_hi:[1,0,1]
	v_pk_fma_f32 v[20:21], v[24:25], s[74:75], v[20:21] op_sel_hi:[1,0,1]
	global_store_dwordx4 v[28:29], v[20:23], off offset:512
	global_load_dwordx4 v[20:23], v[28:29], off offset:576
	s_waitcnt vmcnt(0)
	v_pk_fma_f32 v[18:19], v[22:23], s[74:75], v[18:19] op_sel_hi:[1,0,1]
	v_add_co_u32_e32 v22, vcc, s11, v136
	v_pk_fma_f32 v[16:17], v[20:21], s[74:75], v[16:17] op_sel_hi:[1,0,1]
	s_nop 0
	v_addc_co_u32_e32 v23, vcc, 0, v137, vcc
	global_store_dwordx4 v[28:29], v[16:19], off offset:576
	global_load_dwordx4 v[18:21], v[22:23], off
	s_and_b64 vcc, exec, s[8:9]
	v_lshl_add_u64 v[16:17], v[136:137], 0, s[20:21]
	s_mov_b64 s[20:21], s[14:15]
	s_waitcnt vmcnt(0)
	v_pk_fma_f32 v[14:15], v[20:21], s[74:75], v[14:15] op_sel_hi:[1,0,1]
	v_pk_fma_f32 v[12:13], v[18:19], s[74:75], v[12:13] op_sel_hi:[1,0,1]
	global_store_dwordx4 v[22:23], v[12:15], off
	global_load_dwordx4 v[12:15], v[16:17], off offset:64
	s_waitcnt vmcnt(0)
	v_pk_fma_f32 v[10:11], v[14:15], s[74:75], v[10:11] op_sel_hi:[1,0,1]
	v_pk_fma_f32 v[8:9], v[12:13], s[74:75], v[8:9] op_sel_hi:[1,0,1]
	global_store_dwordx4 v[16:17], v[8:11], off offset:64
	global_load_dwordx4 v[8:11], v[16:17], off offset:512
	s_waitcnt vmcnt(0)
	v_pk_fma_f32 v[6:7], v[10:11], s[74:75], v[6:7] op_sel_hi:[1,0,1]
	v_pk_fma_f32 v[4:5], v[8:9], s[74:75], v[4:5] op_sel_hi:[1,0,1]
	global_store_dwordx4 v[16:17], v[4:7], off offset:512
	global_load_dwordx4 v[4:7], v[16:17], off offset:576
	s_waitcnt vmcnt(0)
	v_pk_fma_f32 v[2:3], v[6:7], s[74:75], v[2:3] op_sel_hi:[1,0,1]
	v_pk_fma_f32 v[0:1], v[4:5], s[74:75], v[0:1] op_sel_hi:[1,0,1]
	global_store_dwordx4 v[16:17], v[0:3], off offset:576
	s_cbranch_vccz .LBB0_160
	s_waitcnt vmcnt(0)
	s_cmpk_gt_u32 s1, 0xff
	s_cbranch_scc1 .LBB0_171
	s_barrier

.LBB0_242:
	s_andn2_b64 vcc, exec, s[8:9]
	s_cbranch_vccnz .LBB0_184
	s_lshr_b32 s20, s1, 2
	s_and_b32 s21, s1, 3
	s_lshr_b32 s14, s20, 4
	s_xor_b32 s14, s14, 1
	s_bfe_u32 s22, s20, 0x20002
	s_and_b32 s23, s20, 3
	s_mul_i32 s24, s14, 6144
	s_lshl_b32 s25, s23, 8
	s_add_u32 s24, s24, s25
	s_addk_i32 s24, 3072
	s_mul_i32 s25, s22, 0x6800000
	s_add_u32 s24, s24, s25
	s_add_u32 s8, s78, 0x15e00000
	s_addc_u32 s9, s79, 0
	s_add_u32 s8, s8, s24
	s_addc_u32 s9, s9, 0
	s_lshl_b32 s24, s14, 11
	s_lshl_b32 s25, s23, 8
	s_add_u32 s24, s24, s25
	s_lshl_b32 s25, s21, 6
	s_add_u32 s24, s24, s25
	s_addk_i32 s24, 1024
	s_lshl_b32 s25, s22, 25
	s_add_u32 s24, s24, s25
	s_add_u32 s10, s78, 0x2fe00000
	s_addc_u32 s11, s79, 0
	s_add_u32 s10, s10, s24
	s_addc_u32 s11, s11, 0
	s_lshl_b32 s24, s14, 23
	s_lshl_b32 s25, s22, 21
	s_add_u32 s24, s24, s25
	s_lshl_b32 s25, s23, 6
	s_add_u32 s24, s24, s25
	s_lshl_b32 s25, s21, 4
	s_add_u32 s24, s24, s25
	s_add_u32 s12, s78, 0x3ae90000
	s_addc_u32 s13, s79, 0
	s_add_u32 s12, s12, s24
	s_addc_u32 s13, s13, 0
	v_lshrrev_b32_e32 v154, 5, v163
	v_and_b32_e32 v155, 31, v163
	v_bfe_u32 v156, v163, 4, 4
	v_and_b32_e32 v157, 15, v163
	v_lshrrev_b32_e32 v160, 6, v163
	v_mul_u32_u24_e32 v130, 0x3400, v154
	v_lshl_add_u32 v130, v155, 3, v130
	v_mul_u32_u24_e32 v131, 0x3400, v156
	v_lshl_add_u32 v131, v157, 2, v131
	s_lshl_b32 s24, s21, 6
	s_addk_i32 s24, 2048
	v_add_u32_e32 v131, s24, v131
	v_readfirstlane_b32 s16, v160
	v_lshlrev_b32_e32 v132, 12, v154
	v_lshl_add_u32 v132, v155, 1, v132
	v_lshlrev_b32_e32 v133, 8, v154
	v_and_b32_e32 v134, 0xfffffff0, v163
	v_lshlrev_b32_e32 v135, 4, v157
	v_lshlrev_b32_e32 v139, 9, v154
	v_lshl_add_u32 v139, v155, 4, v139
	v_and_b32_e32 v158, 7, v157
	v_lshlrev_b32_e32 v158, 5, v158
	v_lshrrev_b32_e32 v159, 3, v157
	v_lshl_add_u32 v158, v159, 2, v158
	v_and_b32_e32 v159, 1, v156
	v_lshl_add_u32 v158, v159, 3, v158
	v_lshrrev_b32_e32 v159, 1, v156
	v_lshl_add_u32 v158, v159, 8, v158
	v_add_u32_e32 v140, 0x6000, v158
	v_add_u32_e32 v153, 0xe000, v158
	v_bfe_u32 v158, v163, 4, 1
	v_bfe_u32 v159, v163, 5, 1
	v_lshlrev_b32_e32 v158, 3, v158
	v_lshl_add_u32 v158, v159, 2, v158
	v_lshl_add_u32 v158, v158, 3, v160
	v_lshlrev_b32_e32 v158, 7, v158
	v_lshl_add_u32 v158, v157, 2, v158
	v_add_u32_e32 v141, 0x10000, v158
	v_add_u32_e32 v142, 0x10400, v158
	v_add_u32_e32 v143, 0x10800, v158
	v_add_u32_e32 v144, 0x10c00, v158
	v_add_u32_e32 v145, 0x14000, v158
	v_add_u32_e32 v146, 0x14400, v158
	v_add_u32_e32 v147, 0x14800, v158
	v_add_u32_e32 v148, 0x14c00, v158
	v_lshlrev_b32_e32 v161, 10, v154
	v_lshl_add_u32 v161, v155, 2, v161
	v_add_u32_e32 v149, 0x10000, v161
	v_add_u32_e32 v150, 0x14000, v161
	s_sub_u32 s24, 122, s23
	s_lshl_b32 s24, s24, 23
	v_mov_b32_e32 v100, s24
	v_sub_f32_e32 v100, 1.0, v100
	v_mov_b32_e32 v101, v100
	v_mov_b32_e32 v0, 0
	v_mov_b32_e32 v1, 0
	v_mov_b32_e32 v2, 0
	v_mov_b32_e32 v3, 0
	v_mov_b32_e32 v4, 0
	v_mov_b32_e32 v5, 0
	v_mov_b32_e32 v6, 0
	v_mov_b32_e32 v7, 0
	s_mov_b32 s18, 1
	s_mov_b32 s19, 1
	s_movk_i32 s15, 512
	global_load_dwordx2 v[120:121], v130, s[8:9]
	global_load_dwordx2 v[122:123], v130, s[8:9] offset:1024
	global_load_dword v124, v131, s[8:9]
	s_add_u32 s8, s8, 0x34000
	s_addc_u32 s9, s9, 0
	s_waitcnt vmcnt(0)
	v_lshlrev_b32_e32 v180, 16, v122
	v_and_b32_e32 v181, s69, v122
	v_lshlrev_b32_e32 v182, 16, v123
	v_and_b32_e32 v183, s69, v123
	s_cmp_eq_u32 s14, 0
	s_cbranch_scc1 .Lgla_st_join_1
	v_mul_f32_e32 v180, 0x3fb8aa3b, v180
	v_mul_f32_e32 v181, 0x3fb8aa3b, v181
	v_mul_f32_e32 v182, 0x3fb8aa3b, v182
	v_mul_f32_e32 v183, 0x3fb8aa3b, v183
	v_exp_f32_e32 v180, v180
	v_exp_f32_e32 v181, v181
	v_exp_f32_e32 v182, v182
	v_exp_f32_e32 v183, v183
.Lgla_st_join_1:
	v_lshlrev_b32_e32 v184, 16, v120
	v_and_b32_e32 v185, s69, v120
	v_lshlrev_b32_e32 v186, 16, v121
	v_and_b32_e32 v187, s69, v121
	v_lshlrev_b32_e32 v188, 16, v124
	v_and_b32_e32 v189, s69, v124
	ds_write_b128 v139, v[180:183] offset:8192
	ds_write_b128 v139, v[184:187] offset:16384
	ds_write2_b32 v140, v188, v189 offset1:4
	global_load_dwordx2 v[126:127], v130, s[8:9]
	global_load_dwordx2 v[190:191], v130, s[8:9] offset:1024
	global_load_dword v119, v131, s[8:9]
	s_add_u32 s8, s8, 0x34000
	s_addc_u32 s9, s9, 0
	global_load_dword v152, v131, s[8:9]
	global_load_dword v152, v131, s[8:9]
	global_load_dwordx2 v[120:121], v130, s[8:9]
	global_load_dwordx2 v[122:123], v130, s[8:9] offset:1024
	global_load_dword v124, v131, s[8:9]
	s_add_u32 s8, s8, 0x34000
	s_addc_u32 s9, s9, 0
	global_load_dword v152, v131, s[8:9]
	global_load_dword v152, v131, s[8:9]
	s_waitcnt lgkmcnt(0)
	s_barrier
	s_cmp_eq_u32 s14, 0
	s_cbranch_scc1 .Lgla_loop_ret
.Lgla_loop_hgrn:
	ds_read2_b32 v[104:105], v150 offset0:0 offset1:32
	ds_read2_b32 v[106:107], v150 offset0:64 offset1:96
	ds_read2_b32 v[108:109], v150 offset0:128 offset1:160
	ds_read2_b32 v[110:111], v150 offset0:192 offset1:224
	s_waitcnt vmcnt(7)
	v_lshlrev_b32_e32 v180, 16, v190
	v_and_b32_e32 v181, s69, v190
	v_lshlrev_b32_e32 v182, 16, v191
	v_and_b32_e32 v183, s69, v191
	s_cmp_eq_u32 s14, 0
	s_cbranch_scc1 .Lgla_st_join_2
	v_mul_f32_e32 v180, 0x3fb8aa3b, v180
	v_mul_f32_e32 v181, 0x3fb8aa3b, v181
	v_mul_f32_e32 v182, 0x3fb8aa3b, v182
	v_mul_f32_e32 v183, 0x3fb8aa3b, v183
	v_exp_f32_e32 v180, v180
	v_exp_f32_e32 v181, v181
	v_exp_f32_e32 v182, v182
	v_exp_f32_e32 v183, v183
.Lgla_st_join_2:
	v_lshlrev_b32_e32 v184, 16, v126
	v_and_b32_e32 v185, s69, v126
	v_lshlrev_b32_e32 v186, 16, v127
	v_and_b32_e32 v187, s69, v127
	v_lshlrev_b32_e32 v188, 16, v119
	v_and_b32_e32 v189, s69, v119
	ds_write_b128 v139, v[180:183] offset:40960
	ds_write_b128 v139, v[184:187] offset:49152
	ds_write2_b32 v153, v188, v189 offset1:4
	global_load_dwordx2 v[126:127], v130, s[8:9]
	global_load_dwordx2 v[190:191], v130, s[8:9] offset:1024
	global_load_dword v119, v131, s[8:9]
	s_add_u32 s8, s8, 0x34000
	s_addc_u32 s9, s9, 0
	s_waitcnt lgkmcnt(3)
	v_add_f32_e32 v112, v104, v105
	v_add_f32_e32 v112, v112, v106
	v_add_f32_e32 v112, v112, v107
	v_add_f32_e32 v112, v112, v108
	v_add_f32_e32 v112, v112, v109
	v_add_f32_e32 v112, v112, v110
	v_add_f32_e32 v112, v112, v111
	v_mul_f32_e32 v113, v112, v112
	v_cvt_pk_bf16_f32 v116, v112, v129
	v_mov_b32_e32 v117, v112
	v_mov_b32_e32 v118, v113
	global_store_short v132, v116, s[10:11]
	s_nop 1
	v_permlane16_swap_b32_e32 v112, v117
	v_permlane16_swap_b32_e32 v113, v118
	v_add_f32_e32 v112, v112, v117
	v_add_f32_e32 v113, v113, v118
	s_nop 1
	v_add_f32_dpp v112, v112, v112 row_ror:8 row_mask:0xf bank_mask:0xf
	v_add_f32_dpp v113, v113, v113 row_ror:8 row_mask:0xf bank_mask:0xf
	s_nop 1
	v_add_f32_dpp v112, v112, v112 row_ror:4 row_mask:0xf bank_mask:0xf
	v_add_f32_dpp v113, v113, v113 row_ror:4 row_mask:0xf bank_mask:0xf
	s_nop 1
	v_add_f32_dpp v112, v112, v112 row_ror:2 row_mask:0xf bank_mask:0xf
	v_add_f32_dpp v113, v113, v113 row_ror:2 row_mask:0xf bank_mask:0xf
	s_nop 1
	v_add_f32_dpp v112, v112, v112 row_ror:1 row_mask:0xf bank_mask:0xf
	v_add_f32_dpp v113, v113, v113 row_ror:1 row_mask:0xf bank_mask:0xf
	v_mov_b32_e32 v114, 0
	v_mov_b32_e32 v115, 0
	s_mov_b64 exec, s[18:19]
	global_store_dwordx4 v133, v[112:115], s[12:13]
	s_mov_b64 exec, -1
	s_cmp_eq_u32 s15, 512
	s_cselect_b32 s20, 0, 0x10000
	s_cselect_b32 s21, 0, 0x1000
	s_add_u32 s10, s10, s20
	s_addc_u32 s11, s11, 0
	s_add_u32 s12, s12, s21
	s_addc_u32 s13, s13, 0
	ds_read_b128 v[80:83], v135 offset:24576
	ds_read_b128 v[40:43], v134 offset:8192
	ds_read_b128 v[44:47], v134 offset:16384
	ds_read_b128 v[48:51], v134 offset:8704
	ds_read_b128 v[52:55], v134 offset:16896
	ds_read_b128 v[84:87], v135 offset:24832
	ds_read_b128 v[56:59], v134 offset:9216
	ds_read_b128 v[60:63], v134 offset:17408
	ds_read_b128 v[64:67], v134 offset:9728
	ds_read_b128 v[68:71], v134 offset:17920
	s_waitcnt lgkmcnt(7)
	v_pk_add_f32 v[92:93], v[0:1], v[80:81] neg_lo:[0,1] neg_hi:[0,1]
	v_pk_add_f32 v[94:95], v[2:3], v[80:81] neg_lo:[0,1] neg_hi:[0,1]
	v_pk_add_f32 v[96:97], v[4:5], v[80:81] neg_lo:[0,1] neg_hi:[0,1]
	v_pk_add_f32 v[98:99], v[6:7], v[80:81] neg_lo:[0,1] neg_hi:[0,1]
	v_pk_fma_f32 v[0:1], v[92:93], v[40:41], v[80:81] op_sel_hi:[1,0,1]
	v_pk_fma_f32 v[2:3], v[94:95], v[40:41], v[80:81] op_sel:[0,1,0] op_sel_hi:[1,1,1]
	v_pk_fma_f32 v[4:5], v[96:97], v[42:43], v[80:81] op_sel_hi:[1,0,1]
	v_pk_fma_f32 v[6:7], v[98:99], v[42:43], v[80:81] op_sel:[0,1,0] op_sel_hi:[1,1,1]
	ds_read_b128 v[88:91], v135 offset:25088
	ds_read_b128 v[72:75], v134 offset:10240
	ds_read_b128 v[76:79], v134 offset:18432
	s_waitcnt lgkmcnt(8)
	v_pk_add_f32 v[92:93], v[0:1], v[82:83] neg_lo:[0,1] neg_hi:[0,1]
	v_pk_mul_f32 v[8:9], v[0:1], v[44:45] op_sel_hi:[1,0]
	v_pk_add_f32 v[94:95], v[2:3], v[82:83] neg_lo:[0,1] neg_hi:[0,1]
	v_pk_fma_f32 v[8:9], v[2:3], v[44:45], v[8:9] op_sel:[0,1,0] op_sel_hi:[1,1,1]
	v_pk_add_f32 v[96:97], v[4:5], v[82:83] neg_lo:[0,1] neg_hi:[0,1]
	v_pk_fma_f32 v[8:9], v[4:5], v[46:47], v[8:9] op_sel_hi:[1,0,1]
	v_pk_add_f32 v[98:99], v[6:7], v[82:83] neg_lo:[0,1] neg_hi:[0,1]
	v_pk_fma_f32 v[8:9], v[6:7], v[46:47], v[8:9] op_sel:[0,1,0] op_sel_hi:[1,1,1]
	v_pk_fma_f32 v[0:1], v[92:93], v[48:49], v[82:83] op_sel_hi:[1,0,1]
	v_pk_fma_f32 v[2:3], v[94:95], v[48:49], v[82:83] op_sel:[0,1,0] op_sel_hi:[1,1,1]
	v_pk_fma_f32 v[4:5], v[96:97], v[50:51], v[82:83] op_sel_hi:[1,0,1]
	v_pk_fma_f32 v[6:7], v[98:99], v[50:51], v[82:83] op_sel:[0,1,0] op_sel_hi:[1,1,1]
	ds_read_b128 v[40:43], v134 offset:10752
	ds_read_b128 v[44:47], v134 offset:18944
	s_waitcnt lgkmcnt(7)
	v_pk_add_f32 v[92:93], v[0:1], v[84:85] neg_lo:[0,1] neg_hi:[0,1]
	v_pk_mul_f32 v[10:11], v[0:1], v[52:53] op_sel_hi:[1,0]
	v_pk_add_f32 v[94:95], v[2:3], v[84:85] neg_lo:[0,1] neg_hi:[0,1]
	v_pk_fma_f32 v[10:11], v[2:3], v[52:53], v[10:11] op_sel:[0,1,0] op_sel_hi:[1,1,1]
	v_pk_add_f32 v[96:97], v[4:5], v[84:85] neg_lo:[0,1] neg_hi:[0,1]
	v_pk_fma_f32 v[10:11], v[4:5], v[54:55], v[10:11] op_sel_hi:[1,0,1]
	v_pk_add_f32 v[98:99], v[6:7], v[84:85] neg_lo:[0,1] neg_hi:[0,1]
	v_pk_fma_f32 v[10:11], v[6:7], v[54:55], v[10:11] op_sel:[0,1,0] op_sel_hi:[1,1,1]
	v_pk_fma_f32 v[0:1], v[92:93], v[56:57], v[84:85] op_sel_hi:[1,0,1]
	v_pk_fma_f32 v[2:3], v[94:95], v[56:57], v[84:85] op_sel:[0,1,0] op_sel_hi:[1,1,1]
	v_pk_fma_f32 v[4:5], v[96:97], v[58:59], v[84:85] op_sel_hi:[1,0,1]
	v_pk_fma_f32 v[6:7], v[98:99], v[58:59], v[84:85] op_sel:[0,1,0] op_sel_hi:[1,1,1]
	ds_read_b128 v[80:83], v135 offset:25344
	ds_read_b128 v[48:51], v134 offset:11264
	ds_read_b128 v[52:55], v134 offset:19456
	s_waitcnt lgkmcnt(8)
	v_pk_add_f32 v[92:93], v[0:1], v[86:87] neg_lo:[0,1] neg_hi:[0,1]
	v_pk_mul_f32 v[12:13], v[0:1], v[60:61] op_sel_hi:[1,0]
	v_pk_add_f32 v[94:95], v[2:3], v[86:87] neg_lo:[0,1] neg_hi:[0,1]
	v_pk_fma_f32 v[12:13], v[2:3], v[60:61], v[12:13] op_sel:[0,1,0] op_sel_hi:[1,1,1]
	v_pk_add_f32 v[96:97], v[4:5], v[86:87] neg_lo:[0,1] neg_hi:[0,1]
	v_pk_fma_f32 v[12:13], v[4:5], v[62:63], v[12:13] op_sel_hi:[1,0,1]
	v_pk_add_f32 v[98:99], v[6:7], v[86:87] neg_lo:[0,1] neg_hi:[0,1]
	v_pk_fma_f32 v[12:13], v[6:7], v[62:63], v[12:13] op_sel:[0,1,0] op_sel_hi:[1,1,1]
	v_pk_fma_f32 v[0:1], v[92:93], v[64:65], v[86:87] op_sel_hi:[1,0,1]
	v_pk_fma_f32 v[2:3], v[94:95], v[64:65], v[86:87] op_sel:[0,1,0] op_sel_hi:[1,1,1]
	v_pk_fma_f32 v[4:5], v[96:97], v[66:67], v[86:87] op_sel_hi:[1,0,1]
	v_pk_fma_f32 v[6:7], v[98:99], v[66:67], v[86:87] op_sel:[0,1,0] op_sel_hi:[1,1,1]
	ds_read_b128 v[56:59], v134 offset:11776
	ds_read_b128 v[60:63], v134 offset:19968
	s_waitcnt lgkmcnt(7)
	v_pk_add_f32 v[92:93], v[0:1], v[88:89] neg_lo:[0,1] neg_hi:[0,1]
	v_pk_mul_f32 v[14:15], v[0:1], v[68:69] op_sel_hi:[1,0]
	v_pk_add_f32 v[94:95], v[2:3], v[88:89] neg_lo:[0,1] neg_hi:[0,1]
	v_pk_fma_f32 v[14:15], v[2:3], v[68:69], v[14:15] op_sel:[0,1,0] op_sel_hi:[1,1,1]
	v_pk_add_f32 v[96:97], v[4:5], v[88:89] neg_lo:[0,1] neg_hi:[0,1]
	v_pk_fma_f32 v[14:15], v[4:5], v[70:71], v[14:15] op_sel_hi:[1,0,1]
	v_pk_add_f32 v[98:99], v[6:7], v[88:89] neg_lo:[0,1] neg_hi:[0,1]
	v_pk_fma_f32 v[14:15], v[6:7], v[70:71], v[14:15] op_sel:[0,1,0] op_sel_hi:[1,1,1]
	v_pk_fma_f32 v[0:1], v[92:93], v[72:73], v[88:89] op_sel_hi:[1,0,1]
	v_pk_fma_f32 v[2:3], v[94:95], v[72:73], v[88:89] op_sel:[0,1,0] op_sel_hi:[1,1,1]
	v_pk_fma_f32 v[4:5], v[96:97], v[74:75], v[88:89] op_sel_hi:[1,0,1]
	v_pk_fma_f32 v[6:7], v[98:99], v[74:75], v[88:89] op_sel:[0,1,0] op_sel_hi:[1,1,1]
	ds_read_b128 v[84:87], v135 offset:25600
	ds_read_b128 v[64:67], v134 offset:12288
	ds_read_b128 v[68:71], v134 offset:20480
	s_waitcnt lgkmcnt(8)
	v_pk_add_f32 v[92:93], v[0:1], v[90:91] neg_lo:[0,1] neg_hi:[0,1]
	v_pk_mul_f32 v[16:17], v[0:1], v[76:77] op_sel_hi:[1,0]
	v_pk_add_f32 v[94:95], v[2:3], v[90:91] neg_lo:[0,1] neg_hi:[0,1]
	v_pk_fma_f32 v[16:17], v[2:3], v[76:77], v[16:17] op_sel:[0,1,0] op_sel_hi:[1,1,1]
	v_pk_add_f32 v[96:97], v[4:5], v[90:91] neg_lo:[0,1] neg_hi:[0,1]
	v_pk_fma_f32 v[16:17], v[4:5], v[78:79], v[16:17] op_sel_hi:[1,0,1]
	v_pk_add_f32 v[98:99], v[6:7], v[90:91] neg_lo:[0,1] neg_hi:[0,1]
	v_pk_fma_f32 v[16:17], v[6:7], v[78:79], v[16:17] op_sel:[0,1,0] op_sel_hi:[1,1,1]
	v_pk_fma_f32 v[0:1], v[92:93], v[40:41], v[90:91] op_sel_hi:[1,0,1]
	v_pk_fma_f32 v[2:3], v[94:95], v[40:41], v[90:91] op_sel:[0,1,0] op_sel_hi:[1,1,1]
	v_pk_fma_f32 v[4:5], v[96:97], v[42:43], v[90:91] op_sel_hi:[1,0,1]
	v_pk_fma_f32 v[6:7], v[98:99], v[42:43], v[90:91] op_sel:[0,1,0] op_sel_hi:[1,1,1]
	ds_read_b128 v[72:75], v134 offset:12800
	ds_read_b128 v[76:79], v134 offset:20992
	s_waitcnt lgkmcnt(7)
	v_pk_add_f32 v[92:93], v[0:1], v[80:81] neg_lo:[0,1] neg_hi:[0,1]
	v_pk_mul_f32 v[18:19], v[0:1], v[44:45] op_sel_hi:[1,0]
	v_pk_add_f32 v[94:95], v[2:3], v[80:81] neg_lo:[0,1] neg_hi:[0,1]
	v_pk_fma_f32 v[18:19], v[2:3], v[44:45], v[18:19] op_sel:[0,1,0] op_sel_hi:[1,1,1]
	v_pk_add_f32 v[96:97], v[4:5], v[80:81] neg_lo:[0,1] neg_hi:[0,1]
	v_pk_fma_f32 v[18:19], v[4:5], v[46:47], v[18:19] op_sel_hi:[1,0,1]
	v_pk_add_f32 v[98:99], v[6:7], v[80:81] neg_lo:[0,1] neg_hi:[0,1]
	v_pk_fma_f32 v[18:19], v[6:7], v[46:47], v[18:19] op_sel:[0,1,0] op_sel_hi:[1,1,1]
	v_pk_fma_f32 v[0:1], v[92:93], v[48:49], v[80:81] op_sel_hi:[1,0,1]
	v_pk_fma_f32 v[2:3], v[94:95], v[48:49], v[80:81] op_sel:[0,1,0] op_sel_hi:[1,1,1]
	v_pk_fma_f32 v[4:5], v[96:97], v[50:51], v[80:81] op_sel_hi:[1,0,1]
	v_pk_fma_f32 v[6:7], v[98:99], v[50:51], v[80:81] op_sel:[0,1,0] op_sel_hi:[1,1,1]
	ds_read_b128 v[88:91], v135 offset:25856
	ds_read_b128 v[40:43], v134 offset:13312
	ds_read_b128 v[44:47], v134 offset:21504
	s_waitcnt lgkmcnt(8)
	v_pk_add_f32 v[92:93], v[0:1], v[82:83] neg_lo:[0,1] neg_hi:[0,1]
	v_pk_mul_f32 v[20:21], v[0:1], v[52:53] op_sel_hi:[1,0]
	v_pk_add_f32 v[94:95], v[2:3], v[82:83] neg_lo:[0,1] neg_hi:[0,1]
	v_pk_fma_f32 v[20:21], v[2:3], v[52:53], v[20:21] op_sel:[0,1,0] op_sel_hi:[1,1,1]
	v_pk_add_f32 v[96:97], v[4:5], v[82:83] neg_lo:[0,1] neg_hi:[0,1]
	v_pk_fma_f32 v[20:21], v[4:5], v[54:55], v[20:21] op_sel_hi:[1,0,1]
	v_pk_add_f32 v[98:99], v[6:7], v[82:83] neg_lo:[0,1] neg_hi:[0,1]
	v_pk_fma_f32 v[20:21], v[6:7], v[54:55], v[20:21] op_sel:[0,1,0] op_sel_hi:[1,1,1]
	v_pk_fma_f32 v[0:1], v[92:93], v[56:57], v[82:83] op_sel_hi:[1,0,1]
	v_pk_fma_f32 v[2:3], v[94:95], v[56:57], v[82:83] op_sel:[0,1,0] op_sel_hi:[1,1,1]
	v_pk_fma_f32 v[4:5], v[96:97], v[58:59], v[82:83] op_sel_hi:[1,0,1]
	v_pk_fma_f32 v[6:7], v[98:99], v[58:59], v[82:83] op_sel:[0,1,0] op_sel_hi:[1,1,1]
	ds_read_b128 v[48:51], v134 offset:13824
	ds_read_b128 v[52:55], v134 offset:22016
	s_waitcnt lgkmcnt(7)
	v_pk_add_f32 v[92:93], v[0:1], v[84:85] neg_lo:[0,1] neg_hi:[0,1]
	v_pk_mul_f32 v[22:23], v[0:1], v[60:61] op_sel_hi:[1,0]
	v_pk_add_f32 v[94:95], v[2:3], v[84:85] neg_lo:[0,1] neg_hi:[0,1]
	v_pk_fma_f32 v[22:23], v[2:3], v[60:61], v[22:23] op_sel:[0,1,0] op_sel_hi:[1,1,1]
	v_pk_add_f32 v[96:97], v[4:5], v[84:85] neg_lo:[0,1] neg_hi:[0,1]
	v_pk_fma_f32 v[22:23], v[4:5], v[62:63], v[22:23] op_sel_hi:[1,0,1]
	v_pk_add_f32 v[98:99], v[6:7], v[84:85] neg_lo:[0,1] neg_hi:[0,1]
	v_pk_fma_f32 v[22:23], v[6:7], v[62:63], v[22:23] op_sel:[0,1,0] op_sel_hi:[1,1,1]
	v_pk_fma_f32 v[0:1], v[92:93], v[64:65], v[84:85] op_sel_hi:[1,0,1]
	v_pk_fma_f32 v[2:3], v[94:95], v[64:65], v[84:85] op_sel:[0,1,0] op_sel_hi:[1,1,1]
	v_pk_fma_f32 v[4:5], v[96:97], v[66:67], v[84:85] op_sel_hi:[1,0,1]
	v_pk_fma_f32 v[6:7], v[98:99], v[66:67], v[84:85] op_sel:[0,1,0] op_sel_hi:[1,1,1]
	ds_read_b128 v[80:83], v135 offset:26112
	ds_read_b128 v[56:59], v134 offset:14336
	ds_read_b128 v[60:63], v134 offset:22528
	s_waitcnt lgkmcnt(8)
	v_pk_add_f32 v[92:93], v[0:1], v[86:87] neg_lo:[0,1] neg_hi:[0,1]
	v_pk_mul_f32 v[24:25], v[0:1], v[68:69] op_sel_hi:[1,0]
	v_pk_add_f32 v[94:95], v[2:3], v[86:87] neg_lo:[0,1] neg_hi:[0,1]
	v_pk_fma_f32 v[24:25], v[2:3], v[68:69], v[24:25] op_sel:[0,1,0] op_sel_hi:[1,1,1]
	v_pk_add_f32 v[96:97], v[4:5], v[86:87] neg_lo:[0,1] neg_hi:[0,1]
	v_pk_fma_f32 v[24:25], v[4:5], v[70:71], v[24:25] op_sel_hi:[1,0,1]
	v_pk_add_f32 v[98:99], v[6:7], v[86:87] neg_lo:[0,1] neg_hi:[0,1]
	v_pk_fma_f32 v[24:25], v[6:7], v[70:71], v[24:25] op_sel:[0,1,0] op_sel_hi:[1,1,1]
	v_pk_fma_f32 v[0:1], v[92:93], v[72:73], v[86:87] op_sel_hi:[1,0,1]
	v_pk_fma_f32 v[2:3], v[94:95], v[72:73], v[86:87] op_sel:[0,1,0] op_sel_hi:[1,1,1]
	v_pk_fma_f32 v[4:5], v[96:97], v[74:75], v[86:87] op_sel_hi:[1,0,1]
	v_pk_fma_f32 v[6:7], v[98:99], v[74:75], v[86:87] op_sel:[0,1,0] op_sel_hi:[1,1,1]
	ds_read_b128 v[64:67], v134 offset:14848
	ds_read_b128 v[68:71], v134 offset:23040
	s_waitcnt lgkmcnt(7)
	v_pk_add_f32 v[92:93], v[0:1], v[88:89] neg_lo:[0,1] neg_hi:[0,1]
	v_pk_mul_f32 v[26:27], v[0:1], v[76:77] op_sel_hi:[1,0]
	v_pk_add_f32 v[94:95], v[2:3], v[88:89] neg_lo:[0,1] neg_hi:[0,1]
	v_pk_fma_f32 v[26:27], v[2:3], v[76:77], v[26:27] op_sel:[0,1,0] op_sel_hi:[1,1,1]
	v_pk_add_f32 v[96:97], v[4:5], v[88:89] neg_lo:[0,1] neg_hi:[0,1]
	v_pk_fma_f32 v[26:27], v[4:5], v[78:79], v[26:27] op_sel_hi:[1,0,1]
	v_pk_add_f32 v[98:99], v[6:7], v[88:89] neg_lo:[0,1] neg_hi:[0,1]
	v_pk_fma_f32 v[26:27], v[6:7], v[78:79], v[26:27] op_sel:[0,1,0] op_sel_hi:[1,1,1]
	v_pk_fma_f32 v[0:1], v[92:93], v[40:41], v[88:89] op_sel_hi:[1,0,1]
	v_pk_fma_f32 v[2:3], v[94:95], v[40:41], v[88:89] op_sel:[0,1,0] op_sel_hi:[1,1,1]
	v_pk_fma_f32 v[4:5], v[96:97], v[42:43], v[88:89] op_sel_hi:[1,0,1]
	v_pk_fma_f32 v[6:7], v[98:99], v[42:43], v[88:89] op_sel:[0,1,0] op_sel_hi:[1,1,1]
	ds_read_b128 v[84:87], v135 offset:26368
	ds_read_b128 v[72:75], v134 offset:15360
	ds_read_b128 v[76:79], v134 offset:23552
	s_waitcnt lgkmcnt(8)
	v_pk_add_f32 v[92:93], v[0:1], v[90:91] neg_lo:[0,1] neg_hi:[0,1]
	v_pk_mul_f32 v[28:29], v[0:1], v[44:45] op_sel_hi:[1,0]
	v_pk_add_f32 v[94:95], v[2:3], v[90:91] neg_lo:[0,1] neg_hi:[0,1]
	v_pk_fma_f32 v[28:29], v[2:3], v[44:45], v[28:29] op_sel:[0,1,0] op_sel_hi:[1,1,1]
	v_pk_add_f32 v[96:97], v[4:5], v[90:91] neg_lo:[0,1] neg_hi:[0,1]
	v_pk_fma_f32 v[28:29], v[4:5], v[46:47], v[28:29] op_sel_hi:[1,0,1]
	v_pk_add_f32 v[98:99], v[6:7], v[90:91] neg_lo:[0,1] neg_hi:[0,1]
	v_pk_fma_f32 v[28:29], v[6:7], v[46:47], v[28:29] op_sel:[0,1,0] op_sel_hi:[1,1,1]
	v_pk_fma_f32 v[0:1], v[92:93], v[48:49], v[90:91] op_sel_hi:[1,0,1]
	v_pk_fma_f32 v[2:3], v[94:95], v[48:49], v[90:91] op_sel:[0,1,0] op_sel_hi:[1,1,1]
	v_pk_fma_f32 v[4:5], v[96:97], v[50:51], v[90:91] op_sel_hi:[1,0,1]
	v_pk_fma_f32 v[6:7], v[98:99], v[50:51], v[90:91] op_sel:[0,1,0] op_sel_hi:[1,1,1]
	ds_read_b128 v[40:43], v134 offset:15872
	ds_read_b128 v[44:47], v134 offset:24064
	s_waitcnt lgkmcnt(7)
	v_pk_add_f32 v[92:93], v[0:1], v[80:81] neg_lo:[0,1] neg_hi:[0,1]
	v_pk_mul_f32 v[30:31], v[0:1], v[52:53] op_sel_hi:[1,0]
	v_pk_add_f32 v[94:95], v[2:3], v[80:81] neg_lo:[0,1] neg_hi:[0,1]
	v_pk_fma_f32 v[30:31], v[2:3], v[52:53], v[30:31] op_sel:[0,1,0] op_sel_hi:[1,1,1]
	v_pk_add_f32 v[96:97], v[4:5], v[80:81] neg_lo:[0,1] neg_hi:[0,1]
	v_pk_fma_f32 v[30:31], v[4:5], v[54:55], v[30:31] op_sel_hi:[1,0,1]
	v_pk_add_f32 v[98:99], v[6:7], v[80:81] neg_lo:[0,1] neg_hi:[0,1]
	v_pk_fma_f32 v[30:31], v[6:7], v[54:55], v[30:31] op_sel:[0,1,0] op_sel_hi:[1,1,1]
	v_pk_fma_f32 v[0:1], v[92:93], v[56:57], v[80:81] op_sel_hi:[1,0,1]
	v_pk_fma_f32 v[2:3], v[94:95], v[56:57], v[80:81] op_sel:[0,1,0] op_sel_hi:[1,1,1]
	v_pk_fma_f32 v[4:5], v[96:97], v[58:59], v[80:81] op_sel_hi:[1,0,1]
	v_pk_fma_f32 v[6:7], v[98:99], v[58:59], v[80:81] op_sel:[0,1,0] op_sel_hi:[1,1,1]
	s_waitcnt lgkmcnt(5)
	v_pk_add_f32 v[92:93], v[0:1], v[82:83] neg_lo:[0,1] neg_hi:[0,1]
	v_pk_mul_f32 v[32:33], v[0:1], v[60:61] op_sel_hi:[1,0]
	v_pk_add_f32 v[94:95], v[2:3], v[82:83] neg_lo:[0,1] neg_hi:[0,1]
	v_pk_fma_f32 v[32:33], v[2:3], v[60:61], v[32:33] op_sel:[0,1,0] op_sel_hi:[1,1,1]
	v_pk_add_f32 v[96:97], v[4:5], v[82:83] neg_lo:[0,1] neg_hi:[0,1]
	v_pk_fma_f32 v[32:33], v[4:5], v[62:63], v[32:33] op_sel_hi:[1,0,1]
	v_pk_add_f32 v[98:99], v[6:7], v[82:83] neg_lo:[0,1] neg_hi:[0,1]
	v_pk_fma_f32 v[32:33], v[6:7], v[62:63], v[32:33] op_sel:[0,1,0] op_sel_hi:[1,1,1]
	v_pk_fma_f32 v[0:1], v[92:93], v[64:65], v[82:83] op_sel_hi:[1,0,1]
	v_pk_fma_f32 v[2:3], v[94:95], v[64:65], v[82:83] op_sel:[0,1,0] op_sel_hi:[1,1,1]
	v_pk_fma_f32 v[4:5], v[96:97], v[66:67], v[82:83] op_sel_hi:[1,0,1]
	v_pk_fma_f32 v[6:7], v[98:99], v[66:67], v[82:83] op_sel:[0,1,0] op_sel_hi:[1,1,1]
	s_waitcnt lgkmcnt(2)
	v_pk_add_f32 v[92:93], v[0:1], v[84:85] neg_lo:[0,1] neg_hi:[0,1]
	v_pk_mul_f32 v[34:35], v[0:1], v[68:69] op_sel_hi:[1,0]
	v_pk_add_f32 v[94:95], v[2:3], v[84:85] neg_lo:[0,1] neg_hi:[0,1]
	v_pk_fma_f32 v[34:35], v[2:3], v[68:69], v[34:35] op_sel:[0,1,0] op_sel_hi:[1,1,1]
	v_pk_add_f32 v[96:97], v[4:5], v[84:85] neg_lo:[0,1] neg_hi:[0,1]
	v_pk_fma_f32 v[34:35], v[4:5], v[70:71], v[34:35] op_sel_hi:[1,0,1]
	v_pk_add_f32 v[98:99], v[6:7], v[84:85] neg_lo:[0,1] neg_hi:[0,1]
	v_pk_fma_f32 v[34:35], v[6:7], v[70:71], v[34:35] op_sel:[0,1,0] op_sel_hi:[1,1,1]
	v_pk_fma_f32 v[0:1], v[92:93], v[72:73], v[84:85] op_sel_hi:[1,0,1]
	v_pk_fma_f32 v[2:3], v[94:95], v[72:73], v[84:85] op_sel:[0,1,0] op_sel_hi:[1,1,1]
	v_pk_fma_f32 v[4:5], v[96:97], v[74:75], v[84:85] op_sel_hi:[1,0,1]
	v_pk_fma_f32 v[6:7], v[98:99], v[74:75], v[84:85] op_sel:[0,1,0] op_sel_hi:[1,1,1]
	s_waitcnt lgkmcnt(0)
	v_pk_add_f32 v[92:93], v[0:1], v[86:87] neg_lo:[0,1] neg_hi:[0,1]
	v_pk_mul_f32 v[36:37], v[0:1], v[76:77] op_sel_hi:[1,0]
	v_pk_add_f32 v[94:95], v[2:3], v[86:87] neg_lo:[0,1] neg_hi:[0,1]
	v_pk_fma_f32 v[36:37], v[2:3], v[76:77], v[36:37] op_sel:[0,1,0] op_sel_hi:[1,1,1]
	v_pk_add_f32 v[96:97], v[4:5], v[86:87] neg_lo:[0,1] neg_hi:[0,1]
	v_pk_fma_f32 v[36:37], v[4:5], v[78:79], v[36:37] op_sel_hi:[1,0,1]
	v_pk_add_f32 v[98:99], v[6:7], v[86:87] neg_lo:[0,1] neg_hi:[0,1]
	v_pk_fma_f32 v[36:37], v[6:7], v[78:79], v[36:37] op_sel:[0,1,0] op_sel_hi:[1,1,1]
	v_pk_fma_f32 v[0:1], v[92:93], v[40:41], v[86:87] op_sel_hi:[1,0,1]
	v_pk_fma_f32 v[2:3], v[94:95], v[40:41], v[86:87] op_sel:[0,1,0] op_sel_hi:[1,1,1]
	v_pk_fma_f32 v[4:5], v[96:97], v[42:43], v[86:87] op_sel_hi:[1,0,1]
	v_pk_fma_f32 v[6:7], v[98:99], v[42:43], v[86:87] op_sel:[0,1,0] op_sel_hi:[1,1,1]
	v_pk_mul_f32 v[38:39], v[0:1], v[44:45] op_sel_hi:[1,0]
	v_pk_fma_f32 v[38:39], v[2:3], v[44:45], v[38:39] op_sel:[0,1,0] op_sel_hi:[1,1,1]
	v_pk_fma_f32 v[38:39], v[4:5], v[46:47], v[38:39] op_sel_hi:[1,0,1]
	v_pk_fma_f32 v[38:39], v[6:7], v[46:47], v[38:39] op_sel:[0,1,0] op_sel_hi:[1,1,1]
	s_nop 1
	v_permlane16_swap_b32_e32 v8, v24
	v_permlane16_swap_b32_e32 v9, v25
	v_permlane16_swap_b32_e32 v10, v26
	v_permlane16_swap_b32_e32 v11, v27
	v_permlane16_swap_b32_e32 v12, v28
	v_permlane16_swap_b32_e32 v13, v29
	v_permlane16_swap_b32_e32 v14, v30
	v_permlane16_swap_b32_e32 v15, v31
	v_permlane16_swap_b32_e32 v16, v32
	v_permlane16_swap_b32_e32 v17, v33
	v_permlane16_swap_b32_e32 v18, v34
	v_permlane16_swap_b32_e32 v19, v35
	v_permlane16_swap_b32_e32 v20, v36
	v_permlane16_swap_b32_e32 v21, v37
	v_permlane16_swap_b32_e32 v22, v38
	v_permlane16_swap_b32_e32 v23, v39
	v_pk_add_f32 v[8:9], v[8:9], v[24:25]
	v_pk_add_f32 v[10:11], v[10:11], v[26:27]
	v_pk_add_f32 v[12:13], v[12:13], v[28:29]
	v_pk_add_f32 v[14:15], v[14:15], v[30:31]
	v_pk_add_f32 v[16:17], v[16:17], v[32:33]
	v_pk_add_f32 v[18:19], v[18:19], v[34:35]
	v_pk_add_f32 v[20:21], v[20:21], v[36:37]
	v_pk_add_f32 v[22:23], v[22:23], v[38:39]
	s_nop 1
	v_permlane32_swap_b32_e32 v8, v16
	v_permlane32_swap_b32_e32 v9, v17
	v_permlane32_swap_b32_e32 v10, v18
	v_permlane32_swap_b32_e32 v11, v19
	v_permlane32_swap_b32_e32 v12, v20
	v_permlane32_swap_b32_e32 v13, v21
	v_permlane32_swap_b32_e32 v14, v22
	v_permlane32_swap_b32_e32 v15, v23
	v_pk_add_f32 v[8:9], v[8:9], v[16:17]
	v_pk_add_f32 v[10:11], v[10:11], v[18:19]
	v_pk_add_f32 v[12:13], v[12:13], v[20:21]
	v_pk_add_f32 v[14:15], v[14:15], v[22:23]
	ds_write2_b32 v141, v8, v9 offset1:16
	ds_write2_b32 v142, v10, v11 offset1:16
	ds_write2_b32 v143, v12, v13 offset1:16
	ds_write2_b32 v144, v14, v15 offset1:16
	s_sub_u32 s15, s15, 1
	s_waitcnt lgkmcnt(0)
	s_barrier
	ds_read2_b32 v[104:105], v149 offset0:0 offset1:32
	ds_read2_b32 v[106:107], v149 offset0:64 offset1:96
	ds_read2_b32 v[108:109], v149 offset0:128 offset1:160
	ds_read2_b32 v[110:111], v149 offset0:192 offset1:224
	s_waitcnt vmcnt(7)
	v_lshlrev_b32_e32 v180, 16, v122
	v_and_b32_e32 v181, s69, v122
	v_lshlrev_b32_e32 v182, 16, v123
	v_and_b32_e32 v183, s69, v123
	s_cmp_eq_u32 s14, 0
	s_cbranch_scc1 .Lgla_st_join_3
	v_mul_f32_e32 v180, 0x3fb8aa3b, v180
	v_mul_f32_e32 v181, 0x3fb8aa3b, v181
	v_mul_f32_e32 v182, 0x3fb8aa3b, v182
	v_mul_f32_e32 v183, 0x3fb8aa3b, v183
	v_exp_f32_e32 v180, v180
	v_exp_f32_e32 v181, v181
	v_exp_f32_e32 v182, v182
	v_exp_f32_e32 v183, v183
.Lgla_st_join_3:
	v_lshlrev_b32_e32 v184, 16, v120
	v_and_b32_e32 v185, s69, v120
	v_lshlrev_b32_e32 v186, 16, v121
	v_and_b32_e32 v187, s69, v121
	v_lshlrev_b32_e32 v188, 16, v124
	v_and_b32_e32 v189, s69, v124
	ds_write_b128 v139, v[180:183] offset:8192
	ds_write_b128 v139, v[184:187] offset:16384
	ds_write2_b32 v140, v188, v189 offset1:4
	global_load_dwordx2 v[120:121], v130, s[8:9]
	global_load_dwordx2 v[122:123], v130, s[8:9] offset:1024
	global_load_dword v124, v131, s[8:9]
	s_add_u32 s8, s8, 0x34000
	s_addc_u32 s9, s9, 0
	s_waitcnt lgkmcnt(3)
	v_add_f32_e32 v112, v104, v105
	v_add_f32_e32 v112, v112, v106
	v_add_f32_e32 v112, v112, v107
	v_add_f32_e32 v112, v112, v108
	v_add_f32_e32 v112, v112, v109
	v_add_f32_e32 v112, v112, v110
	v_add_f32_e32 v112, v112, v111
	v_mul_f32_e32 v113, v112, v112
	v_cvt_pk_bf16_f32 v116, v112, v129
	v_mov_b32_e32 v117, v112
	v_mov_b32_e32 v118, v113
	global_store_short v132, v116, s[10:11]
	s_nop 1
	v_permlane16_swap_b32_e32 v112, v117
	v_permlane16_swap_b32_e32 v113, v118
	v_add_f32_e32 v112, v112, v117
	v_add_f32_e32 v113, v113, v118
	s_nop 1
	v_add_f32_dpp v112, v112, v112 row_ror:8 row_mask:0xf bank_mask:0xf
	v_add_f32_dpp v113, v113, v113 row_ror:8 row_mask:0xf bank_mask:0xf
	s_nop 1
	v_add_f32_dpp v112, v112, v112 row_ror:4 row_mask:0xf bank_mask:0xf
	v_add_f32_dpp v113, v113, v113 row_ror:4 row_mask:0xf bank_mask:0xf
	s_nop 1
	v_add_f32_dpp v112, v112, v112 row_ror:2 row_mask:0xf bank_mask:0xf
	v_add_f32_dpp v113, v113, v113 row_ror:2 row_mask:0xf bank_mask:0xf
	s_nop 1
	v_add_f32_dpp v112, v112, v112 row_ror:1 row_mask:0xf bank_mask:0xf
	v_add_f32_dpp v113, v113, v113 row_ror:1 row_mask:0xf bank_mask:0xf
	v_mov_b32_e32 v114, 0
	v_mov_b32_e32 v115, 0
	s_mov_b64 exec, s[18:19]
	global_store_dwordx4 v133, v[112:115], s[12:13]
	s_mov_b64 exec, -1
	s_cmp_eq_u32 s15, 512
	s_cselect_b32 s20, 0, 0x10000
	s_cselect_b32 s21, 0, 0x1000
	s_add_u32 s10, s10, s20
	s_addc_u32 s11, s11, 0
	s_add_u32 s12, s12, s21
	s_addc_u32 s13, s13, 0
	ds_read_b128 v[80:83], v135 offset:57344
	ds_read_b128 v[40:43], v134 offset:40960
	ds_read_b128 v[44:47], v134 offset:49152
	ds_read_b128 v[48:51], v134 offset:41472
	ds_read_b128 v[52:55], v134 offset:49664
	ds_read_b128 v[84:87], v135 offset:57600
	ds_read_b128 v[56:59], v134 offset:41984
	ds_read_b128 v[60:63], v134 offset:50176
	ds_read_b128 v[64:67], v134 offset:42496
	ds_read_b128 v[68:71], v134 offset:50688
	s_waitcnt lgkmcnt(7)
	v_pk_add_f32 v[92:93], v[0:1], v[80:81] neg_lo:[0,1] neg_hi:[0,1]
	v_pk_add_f32 v[94:95], v[2:3], v[80:81] neg_lo:[0,1] neg_hi:[0,1]
	v_pk_add_f32 v[96:97], v[4:5], v[80:81] neg_lo:[0,1] neg_hi:[0,1]
	v_pk_add_f32 v[98:99], v[6:7], v[80:81] neg_lo:[0,1] neg_hi:[0,1]
	v_pk_fma_f32 v[0:1], v[92:93], v[40:41], v[80:81] op_sel_hi:[1,0,1]
	v_pk_fma_f32 v[2:3], v[94:95], v[40:41], v[80:81] op_sel:[0,1,0] op_sel_hi:[1,1,1]
	v_pk_fma_f32 v[4:5], v[96:97], v[42:43], v[80:81] op_sel_hi:[1,0,1]
	v_pk_fma_f32 v[6:7], v[98:99], v[42:43], v[80:81] op_sel:[0,1,0] op_sel_hi:[1,1,1]
	ds_read_b128 v[88:91], v135 offset:57856
	ds_read_b128 v[72:75], v134 offset:43008
	ds_read_b128 v[76:79], v134 offset:51200
	s_waitcnt lgkmcnt(8)
	v_pk_add_f32 v[92:93], v[0:1], v[82:83] neg_lo:[0,1] neg_hi:[0,1]
	v_pk_mul_f32 v[8:9], v[0:1], v[44:45] op_sel_hi:[1,0]
	v_pk_add_f32 v[94:95], v[2:3], v[82:83] neg_lo:[0,1] neg_hi:[0,1]
	v_pk_fma_f32 v[8:9], v[2:3], v[44:45], v[8:9] op_sel:[0,1,0] op_sel_hi:[1,1,1]
	v_pk_add_f32 v[96:97], v[4:5], v[82:83] neg_lo:[0,1] neg_hi:[0,1]
	v_pk_fma_f32 v[8:9], v[4:5], v[46:47], v[8:9] op_sel_hi:[1,0,1]
	v_pk_add_f32 v[98:99], v[6:7], v[82:83] neg_lo:[0,1] neg_hi:[0,1]
	v_pk_fma_f32 v[8:9], v[6:7], v[46:47], v[8:9] op_sel:[0,1,0] op_sel_hi:[1,1,1]
	v_pk_fma_f32 v[0:1], v[92:93], v[48:49], v[82:83] op_sel_hi:[1,0,1]
	v_pk_fma_f32 v[2:3], v[94:95], v[48:49], v[82:83] op_sel:[0,1,0] op_sel_hi:[1,1,1]
	v_pk_fma_f32 v[4:5], v[96:97], v[50:51], v[82:83] op_sel_hi:[1,0,1]
	v_pk_fma_f32 v[6:7], v[98:99], v[50:51], v[82:83] op_sel:[0,1,0] op_sel_hi:[1,1,1]
	ds_read_b128 v[40:43], v134 offset:43520
	ds_read_b128 v[44:47], v134 offset:51712
	s_waitcnt lgkmcnt(7)
	v_pk_add_f32 v[92:93], v[0:1], v[84:85] neg_lo:[0,1] neg_hi:[0,1]
	v_pk_mul_f32 v[10:11], v[0:1], v[52:53] op_sel_hi:[1,0]
	v_pk_add_f32 v[94:95], v[2:3], v[84:85] neg_lo:[0,1] neg_hi:[0,1]
	v_pk_fma_f32 v[10:11], v[2:3], v[52:53], v[10:11] op_sel:[0,1,0] op_sel_hi:[1,1,1]
	v_pk_add_f32 v[96:97], v[4:5], v[84:85] neg_lo:[0,1] neg_hi:[0,1]
	v_pk_fma_f32 v[10:11], v[4:5], v[54:55], v[10:11] op_sel_hi:[1,0,1]
	v_pk_add_f32 v[98:99], v[6:7], v[84:85] neg_lo:[0,1] neg_hi:[0,1]
	v_pk_fma_f32 v[10:11], v[6:7], v[54:55], v[10:11] op_sel:[0,1,0] op_sel_hi:[1,1,1]
	v_pk_fma_f32 v[0:1], v[92:93], v[56:57], v[84:85] op_sel_hi:[1,0,1]
	v_pk_fma_f32 v[2:3], v[94:95], v[56:57], v[84:85] op_sel:[0,1,0] op_sel_hi:[1,1,1]
	v_pk_fma_f32 v[4:5], v[96:97], v[58:59], v[84:85] op_sel_hi:[1,0,1]
	v_pk_fma_f32 v[6:7], v[98:99], v[58:59], v[84:85] op_sel:[0,1,0] op_sel_hi:[1,1,1]
	ds_read_b128 v[80:83], v135 offset:58112
	ds_read_b128 v[48:51], v134 offset:44032
	ds_read_b128 v[52:55], v134 offset:52224
	s_waitcnt lgkmcnt(8)
	v_pk_add_f32 v[92:93], v[0:1], v[86:87] neg_lo:[0,1] neg_hi:[0,1]
	v_pk_mul_f32 v[12:13], v[0:1], v[60:61] op_sel_hi:[1,0]
	v_pk_add_f32 v[94:95], v[2:3], v[86:87] neg_lo:[0,1] neg_hi:[0,1]
	v_pk_fma_f32 v[12:13], v[2:3], v[60:61], v[12:13] op_sel:[0,1,0] op_sel_hi:[1,1,1]
	v_pk_add_f32 v[96:97], v[4:5], v[86:87] neg_lo:[0,1] neg_hi:[0,1]
	v_pk_fma_f32 v[12:13], v[4:5], v[62:63], v[12:13] op_sel_hi:[1,0,1]
	v_pk_add_f32 v[98:99], v[6:7], v[86:87] neg_lo:[0,1] neg_hi:[0,1]
	v_pk_fma_f32 v[12:13], v[6:7], v[62:63], v[12:13] op_sel:[0,1,0] op_sel_hi:[1,1,1]
	v_pk_fma_f32 v[0:1], v[92:93], v[64:65], v[86:87] op_sel_hi:[1,0,1]
	v_pk_fma_f32 v[2:3], v[94:95], v[64:65], v[86:87] op_sel:[0,1,0] op_sel_hi:[1,1,1]
	v_pk_fma_f32 v[4:5], v[96:97], v[66:67], v[86:87] op_sel_hi:[1,0,1]
	v_pk_fma_f32 v[6:7], v[98:99], v[66:67], v[86:87] op_sel:[0,1,0] op_sel_hi:[1,1,1]
	ds_read_b128 v[56:59], v134 offset:44544
	ds_read_b128 v[60:63], v134 offset:52736
	s_waitcnt lgkmcnt(7)
	v_pk_add_f32 v[92:93], v[0:1], v[88:89] neg_lo:[0,1] neg_hi:[0,1]
	v_pk_mul_f32 v[14:15], v[0:1], v[68:69] op_sel_hi:[1,0]
	v_pk_add_f32 v[94:95], v[2:3], v[88:89] neg_lo:[0,1] neg_hi:[0,1]
	v_pk_fma_f32 v[14:15], v[2:3], v[68:69], v[14:15] op_sel:[0,1,0] op_sel_hi:[1,1,1]
	v_pk_add_f32 v[96:97], v[4:5], v[88:89] neg_lo:[0,1] neg_hi:[0,1]
	v_pk_fma_f32 v[14:15], v[4:5], v[70:71], v[14:15] op_sel_hi:[1,0,1]
	v_pk_add_f32 v[98:99], v[6:7], v[88:89] neg_lo:[0,1] neg_hi:[0,1]
	v_pk_fma_f32 v[14:15], v[6:7], v[70:71], v[14:15] op_sel:[0,1,0] op_sel_hi:[1,1,1]
	v_pk_fma_f32 v[0:1], v[92:93], v[72:73], v[88:89] op_sel_hi:[1,0,1]
	v_pk_fma_f32 v[2:3], v[94:95], v[72:73], v[88:89] op_sel:[0,1,0] op_sel_hi:[1,1,1]
	v_pk_fma_f32 v[4:5], v[96:97], v[74:75], v[88:89] op_sel_hi:[1,0,1]
	v_pk_fma_f32 v[6:7], v[98:99], v[74:75], v[88:89] op_sel:[0,1,0] op_sel_hi:[1,1,1]
	ds_read_b128 v[84:87], v135 offset:58368
	ds_read_b128 v[64:67], v134 offset:45056
	ds_read_b128 v[68:71], v134 offset:53248
	s_waitcnt lgkmcnt(8)
	v_pk_add_f32 v[92:93], v[0:1], v[90:91] neg_lo:[0,1] neg_hi:[0,1]
	v_pk_mul_f32 v[16:17], v[0:1], v[76:77] op_sel_hi:[1,0]
	v_pk_add_f32 v[94:95], v[2:3], v[90:91] neg_lo:[0,1] neg_hi:[0,1]
	v_pk_fma_f32 v[16:17], v[2:3], v[76:77], v[16:17] op_sel:[0,1,0] op_sel_hi:[1,1,1]
	v_pk_add_f32 v[96:97], v[4:5], v[90:91] neg_lo:[0,1] neg_hi:[0,1]
	v_pk_fma_f32 v[16:17], v[4:5], v[78:79], v[16:17] op_sel_hi:[1,0,1]
	v_pk_add_f32 v[98:99], v[6:7], v[90:91] neg_lo:[0,1] neg_hi:[0,1]
	v_pk_fma_f32 v[16:17], v[6:7], v[78:79], v[16:17] op_sel:[0,1,0] op_sel_hi:[1,1,1]
	v_pk_fma_f32 v[0:1], v[92:93], v[40:41], v[90:91] op_sel_hi:[1,0,1]
	v_pk_fma_f32 v[2:3], v[94:95], v[40:41], v[90:91] op_sel:[0,1,0] op_sel_hi:[1,1,1]
	v_pk_fma_f32 v[4:5], v[96:97], v[42:43], v[90:91] op_sel_hi:[1,0,1]
	v_pk_fma_f32 v[6:7], v[98:99], v[42:43], v[90:91] op_sel:[0,1,0] op_sel_hi:[1,1,1]
	ds_read_b128 v[72:75], v134 offset:45568
	ds_read_b128 v[76:79], v134 offset:53760
	s_waitcnt lgkmcnt(7)
	v_pk_add_f32 v[92:93], v[0:1], v[80:81] neg_lo:[0,1] neg_hi:[0,1]
	v_pk_mul_f32 v[18:19], v[0:1], v[44:45] op_sel_hi:[1,0]
	v_pk_add_f32 v[94:95], v[2:3], v[80:81] neg_lo:[0,1] neg_hi:[0,1]
	v_pk_fma_f32 v[18:19], v[2:3], v[44:45], v[18:19] op_sel:[0,1,0] op_sel_hi:[1,1,1]
	v_pk_add_f32 v[96:97], v[4:5], v[80:81] neg_lo:[0,1] neg_hi:[0,1]
	v_pk_fma_f32 v[18:19], v[4:5], v[46:47], v[18:19] op_sel_hi:[1,0,1]
	v_pk_add_f32 v[98:99], v[6:7], v[80:81] neg_lo:[0,1] neg_hi:[0,1]
	v_pk_fma_f32 v[18:19], v[6:7], v[46:47], v[18:19] op_sel:[0,1,0] op_sel_hi:[1,1,1]
	v_pk_fma_f32 v[0:1], v[92:93], v[48:49], v[80:81] op_sel_hi:[1,0,1]
	v_pk_fma_f32 v[2:3], v[94:95], v[48:49], v[80:81] op_sel:[0,1,0] op_sel_hi:[1,1,1]
	v_pk_fma_f32 v[4:5], v[96:97], v[50:51], v[80:81] op_sel_hi:[1,0,1]
	v_pk_fma_f32 v[6:7], v[98:99], v[50:51], v[80:81] op_sel:[0,1,0] op_sel_hi:[1,1,1]
	ds_read_b128 v[88:91], v135 offset:58624
	ds_read_b128 v[40:43], v134 offset:46080
	ds_read_b128 v[44:47], v134 offset:54272
	s_waitcnt lgkmcnt(8)
	v_pk_add_f32 v[92:93], v[0:1], v[82:83] neg_lo:[0,1] neg_hi:[0,1]
	v_pk_mul_f32 v[20:21], v[0:1], v[52:53] op_sel_hi:[1,0]
	v_pk_add_f32 v[94:95], v[2:3], v[82:83] neg_lo:[0,1] neg_hi:[0,1]
	v_pk_fma_f32 v[20:21], v[2:3], v[52:53], v[20:21] op_sel:[0,1,0] op_sel_hi:[1,1,1]
	v_pk_add_f32 v[96:97], v[4:5], v[82:83] neg_lo:[0,1] neg_hi:[0,1]
	v_pk_fma_f32 v[20:21], v[4:5], v[54:55], v[20:21] op_sel_hi:[1,0,1]
	v_pk_add_f32 v[98:99], v[6:7], v[82:83] neg_lo:[0,1] neg_hi:[0,1]
	v_pk_fma_f32 v[20:21], v[6:7], v[54:55], v[20:21] op_sel:[0,1,0] op_sel_hi:[1,1,1]
	v_pk_fma_f32 v[0:1], v[92:93], v[56:57], v[82:83] op_sel_hi:[1,0,1]
	v_pk_fma_f32 v[2:3], v[94:95], v[56:57], v[82:83] op_sel:[0,1,0] op_sel_hi:[1,1,1]
	v_pk_fma_f32 v[4:5], v[96:97], v[58:59], v[82:83] op_sel_hi:[1,0,1]
	v_pk_fma_f32 v[6:7], v[98:99], v[58:59], v[82:83] op_sel:[0,1,0] op_sel_hi:[1,1,1]
	ds_read_b128 v[48:51], v134 offset:46592
	ds_read_b128 v[52:55], v134 offset:54784
	s_waitcnt lgkmcnt(7)
	v_pk_add_f32 v[92:93], v[0:1], v[84:85] neg_lo:[0,1] neg_hi:[0,1]
	v_pk_mul_f32 v[22:23], v[0:1], v[60:61] op_sel_hi:[1,0]
	v_pk_add_f32 v[94:95], v[2:3], v[84:85] neg_lo:[0,1] neg_hi:[0,1]
	v_pk_fma_f32 v[22:23], v[2:3], v[60:61], v[22:23] op_sel:[0,1,0] op_sel_hi:[1,1,1]
	v_pk_add_f32 v[96:97], v[4:5], v[84:85] neg_lo:[0,1] neg_hi:[0,1]
	v_pk_fma_f32 v[22:23], v[4:5], v[62:63], v[22:23] op_sel_hi:[1,0,1]
	v_pk_add_f32 v[98:99], v[6:7], v[84:85] neg_lo:[0,1] neg_hi:[0,1]
	v_pk_fma_f32 v[22:23], v[6:7], v[62:63], v[22:23] op_sel:[0,1,0] op_sel_hi:[1,1,1]
	v_pk_fma_f32 v[0:1], v[92:93], v[64:65], v[84:85] op_sel_hi:[1,0,1]
	v_pk_fma_f32 v[2:3], v[94:95], v[64:65], v[84:85] op_sel:[0,1,0] op_sel_hi:[1,1,1]
	v_pk_fma_f32 v[4:5], v[96:97], v[66:67], v[84:85] op_sel_hi:[1,0,1]
	v_pk_fma_f32 v[6:7], v[98:99], v[66:67], v[84:85] op_sel:[0,1,0] op_sel_hi:[1,1,1]
	ds_read_b128 v[80:83], v135 offset:58880
	ds_read_b128 v[56:59], v134 offset:47104
	ds_read_b128 v[60:63], v134 offset:55296
	s_waitcnt lgkmcnt(8)
	v_pk_add_f32 v[92:93], v[0:1], v[86:87] neg_lo:[0,1] neg_hi:[0,1]
	v_pk_mul_f32 v[24:25], v[0:1], v[68:69] op_sel_hi:[1,0]
	v_pk_add_f32 v[94:95], v[2:3], v[86:87] neg_lo:[0,1] neg_hi:[0,1]
	v_pk_fma_f32 v[24:25], v[2:3], v[68:69], v[24:25] op_sel:[0,1,0] op_sel_hi:[1,1,1]
	v_pk_add_f32 v[96:97], v[4:5], v[86:87] neg_lo:[0,1] neg_hi:[0,1]
	v_pk_fma_f32 v[24:25], v[4:5], v[70:71], v[24:25] op_sel_hi:[1,0,1]
	v_pk_add_f32 v[98:99], v[6:7], v[86:87] neg_lo:[0,1] neg_hi:[0,1]
	v_pk_fma_f32 v[24:25], v[6:7], v[70:71], v[24:25] op_sel:[0,1,0] op_sel_hi:[1,1,1]
	v_pk_fma_f32 v[0:1], v[92:93], v[72:73], v[86:87] op_sel_hi:[1,0,1]
	v_pk_fma_f32 v[2:3], v[94:95], v[72:73], v[86:87] op_sel:[0,1,0] op_sel_hi:[1,1,1]
	v_pk_fma_f32 v[4:5], v[96:97], v[74:75], v[86:87] op_sel_hi:[1,0,1]
	v_pk_fma_f32 v[6:7], v[98:99], v[74:75], v[86:87] op_sel:[0,1,0] op_sel_hi:[1,1,1]
	ds_read_b128 v[64:67], v134 offset:47616
	ds_read_b128 v[68:71], v134 offset:55808
	s_waitcnt lgkmcnt(7)
	v_pk_add_f32 v[92:93], v[0:1], v[88:89] neg_lo:[0,1] neg_hi:[0,1]
	v_pk_mul_f32 v[26:27], v[0:1], v[76:77] op_sel_hi:[1,0]
	v_pk_add_f32 v[94:95], v[2:3], v[88:89] neg_lo:[0,1] neg_hi:[0,1]
	v_pk_fma_f32 v[26:27], v[2:3], v[76:77], v[26:27] op_sel:[0,1,0] op_sel_hi:[1,1,1]
	v_pk_add_f32 v[96:97], v[4:5], v[88:89] neg_lo:[0,1] neg_hi:[0,1]
	v_pk_fma_f32 v[26:27], v[4:5], v[78:79], v[26:27] op_sel_hi:[1,0,1]
	v_pk_add_f32 v[98:99], v[6:7], v[88:89] neg_lo:[0,1] neg_hi:[0,1]
	v_pk_fma_f32 v[26:27], v[6:7], v[78:79], v[26:27] op_sel:[0,1,0] op_sel_hi:[1,1,1]
	v_pk_fma_f32 v[0:1], v[92:93], v[40:41], v[88:89] op_sel_hi:[1,0,1]
	v_pk_fma_f32 v[2:3], v[94:95], v[40:41], v[88:89] op_sel:[0,1,0] op_sel_hi:[1,1,1]
	v_pk_fma_f32 v[4:5], v[96:97], v[42:43], v[88:89] op_sel_hi:[1,0,1]
	v_pk_fma_f32 v[6:7], v[98:99], v[42:43], v[88:89] op_sel:[0,1,0] op_sel_hi:[1,1,1]
	ds_read_b128 v[84:87], v135 offset:59136
	ds_read_b128 v[72:75], v134 offset:48128
	ds_read_b128 v[76:79], v134 offset:56320
	s_waitcnt lgkmcnt(8)
	v_pk_add_f32 v[92:93], v[0:1], v[90:91] neg_lo:[0,1] neg_hi:[0,1]
	v_pk_mul_f32 v[28:29], v[0:1], v[44:45] op_sel_hi:[1,0]
	v_pk_add_f32 v[94:95], v[2:3], v[90:91] neg_lo:[0,1] neg_hi:[0,1]
	v_pk_fma_f32 v[28:29], v[2:3], v[44:45], v[28:29] op_sel:[0,1,0] op_sel_hi:[1,1,1]
	v_pk_add_f32 v[96:97], v[4:5], v[90:91] neg_lo:[0,1] neg_hi:[0,1]
	v_pk_fma_f32 v[28:29], v[4:5], v[46:47], v[28:29] op_sel_hi:[1,0,1]
	v_pk_add_f32 v[98:99], v[6:7], v[90:91] neg_lo:[0,1] neg_hi:[0,1]
	v_pk_fma_f32 v[28:29], v[6:7], v[46:47], v[28:29] op_sel:[0,1,0] op_sel_hi:[1,1,1]
	v_pk_fma_f32 v[0:1], v[92:93], v[48:49], v[90:91] op_sel_hi:[1,0,1]
	v_pk_fma_f32 v[2:3], v[94:95], v[48:49], v[90:91] op_sel:[0,1,0] op_sel_hi:[1,1,1]
	v_pk_fma_f32 v[4:5], v[96:97], v[50:51], v[90:91] op_sel_hi:[1,0,1]
	v_pk_fma_f32 v[6:7], v[98:99], v[50:51], v[90:91] op_sel:[0,1,0] op_sel_hi:[1,1,1]
	ds_read_b128 v[40:43], v134 offset:48640
	ds_read_b128 v[44:47], v134 offset:56832
	s_waitcnt lgkmcnt(7)
	v_pk_add_f32 v[92:93], v[0:1], v[80:81] neg_lo:[0,1] neg_hi:[0,1]
	v_pk_mul_f32 v[30:31], v[0:1], v[52:53] op_sel_hi:[1,0]
	v_pk_add_f32 v[94:95], v[2:3], v[80:81] neg_lo:[0,1] neg_hi:[0,1]
	v_pk_fma_f32 v[30:31], v[2:3], v[52:53], v[30:31] op_sel:[0,1,0] op_sel_hi:[1,1,1]
	v_pk_add_f32 v[96:97], v[4:5], v[80:81] neg_lo:[0,1] neg_hi:[0,1]
	v_pk_fma_f32 v[30:31], v[4:5], v[54:55], v[30:31] op_sel_hi:[1,0,1]
	v_pk_add_f32 v[98:99], v[6:7], v[80:81] neg_lo:[0,1] neg_hi:[0,1]
	v_pk_fma_f32 v[30:31], v[6:7], v[54:55], v[30:31] op_sel:[0,1,0] op_sel_hi:[1,1,1]
	v_pk_fma_f32 v[0:1], v[92:93], v[56:57], v[80:81] op_sel_hi:[1,0,1]
	v_pk_fma_f32 v[2:3], v[94:95], v[56:57], v[80:81] op_sel:[0,1,0] op_sel_hi:[1,1,1]
	v_pk_fma_f32 v[4:5], v[96:97], v[58:59], v[80:81] op_sel_hi:[1,0,1]
	v_pk_fma_f32 v[6:7], v[98:99], v[58:59], v[80:81] op_sel:[0,1,0] op_sel_hi:[1,1,1]
	s_waitcnt lgkmcnt(5)
	v_pk_add_f32 v[92:93], v[0:1], v[82:83] neg_lo:[0,1] neg_hi:[0,1]
	v_pk_mul_f32 v[32:33], v[0:1], v[60:61] op_sel_hi:[1,0]
	v_pk_add_f32 v[94:95], v[2:3], v[82:83] neg_lo:[0,1] neg_hi:[0,1]
	v_pk_fma_f32 v[32:33], v[2:3], v[60:61], v[32:33] op_sel:[0,1,0] op_sel_hi:[1,1,1]
	v_pk_add_f32 v[96:97], v[4:5], v[82:83] neg_lo:[0,1] neg_hi:[0,1]
	v_pk_fma_f32 v[32:33], v[4:5], v[62:63], v[32:33] op_sel_hi:[1,0,1]
	v_pk_add_f32 v[98:99], v[6:7], v[82:83] neg_lo:[0,1] neg_hi:[0,1]
	v_pk_fma_f32 v[32:33], v[6:7], v[62:63], v[32:33] op_sel:[0,1,0] op_sel_hi:[1,1,1]
	v_pk_fma_f32 v[0:1], v[92:93], v[64:65], v[82:83] op_sel_hi:[1,0,1]
	v_pk_fma_f32 v[2:3], v[94:95], v[64:65], v[82:83] op_sel:[0,1,0] op_sel_hi:[1,1,1]
	v_pk_fma_f32 v[4:5], v[96:97], v[66:67], v[82:83] op_sel_hi:[1,0,1]
	v_pk_fma_f32 v[6:7], v[98:99], v[66:67], v[82:83] op_sel:[0,1,0] op_sel_hi:[1,1,1]
	s_waitcnt lgkmcnt(2)
	v_pk_add_f32 v[92:93], v[0:1], v[84:85] neg_lo:[0,1] neg_hi:[0,1]
	v_pk_mul_f32 v[34:35], v[0:1], v[68:69] op_sel_hi:[1,0]
	v_pk_add_f32 v[94:95], v[2:3], v[84:85] neg_lo:[0,1] neg_hi:[0,1]
	v_pk_fma_f32 v[34:35], v[2:3], v[68:69], v[34:35] op_sel:[0,1,0] op_sel_hi:[1,1,1]
	v_pk_add_f32 v[96:97], v[4:5], v[84:85] neg_lo:[0,1] neg_hi:[0,1]
	v_pk_fma_f32 v[34:35], v[4:5], v[70:71], v[34:35] op_sel_hi:[1,0,1]
	v_pk_add_f32 v[98:99], v[6:7], v[84:85] neg_lo:[0,1] neg_hi:[0,1]
	v_pk_fma_f32 v[34:35], v[6:7], v[70:71], v[34:35] op_sel:[0,1,0] op_sel_hi:[1,1,1]
	v_pk_fma_f32 v[0:1], v[92:93], v[72:73], v[84:85] op_sel_hi:[1,0,1]
	v_pk_fma_f32 v[2:3], v[94:95], v[72:73], v[84:85] op_sel:[0,1,0] op_sel_hi:[1,1,1]
	v_pk_fma_f32 v[4:5], v[96:97], v[74:75], v[84:85] op_sel_hi:[1,0,1]
	v_pk_fma_f32 v[6:7], v[98:99], v[74:75], v[84:85] op_sel:[0,1,0] op_sel_hi:[1,1,1]
	s_waitcnt lgkmcnt(0)
	v_pk_add_f32 v[92:93], v[0:1], v[86:87] neg_lo:[0,1] neg_hi:[0,1]
	v_pk_mul_f32 v[36:37], v[0:1], v[76:77] op_sel_hi:[1,0]
	v_pk_add_f32 v[94:95], v[2:3], v[86:87] neg_lo:[0,1] neg_hi:[0,1]
	v_pk_fma_f32 v[36:37], v[2:3], v[76:77], v[36:37] op_sel:[0,1,0] op_sel_hi:[1,1,1]
	v_pk_add_f32 v[96:97], v[4:5], v[86:87] neg_lo:[0,1] neg_hi:[0,1]
	v_pk_fma_f32 v[36:37], v[4:5], v[78:79], v[36:37] op_sel_hi:[1,0,1]
	v_pk_add_f32 v[98:99], v[6:7], v[86:87] neg_lo:[0,1] neg_hi:[0,1]
	v_pk_fma_f32 v[36:37], v[6:7], v[78:79], v[36:37] op_sel:[0,1,0] op_sel_hi:[1,1,1]
	v_pk_fma_f32 v[0:1], v[92:93], v[40:41], v[86:87] op_sel_hi:[1,0,1]
	v_pk_fma_f32 v[2:3], v[94:95], v[40:41], v[86:87] op_sel:[0,1,0] op_sel_hi:[1,1,1]
	v_pk_fma_f32 v[4:5], v[96:97], v[42:43], v[86:87] op_sel_hi:[1,0,1]
	v_pk_fma_f32 v[6:7], v[98:99], v[42:43], v[86:87] op_sel:[0,1,0] op_sel_hi:[1,1,1]
	v_pk_mul_f32 v[38:39], v[0:1], v[44:45] op_sel_hi:[1,0]
	v_pk_fma_f32 v[38:39], v[2:3], v[44:45], v[38:39] op_sel:[0,1,0] op_sel_hi:[1,1,1]
	v_pk_fma_f32 v[38:39], v[4:5], v[46:47], v[38:39] op_sel_hi:[1,0,1]
	v_pk_fma_f32 v[38:39], v[6:7], v[46:47], v[38:39] op_sel:[0,1,0] op_sel_hi:[1,1,1]
	s_nop 1
	v_permlane16_swap_b32_e32 v8, v24
	v_permlane16_swap_b32_e32 v9, v25
	v_permlane16_swap_b32_e32 v10, v26
	v_permlane16_swap_b32_e32 v11, v27
	v_permlane16_swap_b32_e32 v12, v28
	v_permlane16_swap_b32_e32 v13, v29
	v_permlane16_swap_b32_e32 v14, v30
	v_permlane16_swap_b32_e32 v15, v31
	v_permlane16_swap_b32_e32 v16, v32
	v_permlane16_swap_b32_e32 v17, v33
	v_permlane16_swap_b32_e32 v18, v34
	v_permlane16_swap_b32_e32 v19, v35
	v_permlane16_swap_b32_e32 v20, v36
	v_permlane16_swap_b32_e32 v21, v37
	v_permlane16_swap_b32_e32 v22, v38
	v_permlane16_swap_b32_e32 v23, v39
	v_pk_add_f32 v[8:9], v[8:9], v[24:25]
	v_pk_add_f32 v[10:11], v[10:11], v[26:27]
	v_pk_add_f32 v[12:13], v[12:13], v[28:29]
	v_pk_add_f32 v[14:15], v[14:15], v[30:31]
	v_pk_add_f32 v[16:17], v[16:17], v[32:33]
	v_pk_add_f32 v[18:19], v[18:19], v[34:35]
	v_pk_add_f32 v[20:21], v[20:21], v[36:37]
	v_pk_add_f32 v[22:23], v[22:23], v[38:39]
	s_nop 1
	v_permlane32_swap_b32_e32 v8, v16
	v_permlane32_swap_b32_e32 v9, v17
	v_permlane32_swap_b32_e32 v10, v18
	v_permlane32_swap_b32_e32 v11, v19
	v_permlane32_swap_b32_e32 v12, v20
	v_permlane32_swap_b32_e32 v13, v21
	v_permlane32_swap_b32_e32 v14, v22
	v_permlane32_swap_b32_e32 v15, v23
	v_pk_add_f32 v[8:9], v[8:9], v[16:17]
	v_pk_add_f32 v[10:11], v[10:11], v[18:19]
	v_pk_add_f32 v[12:13], v[12:13], v[20:21]
	v_pk_add_f32 v[14:15], v[14:15], v[22:23]
	ds_write2_b32 v145, v8, v9 offset1:16
	ds_write2_b32 v146, v10, v11 offset1:16
	ds_write2_b32 v147, v12, v13 offset1:16
	ds_write2_b32 v148, v14, v15 offset1:16
	s_sub_u32 s15, s15, 1
	s_waitcnt lgkmcnt(0)
	s_barrier
	s_cmp_lg_u32 s15, 0
	s_cbranch_scc1 .Lgla_loop_hgrn
	s_branch .Lgla_tail

.Lgla_st_join_4:
	v_lshlrev_b32_e32 v184, 16, v126
	v_and_b32_e32 v185, s69, v126
	v_lshlrev_b32_e32 v186, 16, v127
	v_and_b32_e32 v187, s69, v127
	v_lshlrev_b32_e32 v188, 16, v119
	v_and_b32_e32 v189, s69, v119
	ds_write_b128 v139, v[180:183] offset:40960
	ds_write_b128 v139, v[184:187] offset:49152
	ds_write2_b32 v153, v188, v189 offset1:4
	global_load_dwordx2 v[126:127], v130, s[8:9]
	global_load_dwordx2 v[190:191], v130, s[8:9] offset:1024
	global_load_dword v119, v131, s[8:9]
	s_add_u32 s8, s8, 0x34000
	s_addc_u32 s9, s9, 0
	s_waitcnt lgkmcnt(3)
	v_add_f32_e32 v112, v104, v105
	v_add_f32_e32 v112, v112, v106
	v_add_f32_e32 v112, v112, v107
	v_add_f32_e32 v112, v112, v108
	v_add_f32_e32 v112, v112, v109
	v_add_f32_e32 v112, v112, v110
	v_add_f32_e32 v112, v112, v111
	v_mul_f32_e32 v113, v112, v112
	v_cvt_pk_bf16_f32 v116, v112, v129
	v_mov_b32_e32 v117, v112
	v_mov_b32_e32 v118, v113
	global_store_short v132, v116, s[10:11]
	s_nop 1
	v_permlane16_swap_b32_e32 v112, v117
	v_permlane16_swap_b32_e32 v113, v118
	v_add_f32_e32 v112, v112, v117
	v_add_f32_e32 v113, v113, v118
	s_nop 1
	v_add_f32_dpp v112, v112, v112 row_ror:8 row_mask:0xf bank_mask:0xf
	v_add_f32_dpp v113, v113, v113 row_ror:8 row_mask:0xf bank_mask:0xf
	s_nop 1
	v_add_f32_dpp v112, v112, v112 row_ror:4 row_mask:0xf bank_mask:0xf
	v_add_f32_dpp v113, v113, v113 row_ror:4 row_mask:0xf bank_mask:0xf
	s_nop 1
	v_add_f32_dpp v112, v112, v112 row_ror:2 row_mask:0xf bank_mask:0xf
	v_add_f32_dpp v113, v113, v113 row_ror:2 row_mask:0xf bank_mask:0xf
	s_nop 1
	v_add_f32_dpp v112, v112, v112 row_ror:1 row_mask:0xf bank_mask:0xf
	v_add_f32_dpp v113, v113, v113 row_ror:1 row_mask:0xf bank_mask:0xf
	v_mov_b32_e32 v114, 0
	v_mov_b32_e32 v115, 0
	s_mov_b64 exec, s[18:19]
	global_store_dwordx4 v133, v[112:115], s[12:13]
	s_mov_b64 exec, -1
	s_cmp_eq_u32 s15, 512
	s_cselect_b32 s20, 0, 0x10000
	s_cselect_b32 s21, 0, 0x1000
	s_add_u32 s10, s10, s20
	s_addc_u32 s11, s11, 0
	s_add_u32 s12, s12, s21
	s_addc_u32 s13, s13, 0
	ds_read_b128 v[80:83], v135 offset:24576
	ds_read_b128 v[40:43], v134 offset:8192
	ds_read_b128 v[44:47], v134 offset:16384
	ds_read_b128 v[48:51], v134 offset:8704
	ds_read_b128 v[52:55], v134 offset:16896
	ds_read_b128 v[84:87], v135 offset:24832
	ds_read_b128 v[56:59], v134 offset:9216
	ds_read_b128 v[60:63], v134 offset:17408
	ds_read_b128 v[64:67], v134 offset:9728
	ds_read_b128 v[68:71], v134 offset:17920
	s_waitcnt lgkmcnt(7)
	v_pk_mul_f32 v[92:93], v[80:81], v[40:41] op_sel_hi:[1,0]
	v_pk_mul_f32 v[94:95], v[80:81], v[40:41] op_sel:[0,1] op_sel_hi:[1,1]
	v_pk_mul_f32 v[96:97], v[80:81], v[42:43] op_sel_hi:[1,0]
	v_pk_mul_f32 v[98:99], v[80:81], v[42:43] op_sel:[0,1] op_sel_hi:[1,1]
	v_pk_fma_f32 v[0:1], v[0:1], v[100:101], v[92:93]
	v_pk_fma_f32 v[2:3], v[2:3], v[100:101], v[94:95]
	v_pk_fma_f32 v[4:5], v[4:5], v[100:101], v[96:97]
	v_pk_fma_f32 v[6:7], v[6:7], v[100:101], v[98:99]
	ds_read_b128 v[88:91], v135 offset:25088
	ds_read_b128 v[72:75], v134 offset:10240
	ds_read_b128 v[76:79], v134 offset:18432
	s_waitcnt lgkmcnt(8)
	v_pk_mul_f32 v[92:93], v[82:83], v[48:49] op_sel_hi:[1,0]
	v_pk_mul_f32 v[8:9], v[0:1], v[44:45] op_sel_hi:[1,0]
	v_pk_mul_f32 v[94:95], v[82:83], v[48:49] op_sel:[0,1] op_sel_hi:[1,1]
	v_pk_fma_f32 v[8:9], v[2:3], v[44:45], v[8:9] op_sel:[0,1,0] op_sel_hi:[1,1,1]
	v_pk_mul_f32 v[96:97], v[82:83], v[50:51] op_sel_hi:[1,0]
	v_pk_fma_f32 v[8:9], v[4:5], v[46:47], v[8:9] op_sel_hi:[1,0,1]
	v_pk_mul_f32 v[98:99], v[82:83], v[50:51] op_sel:[0,1] op_sel_hi:[1,1]
	v_pk_fma_f32 v[8:9], v[6:7], v[46:47], v[8:9] op_sel:[0,1,0] op_sel_hi:[1,1,1]
	v_pk_fma_f32 v[0:1], v[0:1], v[100:101], v[92:93]
	v_pk_fma_f32 v[2:3], v[2:3], v[100:101], v[94:95]
	v_pk_fma_f32 v[4:5], v[4:5], v[100:101], v[96:97]
	v_pk_fma_f32 v[6:7], v[6:7], v[100:101], v[98:99]
	ds_read_b128 v[40:43], v134 offset:10752
	ds_read_b128 v[44:47], v134 offset:18944
	s_waitcnt lgkmcnt(7)
	v_pk_mul_f32 v[92:93], v[84:85], v[56:57] op_sel_hi:[1,0]
	v_pk_mul_f32 v[10:11], v[0:1], v[52:53] op_sel_hi:[1,0]
	v_pk_mul_f32 v[94:95], v[84:85], v[56:57] op_sel:[0,1] op_sel_hi:[1,1]
	v_pk_fma_f32 v[10:11], v[2:3], v[52:53], v[10:11] op_sel:[0,1,0] op_sel_hi:[1,1,1]
	v_pk_mul_f32 v[96:97], v[84:85], v[58:59] op_sel_hi:[1,0]
	v_pk_fma_f32 v[10:11], v[4:5], v[54:55], v[10:11] op_sel_hi:[1,0,1]
	v_pk_mul_f32 v[98:99], v[84:85], v[58:59] op_sel:[0,1] op_sel_hi:[1,1]
	v_pk_fma_f32 v[10:11], v[6:7], v[54:55], v[10:11] op_sel:[0,1,0] op_sel_hi:[1,1,1]
	v_pk_fma_f32 v[0:1], v[0:1], v[100:101], v[92:93]
	v_pk_fma_f32 v[2:3], v[2:3], v[100:101], v[94:95]
	v_pk_fma_f32 v[4:5], v[4:5], v[100:101], v[96:97]
	v_pk_fma_f32 v[6:7], v[6:7], v[100:101], v[98:99]
	ds_read_b128 v[80:83], v135 offset:25344
	ds_read_b128 v[48:51], v134 offset:11264
	ds_read_b128 v[52:55], v134 offset:19456
	s_waitcnt lgkmcnt(8)
	v_pk_mul_f32 v[92:93], v[86:87], v[64:65] op_sel_hi:[1,0]
	v_pk_mul_f32 v[12:13], v[0:1], v[60:61] op_sel_hi:[1,0]
	v_pk_mul_f32 v[94:95], v[86:87], v[64:65] op_sel:[0,1] op_sel_hi:[1,1]
	v_pk_fma_f32 v[12:13], v[2:3], v[60:61], v[12:13] op_sel:[0,1,0] op_sel_hi:[1,1,1]
	v_pk_mul_f32 v[96:97], v[86:87], v[66:67] op_sel_hi:[1,0]
	v_pk_fma_f32 v[12:13], v[4:5], v[62:63], v[12:13] op_sel_hi:[1,0,1]
	v_pk_mul_f32 v[98:99], v[86:87], v[66:67] op_sel:[0,1] op_sel_hi:[1,1]
	v_pk_fma_f32 v[12:13], v[6:7], v[62:63], v[12:13] op_sel:[0,1,0] op_sel_hi:[1,1,1]
	v_pk_fma_f32 v[0:1], v[0:1], v[100:101], v[92:93]
	v_pk_fma_f32 v[2:3], v[2:3], v[100:101], v[94:95]
	v_pk_fma_f32 v[4:5], v[4:5], v[100:101], v[96:97]
	v_pk_fma_f32 v[6:7], v[6:7], v[100:101], v[98:99]
	ds_read_b128 v[56:59], v134 offset:11776
	ds_read_b128 v[60:63], v134 offset:19968
	s_waitcnt lgkmcnt(7)
	v_pk_mul_f32 v[92:93], v[88:89], v[72:73] op_sel_hi:[1,0]
	v_pk_mul_f32 v[14:15], v[0:1], v[68:69] op_sel_hi:[1,0]
	v_pk_mul_f32 v[94:95], v[88:89], v[72:73] op_sel:[0,1] op_sel_hi:[1,1]
	v_pk_fma_f32 v[14:15], v[2:3], v[68:69], v[14:15] op_sel:[0,1,0] op_sel_hi:[1,1,1]
	v_pk_mul_f32 v[96:97], v[88:89], v[74:75] op_sel_hi:[1,0]
	v_pk_fma_f32 v[14:15], v[4:5], v[70:71], v[14:15] op_sel_hi:[1,0,1]
	v_pk_mul_f32 v[98:99], v[88:89], v[74:75] op_sel:[0,1] op_sel_hi:[1,1]
	v_pk_fma_f32 v[14:15], v[6:7], v[70:71], v[14:15] op_sel:[0,1,0] op_sel_hi:[1,1,1]
	v_pk_fma_f32 v[0:1], v[0:1], v[100:101], v[92:93]
	v_pk_fma_f32 v[2:3], v[2:3], v[100:101], v[94:95]
	v_pk_fma_f32 v[4:5], v[4:5], v[100:101], v[96:97]
	v_pk_fma_f32 v[6:7], v[6:7], v[100:101], v[98:99]
	ds_read_b128 v[84:87], v135 offset:25600
	ds_read_b128 v[64:67], v134 offset:12288
	ds_read_b128 v[68:71], v134 offset:20480
	s_waitcnt lgkmcnt(8)
	v_pk_mul_f32 v[92:93], v[90:91], v[40:41] op_sel_hi:[1,0]
	v_pk_mul_f32 v[16:17], v[0:1], v[76:77] op_sel_hi:[1,0]
	v_pk_mul_f32 v[94:95], v[90:91], v[40:41] op_sel:[0,1] op_sel_hi:[1,1]
	v_pk_fma_f32 v[16:17], v[2:3], v[76:77], v[16:17] op_sel:[0,1,0] op_sel_hi:[1,1,1]
	v_pk_mul_f32 v[96:97], v[90:91], v[42:43] op_sel_hi:[1,0]
	v_pk_fma_f32 v[16:17], v[4:5], v[78:79], v[16:17] op_sel_hi:[1,0,1]
	v_pk_mul_f32 v[98:99], v[90:91], v[42:43] op_sel:[0,1] op_sel_hi:[1,1]
	v_pk_fma_f32 v[16:17], v[6:7], v[78:79], v[16:17] op_sel:[0,1,0] op_sel_hi:[1,1,1]
	v_pk_fma_f32 v[0:1], v[0:1], v[100:101], v[92:93]
	v_pk_fma_f32 v[2:3], v[2:3], v[100:101], v[94:95]
	v_pk_fma_f32 v[4:5], v[4:5], v[100:101], v[96:97]
	v_pk_fma_f32 v[6:7], v[6:7], v[100:101], v[98:99]
	ds_read_b128 v[72:75], v134 offset:12800
	ds_read_b128 v[76:79], v134 offset:20992
	s_waitcnt lgkmcnt(7)
	v_pk_mul_f32 v[92:93], v[80:81], v[48:49] op_sel_hi:[1,0]
	v_pk_mul_f32 v[18:19], v[0:1], v[44:45] op_sel_hi:[1,0]
	v_pk_mul_f32 v[94:95], v[80:81], v[48:49] op_sel:[0,1] op_sel_hi:[1,1]
	v_pk_fma_f32 v[18:19], v[2:3], v[44:45], v[18:19] op_sel:[0,1,0] op_sel_hi:[1,1,1]
	v_pk_mul_f32 v[96:97], v[80:81], v[50:51] op_sel_hi:[1,0]
	v_pk_fma_f32 v[18:19], v[4:5], v[46:47], v[18:19] op_sel_hi:[1,0,1]
	v_pk_mul_f32 v[98:99], v[80:81], v[50:51] op_sel:[0,1] op_sel_hi:[1,1]
	v_pk_fma_f32 v[18:19], v[6:7], v[46:47], v[18:19] op_sel:[0,1,0] op_sel_hi:[1,1,1]
	v_pk_fma_f32 v[0:1], v[0:1], v[100:101], v[92:93]
	v_pk_fma_f32 v[2:3], v[2:3], v[100:101], v[94:95]
	v_pk_fma_f32 v[4:5], v[4:5], v[100:101], v[96:97]
	v_pk_fma_f32 v[6:7], v[6:7], v[100:101], v[98:99]
	ds_read_b128 v[88:91], v135 offset:25856
	ds_read_b128 v[40:43], v134 offset:13312
	ds_read_b128 v[44:47], v134 offset:21504
	s_waitcnt lgkmcnt(8)
	v_pk_mul_f32 v[92:93], v[82:83], v[56:57] op_sel_hi:[1,0]
	v_pk_mul_f32 v[20:21], v[0:1], v[52:53] op_sel_hi:[1,0]
	v_pk_mul_f32 v[94:95], v[82:83], v[56:57] op_sel:[0,1] op_sel_hi:[1,1]
	v_pk_fma_f32 v[20:21], v[2:3], v[52:53], v[20:21] op_sel:[0,1,0] op_sel_hi:[1,1,1]
	v_pk_mul_f32 v[96:97], v[82:83], v[58:59] op_sel_hi:[1,0]
	v_pk_fma_f32 v[20:21], v[4:5], v[54:55], v[20:21] op_sel_hi:[1,0,1]
	v_pk_mul_f32 v[98:99], v[82:83], v[58:59] op_sel:[0,1] op_sel_hi:[1,1]
	v_pk_fma_f32 v[20:21], v[6:7], v[54:55], v[20:21] op_sel:[0,1,0] op_sel_hi:[1,1,1]
	v_pk_fma_f32 v[0:1], v[0:1], v[100:101], v[92:93]
	v_pk_fma_f32 v[2:3], v[2:3], v[100:101], v[94:95]
	v_pk_fma_f32 v[4:5], v[4:5], v[100:101], v[96:97]
	v_pk_fma_f32 v[6:7], v[6:7], v[100:101], v[98:99]
	ds_read_b128 v[48:51], v134 offset:13824
	ds_read_b128 v[52:55], v134 offset:22016
	s_waitcnt lgkmcnt(7)
	v_pk_mul_f32 v[92:93], v[84:85], v[64:65] op_sel_hi:[1,0]
	v_pk_mul_f32 v[22:23], v[0:1], v[60:61] op_sel_hi:[1,0]
	v_pk_mul_f32 v[94:95], v[84:85], v[64:65] op_sel:[0,1] op_sel_hi:[1,1]
	v_pk_fma_f32 v[22:23], v[2:3], v[60:61], v[22:23] op_sel:[0,1,0] op_sel_hi:[1,1,1]
	v_pk_mul_f32 v[96:97], v[84:85], v[66:67] op_sel_hi:[1,0]
	v_pk_fma_f32 v[22:23], v[4:5], v[62:63], v[22:23] op_sel_hi:[1,0,1]
	v_pk_mul_f32 v[98:99], v[84:85], v[66:67] op_sel:[0,1] op_sel_hi:[1,1]
	v_pk_fma_f32 v[22:23], v[6:7], v[62:63], v[22:23] op_sel:[0,1,0] op_sel_hi:[1,1,1]
	v_pk_fma_f32 v[0:1], v[0:1], v[100:101], v[92:93]
	v_pk_fma_f32 v[2:3], v[2:3], v[100:101], v[94:95]
	v_pk_fma_f32 v[4:5], v[4:5], v[100:101], v[96:97]
	v_pk_fma_f32 v[6:7], v[6:7], v[100:101], v[98:99]
	ds_read_b128 v[80:83], v135 offset:26112
	ds_read_b128 v[56:59], v134 offset:14336
	ds_read_b128 v[60:63], v134 offset:22528
	s_waitcnt lgkmcnt(8)
	v_pk_mul_f32 v[92:93], v[86:87], v[72:73] op_sel_hi:[1,0]
	v_pk_mul_f32 v[24:25], v[0:1], v[68:69] op_sel_hi:[1,0]
	v_pk_mul_f32 v[94:95], v[86:87], v[72:73] op_sel:[0,1] op_sel_hi:[1,1]
	v_pk_fma_f32 v[24:25], v[2:3], v[68:69], v[24:25] op_sel:[0,1,0] op_sel_hi:[1,1,1]
	v_pk_mul_f32 v[96:97], v[86:87], v[74:75] op_sel_hi:[1,0]
	v_pk_fma_f32 v[24:25], v[4:5], v[70:71], v[24:25] op_sel_hi:[1,0,1]
	v_pk_mul_f32 v[98:99], v[86:87], v[74:75] op_sel:[0,1] op_sel_hi:[1,1]
	v_pk_fma_f32 v[24:25], v[6:7], v[70:71], v[24:25] op_sel:[0,1,0] op_sel_hi:[1,1,1]
	v_pk_fma_f32 v[0:1], v[0:1], v[100:101], v[92:93]
	v_pk_fma_f32 v[2:3], v[2:3], v[100:101], v[94:95]
	v_pk_fma_f32 v[4:5], v[4:5], v[100:101], v[96:97]
	v_pk_fma_f32 v[6:7], v[6:7], v[100:101], v[98:99]
	ds_read_b128 v[64:67], v134 offset:14848
	ds_read_b128 v[68:71], v134 offset:23040
	s_waitcnt lgkmcnt(7)
	v_pk_mul_f32 v[92:93], v[88:89], v[40:41] op_sel_hi:[1,0]
	v_pk_mul_f32 v[26:27], v[0:1], v[76:77] op_sel_hi:[1,0]
	v_pk_mul_f32 v[94:95], v[88:89], v[40:41] op_sel:[0,1] op_sel_hi:[1,1]
	v_pk_fma_f32 v[26:27], v[2:3], v[76:77], v[26:27] op_sel:[0,1,0] op_sel_hi:[1,1,1]
	v_pk_mul_f32 v[96:97], v[88:89], v[42:43] op_sel_hi:[1,0]
	v_pk_fma_f32 v[26:27], v[4:5], v[78:79], v[26:27] op_sel_hi:[1,0,1]
	v_pk_mul_f32 v[98:99], v[88:89], v[42:43] op_sel:[0,1] op_sel_hi:[1,1]
	v_pk_fma_f32 v[26:27], v[6:7], v[78:79], v[26:27] op_sel:[0,1,0] op_sel_hi:[1,1,1]
	v_pk_fma_f32 v[0:1], v[0:1], v[100:101], v[92:93]
	v_pk_fma_f32 v[2:3], v[2:3], v[100:101], v[94:95]
	v_pk_fma_f32 v[4:5], v[4:5], v[100:101], v[96:97]
	v_pk_fma_f32 v[6:7], v[6:7], v[100:101], v[98:99]
	ds_read_b128 v[84:87], v135 offset:26368
	ds_read_b128 v[72:75], v134 offset:15360
	ds_read_b128 v[76:79], v134 offset:23552
	s_waitcnt lgkmcnt(8)
	v_pk_mul_f32 v[92:93], v[90:91], v[48:49] op_sel_hi:[1,0]
	v_pk_mul_f32 v[28:29], v[0:1], v[44:45] op_sel_hi:[1,0]
	v_pk_mul_f32 v[94:95], v[90:91], v[48:49] op_sel:[0,1] op_sel_hi:[1,1]
	v_pk_fma_f32 v[28:29], v[2:3], v[44:45], v[28:29] op_sel:[0,1,0] op_sel_hi:[1,1,1]
	v_pk_mul_f32 v[96:97], v[90:91], v[50:51] op_sel_hi:[1,0]
	v_pk_fma_f32 v[28:29], v[4:5], v[46:47], v[28:29] op_sel_hi:[1,0,1]
	v_pk_mul_f32 v[98:99], v[90:91], v[50:51] op_sel:[0,1] op_sel_hi:[1,1]
	v_pk_fma_f32 v[28:29], v[6:7], v[46:47], v[28:29] op_sel:[0,1,0] op_sel_hi:[1,1,1]
	v_pk_fma_f32 v[0:1], v[0:1], v[100:101], v[92:93]
	v_pk_fma_f32 v[2:3], v[2:3], v[100:101], v[94:95]
	v_pk_fma_f32 v[4:5], v[4:5], v[100:101], v[96:97]
	v_pk_fma_f32 v[6:7], v[6:7], v[100:101], v[98:99]
	ds_read_b128 v[40:43], v134 offset:15872
	ds_read_b128 v[44:47], v134 offset:24064
	s_waitcnt lgkmcnt(7)
	v_pk_mul_f32 v[92:93], v[80:81], v[56:57] op_sel_hi:[1,0]
	v_pk_mul_f32 v[30:31], v[0:1], v[52:53] op_sel_hi:[1,0]
	v_pk_mul_f32 v[94:95], v[80:81], v[56:57] op_sel:[0,1] op_sel_hi:[1,1]
	v_pk_fma_f32 v[30:31], v[2:3], v[52:53], v[30:31] op_sel:[0,1,0] op_sel_hi:[1,1,1]
	v_pk_mul_f32 v[96:97], v[80:81], v[58:59] op_sel_hi:[1,0]
	v_pk_fma_f32 v[30:31], v[4:5], v[54:55], v[30:31] op_sel_hi:[1,0,1]
	v_pk_mul_f32 v[98:99], v[80:81], v[58:59] op_sel:[0,1] op_sel_hi:[1,1]
	v_pk_fma_f32 v[30:31], v[6:7], v[54:55], v[30:31] op_sel:[0,1,0] op_sel_hi:[1,1,1]
	v_pk_fma_f32 v[0:1], v[0:1], v[100:101], v[92:93]
	v_pk_fma_f32 v[2:3], v[2:3], v[100:101], v[94:95]
	v_pk_fma_f32 v[4:5], v[4:5], v[100:101], v[96:97]
	v_pk_fma_f32 v[6:7], v[6:7], v[100:101], v[98:99]
	s_waitcnt lgkmcnt(5)
	v_pk_mul_f32 v[92:93], v[82:83], v[64:65] op_sel_hi:[1,0]
	v_pk_mul_f32 v[32:33], v[0:1], v[60:61] op_sel_hi:[1,0]
	v_pk_mul_f32 v[94:95], v[82:83], v[64:65] op_sel:[0,1] op_sel_hi:[1,1]
	v_pk_fma_f32 v[32:33], v[2:3], v[60:61], v[32:33] op_sel:[0,1,0] op_sel_hi:[1,1,1]
	v_pk_mul_f32 v[96:97], v[82:83], v[66:67] op_sel_hi:[1,0]
	v_pk_fma_f32 v[32:33], v[4:5], v[62:63], v[32:33] op_sel_hi:[1,0,1]
	v_pk_mul_f32 v[98:99], v[82:83], v[66:67] op_sel:[0,1] op_sel_hi:[1,1]
	v_pk_fma_f32 v[32:33], v[6:7], v[62:63], v[32:33] op_sel:[0,1,0] op_sel_hi:[1,1,1]
	v_pk_fma_f32 v[0:1], v[0:1], v[100:101], v[92:93]
	v_pk_fma_f32 v[2:3], v[2:3], v[100:101], v[94:95]
	v_pk_fma_f32 v[4:5], v[4:5], v[100:101], v[96:97]
	v_pk_fma_f32 v[6:7], v[6:7], v[100:101], v[98:99]
	s_waitcnt lgkmcnt(2)
	v_pk_mul_f32 v[92:93], v[84:85], v[72:73] op_sel_hi:[1,0]
	v_pk_mul_f32 v[34:35], v[0:1], v[68:69] op_sel_hi:[1,0]
	v_pk_mul_f32 v[94:95], v[84:85], v[72:73] op_sel:[0,1] op_sel_hi:[1,1]
	v_pk_fma_f32 v[34:35], v[2:3], v[68:69], v[34:35] op_sel:[0,1,0] op_sel_hi:[1,1,1]
	v_pk_mul_f32 v[96:97], v[84:85], v[74:75] op_sel_hi:[1,0]
	v_pk_fma_f32 v[34:35], v[4:5], v[70:71], v[34:35] op_sel_hi:[1,0,1]
	v_pk_mul_f32 v[98:99], v[84:85], v[74:75] op_sel:[0,1] op_sel_hi:[1,1]
	v_pk_fma_f32 v[34:35], v[6:7], v[70:71], v[34:35] op_sel:[0,1,0] op_sel_hi:[1,1,1]
	v_pk_fma_f32 v[0:1], v[0:1], v[100:101], v[92:93]
	v_pk_fma_f32 v[2:3], v[2:3], v[100:101], v[94:95]
	v_pk_fma_f32 v[4:5], v[4:5], v[100:101], v[96:97]
	v_pk_fma_f32 v[6:7], v[6:7], v[100:101], v[98:99]
	s_waitcnt lgkmcnt(0)
	v_pk_mul_f32 v[92:93], v[86:87], v[40:41] op_sel_hi:[1,0]
	v_pk_mul_f32 v[36:37], v[0:1], v[76:77] op_sel_hi:[1,0]
	v_pk_mul_f32 v[94:95], v[86:87], v[40:41] op_sel:[0,1] op_sel_hi:[1,1]
	v_pk_fma_f32 v[36:37], v[2:3], v[76:77], v[36:37] op_sel:[0,1,0] op_sel_hi:[1,1,1]
	v_pk_mul_f32 v[96:97], v[86:87], v[42:43] op_sel_hi:[1,0]
	v_pk_fma_f32 v[36:37], v[4:5], v[78:79], v[36:37] op_sel_hi:[1,0,1]
	v_pk_mul_f32 v[98:99], v[86:87], v[42:43] op_sel:[0,1] op_sel_hi:[1,1]
	v_pk_fma_f32 v[36:37], v[6:7], v[78:79], v[36:37] op_sel:[0,1,0] op_sel_hi:[1,1,1]
	v_pk_fma_f32 v[0:1], v[0:1], v[100:101], v[92:93]
	v_pk_fma_f32 v[2:3], v[2:3], v[100:101], v[94:95]
	v_pk_fma_f32 v[4:5], v[4:5], v[100:101], v[96:97]
	v_pk_fma_f32 v[6:7], v[6:7], v[100:101], v[98:99]
	v_pk_mul_f32 v[38:39], v[0:1], v[44:45] op_sel_hi:[1,0]
	v_pk_fma_f32 v[38:39], v[2:3], v[44:45], v[38:39] op_sel:[0,1,0] op_sel_hi:[1,1,1]
	v_pk_fma_f32 v[38:39], v[4:5], v[46:47], v[38:39] op_sel_hi:[1,0,1]
	v_pk_fma_f32 v[38:39], v[6:7], v[46:47], v[38:39] op_sel:[0,1,0] op_sel_hi:[1,1,1]
	s_nop 1
	v_permlane16_swap_b32_e32 v8, v24
	v_permlane16_swap_b32_e32 v9, v25
	v_permlane16_swap_b32_e32 v10, v26
	v_permlane16_swap_b32_e32 v11, v27
	v_permlane16_swap_b32_e32 v12, v28
	v_permlane16_swap_b32_e32 v13, v29
	v_permlane16_swap_b32_e32 v14, v30
	v_permlane16_swap_b32_e32 v15, v31
	v_permlane16_swap_b32_e32 v16, v32
	v_permlane16_swap_b32_e32 v17, v33
	v_permlane16_swap_b32_e32 v18, v34
	v_permlane16_swap_b32_e32 v19, v35
	v_permlane16_swap_b32_e32 v20, v36
	v_permlane16_swap_b32_e32 v21, v37
	v_permlane16_swap_b32_e32 v22, v38
	v_permlane16_swap_b32_e32 v23, v39
	v_pk_add_f32 v[8:9], v[8:9], v[24:25]
	v_pk_add_f32 v[10:11], v[10:11], v[26:27]
	v_pk_add_f32 v[12:13], v[12:13], v[28:29]
	v_pk_add_f32 v[14:15], v[14:15], v[30:31]
	v_pk_add_f32 v[16:17], v[16:17], v[32:33]
	v_pk_add_f32 v[18:19], v[18:19], v[34:35]
	v_pk_add_f32 v[20:21], v[20:21], v[36:37]
	v_pk_add_f32 v[22:23], v[22:23], v[38:39]
	s_nop 1
	v_permlane32_swap_b32_e32 v8, v16
	v_permlane32_swap_b32_e32 v9, v17
	v_permlane32_swap_b32_e32 v10, v18
	v_permlane32_swap_b32_e32 v11, v19
	v_permlane32_swap_b32_e32 v12, v20
	v_permlane32_swap_b32_e32 v13, v21
	v_permlane32_swap_b32_e32 v14, v22
	v_permlane32_swap_b32_e32 v15, v23
	v_pk_add_f32 v[8:9], v[8:9], v[16:17]
	v_pk_add_f32 v[10:11], v[10:11], v[18:19]
	v_pk_add_f32 v[12:13], v[12:13], v[20:21]
	v_pk_add_f32 v[14:15], v[14:15], v[22:23]
	ds_write2_b32 v141, v8, v9 offset1:16
	ds_write2_b32 v142, v10, v11 offset1:16
	ds_write2_b32 v143, v12, v13 offset1:16
	ds_write2_b32 v144, v14, v15 offset1:16
	s_sub_u32 s15, s15, 1
	s_waitcnt lgkmcnt(0)
	s_barrier
	ds_read2_b32 v[104:105], v149 offset0:0 offset1:32
	ds_read2_b32 v[106:107], v149 offset0:64 offset1:96
	ds_read2_b32 v[108:109], v149 offset0:128 offset1:160
	ds_read2_b32 v[110:111], v149 offset0:192 offset1:224
	s_waitcnt vmcnt(7)
	v_lshlrev_b32_e32 v180, 16, v122
	v_and_b32_e32 v181, s69, v122
	v_lshlrev_b32_e32 v182, 16, v123
	v_and_b32_e32 v183, s69, v123
	s_cmp_eq_u32 s14, 0
	s_cbranch_scc1 .Lgla_st_join_5
	v_mul_f32_e32 v180, 0x3fb8aa3b, v180
	v_mul_f32_e32 v181, 0x3fb8aa3b, v181
	v_mul_f32_e32 v182, 0x3fb8aa3b, v182
	v_mul_f32_e32 v183, 0x3fb8aa3b, v183
	v_exp_f32_e32 v180, v180
	v_exp_f32_e32 v181, v181
	v_exp_f32_e32 v182, v182
	v_exp_f32_e32 v183, v183
.Lgla_st_join_5:
	v_lshlrev_b32_e32 v184, 16, v120
	v_and_b32_e32 v185, s69, v120
	v_lshlrev_b32_e32 v186, 16, v121
	v_and_b32_e32 v187, s69, v121
	v_lshlrev_b32_e32 v188, 16, v124
	v_and_b32_e32 v189, s69, v124
	ds_write_b128 v139, v[180:183] offset:8192
	ds_write_b128 v139, v[184:187] offset:16384
	ds_write2_b32 v140, v188, v189 offset1:4
	global_load_dwordx2 v[120:121], v130, s[8:9]
	global_load_dwordx2 v[122:123], v130, s[8:9] offset:1024
	global_load_dword v124, v131, s[8:9]
	s_add_u32 s8, s8, 0x34000
	s_addc_u32 s9, s9, 0
	s_waitcnt lgkmcnt(3)
	v_add_f32_e32 v112, v104, v105
	v_add_f32_e32 v112, v112, v106
	v_add_f32_e32 v112, v112, v107
	v_add_f32_e32 v112, v112, v108
	v_add_f32_e32 v112, v112, v109
	v_add_f32_e32 v112, v112, v110
	v_add_f32_e32 v112, v112, v111
	v_mul_f32_e32 v113, v112, v112
	v_cvt_pk_bf16_f32 v116, v112, v129
	v_mov_b32_e32 v117, v112
	v_mov_b32_e32 v118, v113
	global_store_short v132, v116, s[10:11]
	s_nop 1
	v_permlane16_swap_b32_e32 v112, v117
	v_permlane16_swap_b32_e32 v113, v118
	v_add_f32_e32 v112, v112, v117
	v_add_f32_e32 v113, v113, v118
	s_nop 1
	v_add_f32_dpp v112, v112, v112 row_ror:8 row_mask:0xf bank_mask:0xf
	v_add_f32_dpp v113, v113, v113 row_ror:8 row_mask:0xf bank_mask:0xf
	s_nop 1
	v_add_f32_dpp v112, v112, v112 row_ror:4 row_mask:0xf bank_mask:0xf
	v_add_f32_dpp v113, v113, v113 row_ror:4 row_mask:0xf bank_mask:0xf
	s_nop 1
	v_add_f32_dpp v112, v112, v112 row_ror:2 row_mask:0xf bank_mask:0xf
	v_add_f32_dpp v113, v113, v113 row_ror:2 row_mask:0xf bank_mask:0xf
	s_nop 1
	v_add_f32_dpp v112, v112, v112 row_ror:1 row_mask:0xf bank_mask:0xf
	v_add_f32_dpp v113, v113, v113 row_ror:1 row_mask:0xf bank_mask:0xf
	v_mov_b32_e32 v114, 0
	v_mov_b32_e32 v115, 0
	s_mov_b64 exec, s[18:19]
	global_store_dwordx4 v133, v[112:115], s[12:13]
	s_mov_b64 exec, -1
	s_cmp_eq_u32 s15, 512
	s_cselect_b32 s20, 0, 0x10000
	s_cselect_b32 s21, 0, 0x1000
	s_add_u32 s10, s10, s20
	s_addc_u32 s11, s11, 0
	s_add_u32 s12, s12, s21
	s_addc_u32 s13, s13, 0
	ds_read_b128 v[80:83], v135 offset:57344
	ds_read_b128 v[40:43], v134 offset:40960
	ds_read_b128 v[44:47], v134 offset:49152
	ds_read_b128 v[48:51], v134 offset:41472
	ds_read_b128 v[52:55], v134 offset:49664
	ds_read_b128 v[84:87], v135 offset:57600
	ds_read_b128 v[56:59], v134 offset:41984
	ds_read_b128 v[60:63], v134 offset:50176
	ds_read_b128 v[64:67], v134 offset:42496
	ds_read_b128 v[68:71], v134 offset:50688
	s_waitcnt lgkmcnt(7)
	v_pk_mul_f32 v[92:93], v[80:81], v[40:41] op_sel_hi:[1,0]
	v_pk_mul_f32 v[94:95], v[80:81], v[40:41] op_sel:[0,1] op_sel_hi:[1,1]
	v_pk_mul_f32 v[96:97], v[80:81], v[42:43] op_sel_hi:[1,0]
	v_pk_mul_f32 v[98:99], v[80:81], v[42:43] op_sel:[0,1] op_sel_hi:[1,1]
	v_pk_fma_f32 v[0:1], v[0:1], v[100:101], v[92:93]
	v_pk_fma_f32 v[2:3], v[2:3], v[100:101], v[94:95]
	v_pk_fma_f32 v[4:5], v[4:5], v[100:101], v[96:97]
	v_pk_fma_f32 v[6:7], v[6:7], v[100:101], v[98:99]
	ds_read_b128 v[88:91], v135 offset:57856
	ds_read_b128 v[72:75], v134 offset:43008
	ds_read_b128 v[76:79], v134 offset:51200
	s_waitcnt lgkmcnt(8)
	v_pk_mul_f32 v[92:93], v[82:83], v[48:49] op_sel_hi:[1,0]
	v_pk_mul_f32 v[8:9], v[0:1], v[44:45] op_sel_hi:[1,0]
	v_pk_mul_f32 v[94:95], v[82:83], v[48:49] op_sel:[0,1] op_sel_hi:[1,1]
	v_pk_fma_f32 v[8:9], v[2:3], v[44:45], v[8:9] op_sel:[0,1,0] op_sel_hi:[1,1,1]
	v_pk_mul_f32 v[96:97], v[82:83], v[50:51] op_sel_hi:[1,0]
	v_pk_fma_f32 v[8:9], v[4:5], v[46:47], v[8:9] op_sel_hi:[1,0,1]
	v_pk_mul_f32 v[98:99], v[82:83], v[50:51] op_sel:[0,1] op_sel_hi:[1,1]
	v_pk_fma_f32 v[8:9], v[6:7], v[46:47], v[8:9] op_sel:[0,1,0] op_sel_hi:[1,1,1]
	v_pk_fma_f32 v[0:1], v[0:1], v[100:101], v[92:93]
	v_pk_fma_f32 v[2:3], v[2:3], v[100:101], v[94:95]
	v_pk_fma_f32 v[4:5], v[4:5], v[100:101], v[96:97]
	v_pk_fma_f32 v[6:7], v[6:7], v[100:101], v[98:99]
	ds_read_b128 v[40:43], v134 offset:43520
	ds_read_b128 v[44:47], v134 offset:51712
	s_waitcnt lgkmcnt(7)
	v_pk_mul_f32 v[92:93], v[84:85], v[56:57] op_sel_hi:[1,0]
	v_pk_mul_f32 v[10:11], v[0:1], v[52:53] op_sel_hi:[1,0]
	v_pk_mul_f32 v[94:95], v[84:85], v[56:57] op_sel:[0,1] op_sel_hi:[1,1]
	v_pk_fma_f32 v[10:11], v[2:3], v[52:53], v[10:11] op_sel:[0,1,0] op_sel_hi:[1,1,1]
	v_pk_mul_f32 v[96:97], v[84:85], v[58:59] op_sel_hi:[1,0]
	v_pk_fma_f32 v[10:11], v[4:5], v[54:55], v[10:11] op_sel_hi:[1,0,1]
	v_pk_mul_f32 v[98:99], v[84:85], v[58:59] op_sel:[0,1] op_sel_hi:[1,1]
	v_pk_fma_f32 v[10:11], v[6:7], v[54:55], v[10:11] op_sel:[0,1,0] op_sel_hi:[1,1,1]
	v_pk_fma_f32 v[0:1], v[0:1], v[100:101], v[92:93]
	v_pk_fma_f32 v[2:3], v[2:3], v[100:101], v[94:95]
	v_pk_fma_f32 v[4:5], v[4:5], v[100:101], v[96:97]
	v_pk_fma_f32 v[6:7], v[6:7], v[100:101], v[98:99]
	ds_read_b128 v[80:83], v135 offset:58112
	ds_read_b128 v[48:51], v134 offset:44032
	ds_read_b128 v[52:55], v134 offset:52224
	s_waitcnt lgkmcnt(8)
	v_pk_mul_f32 v[92:93], v[86:87], v[64:65] op_sel_hi:[1,0]
	v_pk_mul_f32 v[12:13], v[0:1], v[60:61] op_sel_hi:[1,0]
	v_pk_mul_f32 v[94:95], v[86:87], v[64:65] op_sel:[0,1] op_sel_hi:[1,1]
	v_pk_fma_f32 v[12:13], v[2:3], v[60:61], v[12:13] op_sel:[0,1,0] op_sel_hi:[1,1,1]
	v_pk_mul_f32 v[96:97], v[86:87], v[66:67] op_sel_hi:[1,0]
	v_pk_fma_f32 v[12:13], v[4:5], v[62:63], v[12:13] op_sel_hi:[1,0,1]
	v_pk_mul_f32 v[98:99], v[86:87], v[66:67] op_sel:[0,1] op_sel_hi:[1,1]
	v_pk_fma_f32 v[12:13], v[6:7], v[62:63], v[12:13] op_sel:[0,1,0] op_sel_hi:[1,1,1]
	v_pk_fma_f32 v[0:1], v[0:1], v[100:101], v[92:93]
	v_pk_fma_f32 v[2:3], v[2:3], v[100:101], v[94:95]
	v_pk_fma_f32 v[4:5], v[4:5], v[100:101], v[96:97]
	v_pk_fma_f32 v[6:7], v[6:7], v[100:101], v[98:99]
	ds_read_b128 v[56:59], v134 offset:44544
	ds_read_b128 v[60:63], v134 offset:52736
	s_waitcnt lgkmcnt(7)
	v_pk_mul_f32 v[92:93], v[88:89], v[72:73] op_sel_hi:[1,0]
	v_pk_mul_f32 v[14:15], v[0:1], v[68:69] op_sel_hi:[1,0]
	v_pk_mul_f32 v[94:95], v[88:89], v[72:73] op_sel:[0,1] op_sel_hi:[1,1]
	v_pk_fma_f32 v[14:15], v[2:3], v[68:69], v[14:15] op_sel:[0,1,0] op_sel_hi:[1,1,1]
	v_pk_mul_f32 v[96:97], v[88:89], v[74:75] op_sel_hi:[1,0]
	v_pk_fma_f32 v[14:15], v[4:5], v[70:71], v[14:15] op_sel_hi:[1,0,1]
	v_pk_mul_f32 v[98:99], v[88:89], v[74:75] op_sel:[0,1] op_sel_hi:[1,1]
	v_pk_fma_f32 v[14:15], v[6:7], v[70:71], v[14:15] op_sel:[0,1,0] op_sel_hi:[1,1,1]
	v_pk_fma_f32 v[0:1], v[0:1], v[100:101], v[92:93]
	v_pk_fma_f32 v[2:3], v[2:3], v[100:101], v[94:95]
	v_pk_fma_f32 v[4:5], v[4:5], v[100:101], v[96:97]
	v_pk_fma_f32 v[6:7], v[6:7], v[100:101], v[98:99]
	ds_read_b128 v[84:87], v135 offset:58368
	ds_read_b128 v[64:67], v134 offset:45056
	ds_read_b128 v[68:71], v134 offset:53248
	s_waitcnt lgkmcnt(8)
	v_pk_mul_f32 v[92:93], v[90:91], v[40:41] op_sel_hi:[1,0]
	v_pk_mul_f32 v[16:17], v[0:1], v[76:77] op_sel_hi:[1,0]
	v_pk_mul_f32 v[94:95], v[90:91], v[40:41] op_sel:[0,1] op_sel_hi:[1,1]
	v_pk_fma_f32 v[16:17], v[2:3], v[76:77], v[16:17] op_sel:[0,1,0] op_sel_hi:[1,1,1]
	v_pk_mul_f32 v[96:97], v[90:91], v[42:43] op_sel_hi:[1,0]
	v_pk_fma_f32 v[16:17], v[4:5], v[78:79], v[16:17] op_sel_hi:[1,0,1]
	v_pk_mul_f32 v[98:99], v[90:91], v[42:43] op_sel:[0,1] op_sel_hi:[1,1]
	v_pk_fma_f32 v[16:17], v[6:7], v[78:79], v[16:17] op_sel:[0,1,0] op_sel_hi:[1,1,1]
	v_pk_fma_f32 v[0:1], v[0:1], v[100:101], v[92:93]
	v_pk_fma_f32 v[2:3], v[2:3], v[100:101], v[94:95]
	v_pk_fma_f32 v[4:5], v[4:5], v[100:101], v[96:97]
	v_pk_fma_f32 v[6:7], v[6:7], v[100:101], v[98:99]
	ds_read_b128 v[72:75], v134 offset:45568
	ds_read_b128 v[76:79], v134 offset:53760
	s_waitcnt lgkmcnt(7)
	v_pk_mul_f32 v[92:93], v[80:81], v[48:49] op_sel_hi:[1,0]
	v_pk_mul_f32 v[18:19], v[0:1], v[44:45] op_sel_hi:[1,0]
	v_pk_mul_f32 v[94:95], v[80:81], v[48:49] op_sel:[0,1] op_sel_hi:[1,1]
	v_pk_fma_f32 v[18:19], v[2:3], v[44:45], v[18:19] op_sel:[0,1,0] op_sel_hi:[1,1,1]
	v_pk_mul_f32 v[96:97], v[80:81], v[50:51] op_sel_hi:[1,0]
	v_pk_fma_f32 v[18:19], v[4:5], v[46:47], v[18:19] op_sel_hi:[1,0,1]
	v_pk_mul_f32 v[98:99], v[80:81], v[50:51] op_sel:[0,1] op_sel_hi:[1,1]
	v_pk_fma_f32 v[18:19], v[6:7], v[46:47], v[18:19] op_sel:[0,1,0] op_sel_hi:[1,1,1]
	v_pk_fma_f32 v[0:1], v[0:1], v[100:101], v[92:93]
	v_pk_fma_f32 v[2:3], v[2:3], v[100:101], v[94:95]
	v_pk_fma_f32 v[4:5], v[4:5], v[100:101], v[96:97]
	v_pk_fma_f32 v[6:7], v[6:7], v[100:101], v[98:99]
	ds_read_b128 v[88:91], v135 offset:58624
	ds_read_b128 v[40:43], v134 offset:46080
	ds_read_b128 v[44:47], v134 offset:54272
	s_waitcnt lgkmcnt(8)
	v_pk_mul_f32 v[92:93], v[82:83], v[56:57] op_sel_hi:[1,0]
	v_pk_mul_f32 v[20:21], v[0:1], v[52:53] op_sel_hi:[1,0]
	v_pk_mul_f32 v[94:95], v[82:83], v[56:57] op_sel:[0,1] op_sel_hi:[1,1]
	v_pk_fma_f32 v[20:21], v[2:3], v[52:53], v[20:21] op_sel:[0,1,0] op_sel_hi:[1,1,1]
	v_pk_mul_f32 v[96:97], v[82:83], v[58:59] op_sel_hi:[1,0]
	v_pk_fma_f32 v[20:21], v[4:5], v[54:55], v[20:21] op_sel_hi:[1,0,1]
	v_pk_mul_f32 v[98:99], v[82:83], v[58:59] op_sel:[0,1] op_sel_hi:[1,1]
	v_pk_fma_f32 v[20:21], v[6:7], v[54:55], v[20:21] op_sel:[0,1,0] op_sel_hi:[1,1,1]
	v_pk_fma_f32 v[0:1], v[0:1], v[100:101], v[92:93]
	v_pk_fma_f32 v[2:3], v[2:3], v[100:101], v[94:95]
	v_pk_fma_f32 v[4:5], v[4:5], v[100:101], v[96:97]
	v_pk_fma_f32 v[6:7], v[6:7], v[100:101], v[98:99]
	ds_read_b128 v[48:51], v134 offset:46592
	ds_read_b128 v[52:55], v134 offset:54784
	s_waitcnt lgkmcnt(7)
	v_pk_mul_f32 v[92:93], v[84:85], v[64:65] op_sel_hi:[1,0]
	v_pk_mul_f32 v[22:23], v[0:1], v[60:61] op_sel_hi:[1,0]
	v_pk_mul_f32 v[94:95], v[84:85], v[64:65] op_sel:[0,1] op_sel_hi:[1,1]
	v_pk_fma_f32 v[22:23], v[2:3], v[60:61], v[22:23] op_sel:[0,1,0] op_sel_hi:[1,1,1]
	v_pk_mul_f32 v[96:97], v[84:85], v[66:67] op_sel_hi:[1,0]
	v_pk_fma_f32 v[22:23], v[4:5], v[62:63], v[22:23] op_sel_hi:[1,0,1]
	v_pk_mul_f32 v[98:99], v[84:85], v[66:67] op_sel:[0,1] op_sel_hi:[1,1]
	v_pk_fma_f32 v[22:23], v[6:7], v[62:63], v[22:23] op_sel:[0,1,0] op_sel_hi:[1,1,1]
	v_pk_fma_f32 v[0:1], v[0:1], v[100:101], v[92:93]
	v_pk_fma_f32 v[2:3], v[2:3], v[100:101], v[94:95]
	v_pk_fma_f32 v[4:5], v[4:5], v[100:101], v[96:97]
	v_pk_fma_f32 v[6:7], v[6:7], v[100:101], v[98:99]
	ds_read_b128 v[80:83], v135 offset:58880
	ds_read_b128 v[56:59], v134 offset:47104
	ds_read_b128 v[60:63], v134 offset:55296
	s_waitcnt lgkmcnt(8)
	v_pk_mul_f32 v[92:93], v[86:87], v[72:73] op_sel_hi:[1,0]
	v_pk_mul_f32 v[24:25], v[0:1], v[68:69] op_sel_hi:[1,0]
	v_pk_mul_f32 v[94:95], v[86:87], v[72:73] op_sel:[0,1] op_sel_hi:[1,1]
	v_pk_fma_f32 v[24:25], v[2:3], v[68:69], v[24:25] op_sel:[0,1,0] op_sel_hi:[1,1,1]
	v_pk_mul_f32 v[96:97], v[86:87], v[74:75] op_sel_hi:[1,0]
	v_pk_fma_f32 v[24:25], v[4:5], v[70:71], v[24:25] op_sel_hi:[1,0,1]
	v_pk_mul_f32 v[98:99], v[86:87], v[74:75] op_sel:[0,1] op_sel_hi:[1,1]
	v_pk_fma_f32 v[24:25], v[6:7], v[70:71], v[24:25] op_sel:[0,1,0] op_sel_hi:[1,1,1]
	v_pk_fma_f32 v[0:1], v[0:1], v[100:101], v[92:93]
	v_pk_fma_f32 v[2:3], v[2:3], v[100:101], v[94:95]
	v_pk_fma_f32 v[4:5], v[4:5], v[100:101], v[96:97]
	v_pk_fma_f32 v[6:7], v[6:7], v[100:101], v[98:99]
	ds_read_b128 v[64:67], v134 offset:47616
	ds_read_b128 v[68:71], v134 offset:55808
	s_waitcnt lgkmcnt(7)
	v_pk_mul_f32 v[92:93], v[88:89], v[40:41] op_sel_hi:[1,0]
	v_pk_mul_f32 v[26:27], v[0:1], v[76:77] op_sel_hi:[1,0]
	v_pk_mul_f32 v[94:95], v[88:89], v[40:41] op_sel:[0,1] op_sel_hi:[1,1]
	v_pk_fma_f32 v[26:27], v[2:3], v[76:77], v[26:27] op_sel:[0,1,0] op_sel_hi:[1,1,1]
	v_pk_mul_f32 v[96:97], v[88:89], v[42:43] op_sel_hi:[1,0]
	v_pk_fma_f32 v[26:27], v[4:5], v[78:79], v[26:27] op_sel_hi:[1,0,1]
	v_pk_mul_f32 v[98:99], v[88:89], v[42:43] op_sel:[0,1] op_sel_hi:[1,1]
	v_pk_fma_f32 v[26:27], v[6:7], v[78:79], v[26:27] op_sel:[0,1,0] op_sel_hi:[1,1,1]
	v_pk_fma_f32 v[0:1], v[0:1], v[100:101], v[92:93]
	v_pk_fma_f32 v[2:3], v[2:3], v[100:101], v[94:95]
	v_pk_fma_f32 v[4:5], v[4:5], v[100:101], v[96:97]
	v_pk_fma_f32 v[6:7], v[6:7], v[100:101], v[98:99]
	ds_read_b128 v[84:87], v135 offset:59136
	ds_read_b128 v[72:75], v134 offset:48128
	ds_read_b128 v[76:79], v134 offset:56320
	s_waitcnt lgkmcnt(8)
	v_pk_mul_f32 v[92:93], v[90:91], v[48:49] op_sel_hi:[1,0]
	v_pk_mul_f32 v[28:29], v[0:1], v[44:45] op_sel_hi:[1,0]
	v_pk_mul_f32 v[94:95], v[90:91], v[48:49] op_sel:[0,1] op_sel_hi:[1,1]
	v_pk_fma_f32 v[28:29], v[2:3], v[44:45], v[28:29] op_sel:[0,1,0] op_sel_hi:[1,1,1]
	v_pk_mul_f32 v[96:97], v[90:91], v[50:51] op_sel_hi:[1,0]
	v_pk_fma_f32 v[28:29], v[4:5], v[46:47], v[28:29] op_sel_hi:[1,0,1]
	v_pk_mul_f32 v[98:99], v[90:91], v[50:51] op_sel:[0,1] op_sel_hi:[1,1]
	v_pk_fma_f32 v[28:29], v[6:7], v[46:47], v[28:29] op_sel:[0,1,0] op_sel_hi:[1,1,1]
	v_pk_fma_f32 v[0:1], v[0:1], v[100:101], v[92:93]
	v_pk_fma_f32 v[2:3], v[2:3], v[100:101], v[94:95]
	v_pk_fma_f32 v[4:5], v[4:5], v[100:101], v[96:97]
	v_pk_fma_f32 v[6:7], v[6:7], v[100:101], v[98:99]
	ds_read_b128 v[40:43], v134 offset:48640
	ds_read_b128 v[44:47], v134 offset:56832
	s_waitcnt lgkmcnt(7)
	v_pk_mul_f32 v[92:93], v[80:81], v[56:57] op_sel_hi:[1,0]
	v_pk_mul_f32 v[30:31], v[0:1], v[52:53] op_sel_hi:[1,0]
	v_pk_mul_f32 v[94:95], v[80:81], v[56:57] op_sel:[0,1] op_sel_hi:[1,1]
	v_pk_fma_f32 v[30:31], v[2:3], v[52:53], v[30:31] op_sel:[0,1,0] op_sel_hi:[1,1,1]
	v_pk_mul_f32 v[96:97], v[80:81], v[58:59] op_sel_hi:[1,0]
	v_pk_fma_f32 v[30:31], v[4:5], v[54:55], v[30:31] op_sel_hi:[1,0,1]
	v_pk_mul_f32 v[98:99], v[80:81], v[58:59] op_sel:[0,1] op_sel_hi:[1,1]
	v_pk_fma_f32 v[30:31], v[6:7], v[54:55], v[30:31] op_sel:[0,1,0] op_sel_hi:[1,1,1]
	v_pk_fma_f32 v[0:1], v[0:1], v[100:101], v[92:93]
	v_pk_fma_f32 v[2:3], v[2:3], v[100:101], v[94:95]
	v_pk_fma_f32 v[4:5], v[4:5], v[100:101], v[96:97]
	v_pk_fma_f32 v[6:7], v[6:7], v[100:101], v[98:99]
	s_waitcnt lgkmcnt(5)
	v_pk_mul_f32 v[92:93], v[82:83], v[64:65] op_sel_hi:[1,0]
	v_pk_mul_f32 v[32:33], v[0:1], v[60:61] op_sel_hi:[1,0]
	v_pk_mul_f32 v[94:95], v[82:83], v[64:65] op_sel:[0,1] op_sel_hi:[1,1]
	v_pk_fma_f32 v[32:33], v[2:3], v[60:61], v[32:33] op_sel:[0,1,0] op_sel_hi:[1,1,1]
	v_pk_mul_f32 v[96:97], v[82:83], v[66:67] op_sel_hi:[1,0]
	v_pk_fma_f32 v[32:33], v[4:5], v[62:63], v[32:33] op_sel_hi:[1,0,1]
	v_pk_mul_f32 v[98:99], v[82:83], v[66:67] op_sel:[0,1] op_sel_hi:[1,1]
	v_pk_fma_f32 v[32:33], v[6:7], v[62:63], v[32:33] op_sel:[0,1,0] op_sel_hi:[1,1,1]
	v_pk_fma_f32 v[0:1], v[0:1], v[100:101], v[92:93]
	v_pk_fma_f32 v[2:3], v[2:3], v[100:101], v[94:95]
	v_pk_fma_f32 v[4:5], v[4:5], v[100:101], v[96:97]
	v_pk_fma_f32 v[6:7], v[6:7], v[100:101], v[98:99]
	s_waitcnt lgkmcnt(2)
	v_pk_mul_f32 v[92:93], v[84:85], v[72:73] op_sel_hi:[1,0]
	v_pk_mul_f32 v[34:35], v[0:1], v[68:69] op_sel_hi:[1,0]
	v_pk_mul_f32 v[94:95], v[84:85], v[72:73] op_sel:[0,1] op_sel_hi:[1,1]
	v_pk_fma_f32 v[34:35], v[2:3], v[68:69], v[34:35] op_sel:[0,1,0] op_sel_hi:[1,1,1]
	v_pk_mul_f32 v[96:97], v[84:85], v[74:75] op_sel_hi:[1,0]
	v_pk_fma_f32 v[34:35], v[4:5], v[70:71], v[34:35] op_sel_hi:[1,0,1]
	v_pk_mul_f32 v[98:99], v[84:85], v[74:75] op_sel:[0,1] op_sel_hi:[1,1]
	v_pk_fma_f32 v[34:35], v[6:7], v[70:71], v[34:35] op_sel:[0,1,0] op_sel_hi:[1,1,1]
	v_pk_fma_f32 v[0:1], v[0:1], v[100:101], v[92:93]
	v_pk_fma_f32 v[2:3], v[2:3], v[100:101], v[94:95]
	v_pk_fma_f32 v[4:5], v[4:5], v[100:101], v[96:97]
	v_pk_fma_f32 v[6:7], v[6:7], v[100:101], v[98:99]
	s_waitcnt lgkmcnt(0)
	v_pk_mul_f32 v[92:93], v[86:87], v[40:41] op_sel_hi:[1,0]
	v_pk_mul_f32 v[36:37], v[0:1], v[76:77] op_sel_hi:[1,0]
	v_pk_mul_f32 v[94:95], v[86:87], v[40:41] op_sel:[0,1] op_sel_hi:[1,1]
	v_pk_fma_f32 v[36:37], v[2:3], v[76:77], v[36:37] op_sel:[0,1,0] op_sel_hi:[1,1,1]
	v_pk_mul_f32 v[96:97], v[86:87], v[42:43] op_sel_hi:[1,0]
	v_pk_fma_f32 v[36:37], v[4:5], v[78:79], v[36:37] op_sel_hi:[1,0,1]
	v_pk_mul_f32 v[98:99], v[86:87], v[42:43] op_sel:[0,1] op_sel_hi:[1,1]
	v_pk_fma_f32 v[36:37], v[6:7], v[78:79], v[36:37] op_sel:[0,1,0] op_sel_hi:[1,1,1]
	v_pk_fma_f32 v[0:1], v[0:1], v[100:101], v[92:93]
	v_pk_fma_f32 v[2:3], v[2:3], v[100:101], v[94:95]
	v_pk_fma_f32 v[4:5], v[4:5], v[100:101], v[96:97]
	v_pk_fma_f32 v[6:7], v[6:7], v[100:101], v[98:99]
	v_pk_mul_f32 v[38:39], v[0:1], v[44:45] op_sel_hi:[1,0]
	v_pk_fma_f32 v[38:39], v[2:3], v[44:45], v[38:39] op_sel:[0,1,0] op_sel_hi:[1,1,1]
	v_pk_fma_f32 v[38:39], v[4:5], v[46:47], v[38:39] op_sel_hi:[1,0,1]
	v_pk_fma_f32 v[38:39], v[6:7], v[46:47], v[38:39] op_sel:[0,1,0] op_sel_hi:[1,1,1]
	s_nop 1
	v_permlane16_swap_b32_e32 v8, v24
	v_permlane16_swap_b32_e32 v9, v25
	v_permlane16_swap_b32_e32 v10, v26
	v_permlane16_swap_b32_e32 v11, v27
	v_permlane16_swap_b32_e32 v12, v28
	v_permlane16_swap_b32_e32 v13, v29
	v_permlane16_swap_b32_e32 v14, v30
	v_permlane16_swap_b32_e32 v15, v31
	v_permlane16_swap_b32_e32 v16, v32
	v_permlane16_swap_b32_e32 v17, v33
	v_permlane16_swap_b32_e32 v18, v34
	v_permlane16_swap_b32_e32 v19, v35
	v_permlane16_swap_b32_e32 v20, v36
	v_permlane16_swap_b32_e32 v21, v37
	v_permlane16_swap_b32_e32 v22, v38
	v_permlane16_swap_b32_e32 v23, v39
	v_pk_add_f32 v[8:9], v[8:9], v[24:25]
	v_pk_add_f32 v[10:11], v[10:11], v[26:27]
	v_pk_add_f32 v[12:13], v[12:13], v[28:29]
	v_pk_add_f32 v[14:15], v[14:15], v[30:31]
	v_pk_add_f32 v[16:17], v[16:17], v[32:33]
	v_pk_add_f32 v[18:19], v[18:19], v[34:35]
	v_pk_add_f32 v[20:21], v[20:21], v[36:37]
	v_pk_add_f32 v[22:23], v[22:23], v[38:39]
	s_nop 1
	v_permlane32_swap_b32_e32 v8, v16
	v_permlane32_swap_b32_e32 v9, v17
	v_permlane32_swap_b32_e32 v10, v18
	v_permlane32_swap_b32_e32 v11, v19
	v_permlane32_swap_b32_e32 v12, v20
	v_permlane32_swap_b32_e32 v13, v21
	v_permlane32_swap_b32_e32 v14, v22
	v_permlane32_swap_b32_e32 v15, v23
	v_pk_add_f32 v[8:9], v[8:9], v[16:17]
	v_pk_add_f32 v[10:11], v[10:11], v[18:19]
	v_pk_add_f32 v[12:13], v[12:13], v[20:21]
	v_pk_add_f32 v[14:15], v[14:15], v[22:23]
	ds_write2_b32 v145, v8, v9 offset1:16
	ds_write2_b32 v146, v10, v11 offset1:16
	ds_write2_b32 v147, v12, v13 offset1:16
	ds_write2_b32 v148, v14, v15 offset1:16
	s_sub_u32 s15, s15, 1
	s_waitcnt lgkmcnt(0)
	s_barrier
	s_cmp_lg_u32 s15, 0
	s_cbranch_scc1 .Lgla_loop_ret
.Lgla_tail:
	ds_read2_b32 v[104:105], v150 offset0:0 offset1:32
	ds_read2_b32 v[106:107], v150 offset0:64 offset1:96
	ds_read2_b32 v[108:109], v150 offset0:128 offset1:160
	ds_read2_b32 v[110:111], v150 offset0:192 offset1:224
	s_waitcnt lgkmcnt(0)
	v_add_f32_e32 v112, v104, v105
	v_add_f32_e32 v112, v112, v106
	v_add_f32_e32 v112, v112, v107
	v_add_f32_e32 v112, v112, v108
	v_add_f32_e32 v112, v112, v109
	v_add_f32_e32 v112, v112, v110
	v_add_f32_e32 v112, v112, v111
	v_mul_f32_e32 v113, v112, v112
	v_cvt_pk_bf16_f32 v116, v112, v129
	v_mov_b32_e32 v117, v112
	v_mov_b32_e32 v118, v113
	global_store_short v132, v116, s[10:11]
	s_nop 1
	v_permlane16_swap_b32_e32 v112, v117
	v_permlane16_swap_b32_e32 v113, v118
	v_add_f32_e32 v112, v112, v117
	v_add_f32_e32 v113, v113, v118
	s_nop 1
	v_add_f32_dpp v112, v112, v112 row_ror:8 row_mask:0xf bank_mask:0xf
	v_add_f32_dpp v113, v113, v113 row_ror:8 row_mask:0xf bank_mask:0xf
	s_nop 1
	v_add_f32_dpp v112, v112, v112 row_ror:4 row_mask:0xf bank_mask:0xf
	v_add_f32_dpp v113, v113, v113 row_ror:4 row_mask:0xf bank_mask:0xf
	s_nop 1
	v_add_f32_dpp v112, v112, v112 row_ror:2 row_mask:0xf bank_mask:0xf
	v_add_f32_dpp v113, v113, v113 row_ror:2 row_mask:0xf bank_mask:0xf
	s_nop 1
	v_add_f32_dpp v112, v112, v112 row_ror:1 row_mask:0xf bank_mask:0xf
	v_add_f32_dpp v113, v113, v113 row_ror:1 row_mask:0xf bank_mask:0xf
	v_mov_b32_e32 v114, 0
	v_mov_b32_e32 v115, 0
	s_mov_b64 exec, s[18:19]
	global_store_dwordx4 v133, v[112:115], s[12:13]
	s_mov_b64 exec, -1
	s_mov_b32 s20, 0x10000
	s_movk_i32 s21, 0x1000
	s_add_u32 s10, s10, s20
	s_addc_u32 s11, s11, 0
	s_add_u32 s12, s12, s21
	s_addc_u32 s13, s13, 0
	s_branch .LBB0_183
